# NSA loops: cross-half max via v_permlane32_swap, deferred softmax rescale (threshold 8 in log2 units); GLA stage 3 reductions via DPP adds + v_permlane16_swap instead of ds_bpermute
# speedup vs baseline: 1.0647x; 1.0312x over previous
; #define LAS __attribute__((address_space(3)))
; #define LDS_WAIT() asm volatile("s_waitcnt lgkmcnt(0)" ::: "memory")
; template <bool CMP> DI void tile_compute(LAS unsigned char* lds, int buf, const bf16x8 (&q)[4], int lo, int hv, ASt& st, f32x16& imp0, f32x16& imp1, int jt, LAS float* wsf, int lane) {
;     ...
;     float mx = __builtin_fmaxf(p0[0], p1[0]);
; #pragma unroll
;     for (int rg = 1; rg < 16; ++rg) mx = __builtin_fmaxf(__builtin_fmaxf(mx, p0[rg]), p1[rg]);
;     if (!anyPart && dead) mx = NEGB;
;     mx = __builtin_fmaxf(mx, __shfl_xor(mx, 32));
;     const float mnew = fmaxf(st.m, mx);
;     const float alpha = __builtin_amdgcn_exp2f(st.m - mnew);
;     st.m = mnew;
;     float sum = 0.f;
;     const float msub = (!anyPart && dead) ? 1e30f : mnew;
; #pragma unroll
;     for (int rg = 0; rg < 16; ++rg) { p0[rg] = __builtin_amdgcn_exp2f(p0[rg] - msub); p1[rg] = __builtin_amdgcn_exp2f(p1[rg] - msub); sum += p0[rg] + p1[rg]; }
;     st.l = st.l * alpha + sum;
;     if (__builtin_amdgcn_ballot_w64(alpha != 1.f) != 0ull) {
;         if (hi == 0) wsf[r] = alpha;
;         LDS_WAIT();
; #pragma unroll
;         for (int g4 = 0; g4 < 4; ++g4) { const f32x4 f = *(const LAS f32x4*)(wsf + 8 * g4 + 4 * hi);
; #pragma unroll
;             for (int k = 0; k < 4; ++k) { st.o0[4 * g4 + k] *= f[k]; st.o1[4 * g4 + k] *= f[k]; if (CMP) { imp0[4 * g4 + k] *= f[k]; imp1[4 * g4 + k] *= f[k]; } } }
.LBB0_551:
	s_nop 10
	v_max_f32_e32 v141, v68, v68
	v_max_f32_e32 v234, v84, v84
	v_max_f32_e32 v141, v234, v141
	v_max3_f32 v141, v141, v85, v69
	v_max3_f32 v141, v141, v86, v70
	v_max3_f32 v141, v141, v87, v71
	v_max3_f32 v141, v141, v88, v72
	v_max3_f32 v141, v141, v89, v73
	v_max3_f32 v141, v141, v90, v74
	v_max3_f32 v141, v141, v91, v75
	v_max3_f32 v141, v141, v92, v76
	v_max3_f32 v141, v141, v93, v77
	v_max3_f32 v141, v141, v94, v78
	v_max3_f32 v141, v141, v95, v79
	v_max3_f32 v141, v141, v96, v80
	v_max3_f32 v141, v141, v97, v81
	v_max3_f32 v141, v141, v98, v82
	v_max3_f32 v141, v141, v99, v83
	s_and_b64 s[78:79], s[78:79], s[12:13]
	v_cndmask_b32_e64 v141, v141, v222, s[78:79]
	ds_bpermute_b32 v234, v135, v141
	s_waitcnt lgkmcnt(0)
	v_max3_f32 v141, v233, v141, v234
	v_sub_f32_e32 v234, v141, v233
	v_cmp_lt_f32_e32 vcc, 0x41000000, v234
	s_nop 1
	v_cndmask_b32_e32 v141, v233, v141, vcc
	v_sub_f32_e32 v233, v233, v141
	v_exp_f32_e32 v233, v233
	s_nop 0
	v_cmp_neq_f32_e32 vcc, 1.0, v233
	s_cbranch_vccz .LBB0_555
	s_and_saveexec_b64 s[12:13], s[4:5]
	ds_write_b32 v194, v233 offset:32768
	s_or_b64 exec, exec, s[12:13]
	s_waitcnt lgkmcnt(0)
	v_add_u32_e32 v246, s16, v195
	ds_read_b128 v[234:237], v246 offset:32864
	ds_read_b128 v[238:241], v246 offset:32832
	ds_read_b128 v[242:245], v246 offset:32800
	ds_read_b128 v[246:249], v246 offset:32768
	s_waitcnt lgkmcnt(0)
	s_waitcnt lgkmcnt(0)
	v_pk_mul_f32 v[64:65], v[64:65], v[234:235]
	v_pk_mul_f32 v[60:61], v[60:61], v[238:239]
	v_pk_mul_f32 v[56:57], v[56:57], v[242:243]
	v_pk_mul_f32 v[66:67], v[66:67], v[236:237]
	v_pk_mul_f32 v[62:63], v[62:63], v[240:241]
	v_pk_mul_f32 v[58:59], v[58:59], v[244:245]
	v_pk_mul_f32 v[54:55], v[54:55], v[248:249]
	v_pk_mul_f32 v[52:53], v[52:53], v[246:247]
	v_pk_mul_f32 v[48:49], v[48:49], v[234:235]
	v_pk_mul_f32 v[44:45], v[44:45], v[238:239]
	v_pk_mul_f32 v[40:41], v[40:41], v[242:243]
	v_pk_mul_f32 v[50:51], v[50:51], v[236:237]
	v_pk_mul_f32 v[46:47], v[46:47], v[240:241]
	v_pk_mul_f32 v[42:43], v[42:43], v[244:245]
	v_pk_mul_f32 v[38:39], v[38:39], v[248:249]
	v_pk_mul_f32 v[36:37], v[36:37], v[246:247]
	v_pk_mul_f32 v[32:33], v[32:33], v[234:235]
	v_pk_mul_f32 v[28:29], v[28:29], v[238:239]
	v_pk_mul_f32 v[24:25], v[24:25], v[242:243]
	v_pk_mul_f32 v[34:35], v[34:35], v[236:237]
	v_pk_mul_f32 v[30:31], v[30:31], v[240:241]
	v_pk_mul_f32 v[26:27], v[26:27], v[244:245]
	v_pk_mul_f32 v[22:23], v[22:23], v[248:249]
	v_pk_mul_f32 v[20:21], v[20:21], v[246:247]
	v_pk_mul_f32 v[16:17], v[16:17], v[234:235]
	v_pk_mul_f32 v[12:13], v[12:13], v[238:239]
	v_pk_mul_f32 v[8:9], v[8:9], v[242:243]
	v_pk_mul_f32 v[18:19], v[18:19], v[236:237]
	v_pk_mul_f32 v[14:15], v[14:15], v[240:241]
	v_pk_mul_f32 v[10:11], v[10:11], v[244:245]
	v_pk_mul_f32 v[6:7], v[6:7], v[248:249]
	v_pk_mul_f32 v[4:5], v[4:5], v[246:247]

; #define LDS_WAIT() asm volatile("s_waitcnt lgkmcnt(0)" ::: "memory")
; template <bool CMP> DI void tile_compute(LAS unsigned char* lds, int buf, const bf16x8 (&q)[4], int lo, int hv, ASt& st, f32x16& imp0, f32x16& imp1, int jt, LAS float* wsf, int lane) {
;     ...
;     float mx = __builtin_fmaxf(p0[0], p1[0]);
; #pragma unroll
;     for (int rg = 1; rg < 16; ++rg) mx = __builtin_fmaxf(__builtin_fmaxf(mx, p0[rg]), p1[rg]);
;     if (!anyPart && dead) mx = NEGB;
;     mx = __builtin_fmaxf(mx, __shfl_xor(mx, 32));
;     const float mnew = fmaxf(st.m, mx);
;     const float alpha = __builtin_amdgcn_exp2f(st.m - mnew);
;     st.m = mnew;
;     float sum = 0.f;
;     const float msub = (!anyPart && dead) ? 1e30f : mnew;
; #pragma unroll
;     for (int rg = 0; rg < 16; ++rg) { p0[rg] = __builtin_amdgcn_exp2f(p0[rg] - msub); p1[rg] = __builtin_amdgcn_exp2f(p1[rg] - msub); sum += p0[rg] + p1[rg]; }
;     st.l = st.l * alpha + sum;
;     if (__builtin_amdgcn_ballot_w64(alpha != 1.f) != 0ull) {
;         if (hi == 0) wsf[r] = alpha;
;         LDS_WAIT();
.LBB0_572:
	s_nop 10
	v_max_f32_e32 v2, v50, v50
	v_max_f32_e32 v4, v66, v66
	v_max_f32_e32 v2, v4, v2
	v_max3_f32 v2, v2, v67, v51
	v_max3_f32 v2, v2, v68, v52
	v_max3_f32 v2, v2, v69, v53
	v_max3_f32 v2, v2, v70, v54
	v_max3_f32 v2, v2, v71, v55
	v_max3_f32 v2, v2, v72, v56
	v_max3_f32 v2, v2, v73, v57
	v_max3_f32 v2, v2, v74, v58
	v_max3_f32 v2, v2, v75, v59
	v_max3_f32 v2, v2, v76, v60
	v_max3_f32 v2, v2, v77, v61
	v_max3_f32 v2, v2, v78, v62
	v_max3_f32 v2, v2, v79, v63
	v_max3_f32 v2, v2, v80, v64
	v_max3_f32 v2, v2, v81, v65
	s_and_b64 s[80:81], s[80:81], s[14:15]
	v_cndmask_b32_e64 v2, v2, v222, s[80:81]
	v_mov_b32_e32 v4, v2
	v_mov_b32_e32 v5, v2
	s_nop 1
	v_permlane32_swap_b32_e32 v4, v5
	v_max3_f32 v2, v107, v4, v5
	v_sub_f32_e32 v4, v2, v107
	v_cmp_lt_f32_e32 vcc, 0x41000000, v4
	s_nop 1
	v_cndmask_b32_e32 v2, v107, v2, vcc
	v_sub_f32_e32 v4, v107, v2
	v_exp_f32_e32 v4, v4
	s_nop 0
	v_cmp_neq_f32_e32 vcc, 1.0, v4
	s_cbranch_vccz .LBB0_567
	s_and_saveexec_b64 s[14:15], s[4:5]
	s_cbranch_execz .LBB0_566
	ds_write_b32 v194, v4 offset:32768
	s_branch .LBB0_566

; #define LAS __attribute__((address_space(3)))
; #define LDS_WAIT() asm volatile("s_waitcnt lgkmcnt(0)" ::: "memory")
; template <bool CMP> DI void tile_compute(LAS unsigned char* lds, int buf, const bf16x8 (&q)[4], int lo, int hv, ASt& st, f32x16& imp0, f32x16& imp1, int jt, LAS float* wsf, int lane) {
;     ...
;     float mx = __builtin_fmaxf(p0[0], p1[0]);
; #pragma unroll
;     for (int rg = 1; rg < 16; ++rg) mx = __builtin_fmaxf(__builtin_fmaxf(mx, p0[rg]), p1[rg]);
;     if (!anyPart && dead) mx = NEGB;
;     mx = __builtin_fmaxf(mx, __shfl_xor(mx, 32));
;     const float mnew = fmaxf(st.m, mx);
;     const float alpha = __builtin_amdgcn_exp2f(st.m - mnew);
;     st.m = mnew;
;     float sum = 0.f;
;     const float msub = (!anyPart && dead) ? 1e30f : mnew;
; #pragma unroll
;     for (int rg = 0; rg < 16; ++rg) { p0[rg] = __builtin_amdgcn_exp2f(p0[rg] - msub); p1[rg] = __builtin_amdgcn_exp2f(p1[rg] - msub); sum += p0[rg] + p1[rg]; }
;     st.l = st.l * alpha + sum;
;     if (__builtin_amdgcn_ballot_w64(alpha != 1.f) != 0ull) {
;         if (hi == 0) wsf[r] = alpha;
;         LDS_WAIT();
; #pragma unroll
;         for (int g4 = 0; g4 < 4; ++g4) { const f32x4 f = *(const LAS f32x4*)(wsf + 8 * g4 + 4 * hi);
; #pragma unroll
;             for (int k = 0; k < 4; ++k) { st.o0[4 * g4 + k] *= f[k]; st.o1[4 * g4 + k] *= f[k]; if (CMP) { imp0[4 * g4 + k] *= f[k]; imp1[4 * g4 + k] *= f[k]; } } }
.LBB0_592:
	s_nop 10
	v_max_f32_e32 v79, v52, v52
	v_max_f32_e32 v80, v36, v36
	v_max_f32_e32 v79, v80, v79
	v_max3_f32 v79, v79, v37, v53
	v_max3_f32 v79, v79, v38, v54
	v_max3_f32 v79, v79, v39, v55
	v_max3_f32 v79, v79, v40, v56
	v_max3_f32 v79, v79, v41, v57
	v_max3_f32 v79, v79, v42, v58
	v_max3_f32 v79, v79, v43, v59
	v_max3_f32 v79, v79, v44, v60
	v_max3_f32 v79, v79, v45, v61
	v_max3_f32 v79, v79, v46, v62
	v_max3_f32 v79, v79, v47, v63
	v_max3_f32 v79, v79, v48, v64
	v_max3_f32 v79, v79, v49, v65
	v_max3_f32 v79, v79, v50, v66
	v_max3_f32 v79, v79, v51, v67
	s_and_b64 s[78:79], s[78:79], s[14:15]
	v_cndmask_b32_e64 v79, v79, v222, s[78:79]
	v_mov_b32_e32 v80, v79
	v_mov_b32_e32 v81, v79
	s_nop 1
	v_permlane32_swap_b32_e32 v80, v81
	v_max3_f32 v79, v78, v80, v81
	v_sub_f32_e32 v80, v79, v78
	v_cmp_lt_f32_e32 vcc, 0x41000000, v80
	s_nop 1
	v_cndmask_b32_e32 v79, v78, v79, vcc
	v_sub_f32_e32 v78, v78, v79
	v_exp_f32_e32 v78, v78
	s_nop 0
	v_cmp_neq_f32_e32 vcc, 1.0, v78
	s_cbranch_vccz .LBB0_596
	s_and_saveexec_b64 s[14:15], s[4:5]
	ds_write_b32 v194, v78 offset:32768
	s_or_b64 exec, exec, s[14:15]
	s_waitcnt lgkmcnt(0)
	ds_read_b128 v[98:101], v119 offset:32864
	ds_read_b128 v[102:105], v119 offset:32832
	ds_read_b128 v[106:109], v119 offset:32800
	ds_read_b128 v[110:113], v119 offset:32768
	s_waitcnt lgkmcnt(0)
	s_waitcnt lgkmcnt(0)
	v_pk_mul_f32 v[32:33], v[32:33], v[98:99]
	v_pk_mul_f32 v[28:29], v[28:29], v[102:103]
	v_pk_mul_f32 v[24:25], v[24:25], v[106:107]
	v_pk_mul_f32 v[34:35], v[34:35], v[100:101]
	v_pk_mul_f32 v[30:31], v[30:31], v[104:105]
	v_pk_mul_f32 v[26:27], v[26:27], v[108:109]
	v_pk_mul_f32 v[22:23], v[22:23], v[112:113]
	v_pk_mul_f32 v[20:21], v[20:21], v[110:111]
	v_pk_mul_f32 v[16:17], v[16:17], v[98:99]
	v_pk_mul_f32 v[12:13], v[12:13], v[102:103]
	v_pk_mul_f32 v[8:9], v[8:9], v[106:107]
	v_pk_mul_f32 v[18:19], v[18:19], v[100:101]
	v_pk_mul_f32 v[14:15], v[14:15], v[104:105]
	v_pk_mul_f32 v[10:11], v[10:11], v[108:109]
	v_pk_mul_f32 v[6:7], v[6:7], v[112:113]
	v_pk_mul_f32 v[4:5], v[4:5], v[110:111]

; #define MFMA32(a, b, c) __builtin_amdgcn_mfma_f32_32x32x16_bf16((a), (b), (c), 0, 0, 0)
; DI void gla_stage3(const Ctx& c0, int layer, int unit, int cb, LAS unsigned char* lds) {
;     ...
;     const bf16* qgp = (const bf16*)(c.ws + O_QG) + (row0 + r) * 256 + h * 64 + 8 * hi;
;     const float* sp = (const float*)(c.ws + O_UPD) + (size_t)unit * 8192;
;     const float* gn = c.a->in[I_GNORM] + (size_t)layer * 128;
;     bf16x8 qf[4];
; #pragma unroll
;     for (int s = 0; s < 4; ++s) qf[s] = *(const bf16x8*)(qgp + 16 * s);
;     f32x16 o[4];
; #pragma unroll
;     for (int vb = 0; vb < 4; ++vb) {
;         o[vb] = f32x16{};
; #pragma unroll
;         for (int s = 0; s < 4; ++s) { const float* s0 = sp + (size_t)(16 * s + 8 * hi) * 128 + 32 * vb + r;
;             const bf16x8 bfv = pack8(s0[0], s0[128], s0[256], s0[384], s0[512], s0[640], s0[768], s0[896]);
;             o[vb] = MFMA32(qf[s], bfv, o[vb]); }
;         asm volatile("" ::: "memory");
;     }
.LBB0_604:
	s_mov_b64 s[2:3], s[84:85]
	s_mov_b64 s[0:1], s[86:87]
	s_ashr_i32 s2, s35, 8
	s_ashr_i32 s3, s2, 31
	s_lshl_b64 s[2:3], s[2:3], 12
	s_and_b32 s5, s8, 0xfc0
	s_or_b32 s2, s2, s5
	s_or_b64 s[2:3], s[2:3], s[6:7]
	v_mov_b32_e32 v3, s3
	v_or_b32_e32 v2, s2, v152
	s_bfe_u32 s4, s35, 0x20006
	v_lshlrev_b64 v[2:3], 9, v[2:3]
	v_lshl_add_u64 v[2:3], s[0:1], 0, v[2:3]
	s_lshl_b32 s10, s4, 7
	v_lshl_add_u64 v[2:3], v[2:3], 0, s[10:11]
	v_lshl_add_u64 v[2:3], v[2:3], 0, v[86:87]
	v_lshl_add_u64 v[4:5], v[2:3], 0, s[16:17]
	v_add_co_u32_e32 v2, vcc, s13, v2
	v_lshl_add_u64 v[90:91], s[0:1], 0, v[84:85]
	s_nop 0
	v_addc_co_u32_e32 v3, vcc, 0, v3, vcc
	global_load_dwordx4 v[50:53], v[2:3], off
	global_load_dwordx4 v[110:113], v[4:5], off offset:96
	global_load_dwordx4 v[106:109], v[4:5], off offset:64
	global_load_dwordx4 v[102:105], v[4:5], off offset:32
	v_add_co_u32_e32 v2, vcc, s24, v90
	s_lshl_b64 s[2:3], s[2:3], 10
	s_nop 0
	v_addc_co_u32_e32 v3, vcc, -1, v91, vcc
	v_add_co_u32_e32 v58, vcc, s28, v90
	global_load_dword v2, v[2:3], off
	s_nop 0
	v_addc_co_u32_e32 v59, vcc, -1, v91, vcc
	global_load_dword v3, v[58:59], off offset:384
	global_load_dword v4, v[58:59], off offset:896
	global_load_dword v5, v[58:59], off offset:1408
	global_load_dword v6, v[58:59], off offset:1920
	global_load_dword v7, v[58:59], off offset:2432
	global_load_dword v8, v[58:59], off offset:2944
	global_load_dword v9, v[58:59], off offset:3456
	v_add_co_u32_e32 v18, vcc, s25, v90
	s_lshl_b32 s4, s4, 8
	s_nop 0
	v_addc_co_u32_e32 v19, vcc, -1, v91, vcc
	v_add_co_u32_e32 v114, vcc, s29, v90
	global_load_dword v18, v[18:19], off
	s_nop 0
	v_addc_co_u32_e32 v115, vcc, -1, v91, vcc
	global_load_dword v19, v[114:115], off offset:384
	global_load_dword v20, v[114:115], off offset:896
	global_load_dword v21, v[114:115], off offset:1408
	global_load_dword v22, v[114:115], off offset:1920
	global_load_dword v23, v[114:115], off offset:2432
	global_load_dword v24, v[114:115], off offset:2944
	global_load_dword v25, v[114:115], off offset:3456
	s_add_u32 s0, s0, s2
	s_addc_u32 s1, s1, s3
	s_add_u32 s0, s0, s4
	s_addc_u32 s1, s1, 0
	s_add_i32 s35, s35, s12
	s_add_i32 s8, s8, s9
	v_lshl_add_u64 v[84:85], v[84:85], 0, s[14:15]
	s_cmpk_lt_i32 s35, 0x800
	s_waitcnt vmcnt(0) lgkmcnt(0)
	global_load_dword v41, v[114:115], off offset:3584
	global_load_dword v40, v[114:115], off offset:3072
	global_load_dword v39, v[114:115], off offset:2560
	global_load_dword v38, v[114:115], off offset:2048
	global_load_dword v37, v[114:115], off offset:1536
	global_load_dword v36, v[114:115], off offset:1024
	global_load_dword v35, v[114:115], off offset:512
	global_load_dword v34, v[114:115], off
	global_load_dword v145, v[58:59], off offset:3584
	global_load_dword v146, v[58:59], off offset:3072
	global_load_dword v143, v[58:59], off offset:2560
	global_load_dword v144, v[58:59], off offset:2048
	global_load_dword v141, v[58:59], off offset:1536
	global_load_dword v142, v[58:59], off offset:1024
	global_load_dword v139, v[58:59], off offset:512
	global_load_dword v140, v[58:59], off
	v_cvt_pk_bf16_f32 v2, v2, v3
	v_cvt_pk_bf16_f32 v3, v4, v5
	v_cvt_pk_bf16_f32 v4, v6, v7
	v_cvt_pk_bf16_f32 v5, v8, v9
	v_cvt_pk_bf16_f32 v18, v18, v19
	s_nop 0
	v_mfma_f32_32x32x16_bf16 v[2:17], v[50:53], v[2:5], 0
	v_cvt_pk_bf16_f32 v19, v20, v21
	v_cvt_pk_bf16_f32 v20, v22, v23
	v_cvt_pk_bf16_f32 v21, v24, v25
	s_nop 1
	v_mfma_f32_32x32x16_bf16 v[2:17], v[102:105], v[18:21], v[2:17]
	v_add_co_u32_e32 v18, vcc, s26, v90
	s_nop 1
	v_addc_co_u32_e32 v19, vcc, -1, v91, vcc
	v_add_co_u32_e32 v118, vcc, s30, v90
	global_load_dword v18, v[18:19], off
	s_nop 0
	v_addc_co_u32_e32 v119, vcc, -1, v91, vcc
	global_load_dword v19, v[118:119], off offset:384
	global_load_dword v20, v[118:119], off offset:896
	global_load_dword v21, v[118:119], off offset:1408
	global_load_dword v22, v[118:119], off offset:1920
	global_load_dword v23, v[118:119], off offset:2432
	global_load_dword v24, v[118:119], off offset:2944
	global_load_dword v25, v[118:119], off offset:3456
	s_waitcnt vmcnt(0) lgkmcnt(0)
	global_load_dword v63, v[114:115], off offset:3712
	global_load_dword v62, v[114:115], off offset:3200
	global_load_dword v61, v[114:115], off offset:2688
	global_load_dword v60, v[114:115], off offset:2176
	global_load_dword v57, v[114:115], off offset:1664
	global_load_dword v56, v[114:115], off offset:1152
	global_load_dword v55, v[114:115], off offset:640
	global_load_dword v54, v[114:115], off offset:128
	global_load_dword v173, v[58:59], off offset:3712
	global_load_dword v176, v[58:59], off offset:3200
	global_load_dword v171, v[58:59], off offset:2688
	global_load_dword v174, v[58:59], off offset:2176
	global_load_dword v169, v[58:59], off offset:1664
	global_load_dword v172, v[58:59], off offset:1152
	global_load_dword v167, v[58:59], off offset:640
	global_load_dword v170, v[58:59], off offset:128
	global_load_dword v157, v[118:119], off offset:3584
	global_load_dword v160, v[118:119], off offset:3072
	global_load_dword v155, v[118:119], off offset:2560
	global_load_dword v158, v[118:119], off offset:2048
	global_load_dword v149, v[118:119], off offset:1536
	global_load_dword v156, v[118:119], off offset:1024
	global_load_dword v147, v[118:119], off offset:512
	global_load_dword v148, v[118:119], off
	v_cvt_pk_bf16_f32 v18, v18, v19
	v_cvt_pk_bf16_f32 v19, v20, v21
	v_cvt_pk_bf16_f32 v20, v22, v23
	v_cvt_pk_bf16_f32 v21, v24, v25
	s_nop 1
	v_mfma_f32_32x32x16_bf16 v[2:17], v[106:109], v[18:21], v[2:17]
	v_add_co_u32_e32 v18, vcc, s27, v90
	s_nop 1
	v_addc_co_u32_e32 v19, vcc, -1, v91, vcc
	v_add_co_u32_e32 v120, vcc, s31, v90
	global_load_dword v18, v[18:19], off
	s_nop 0
	v_addc_co_u32_e32 v121, vcc, -1, v91, vcc
	global_load_dword v19, v[120:121], off offset:384
	global_load_dword v20, v[120:121], off offset:896
	global_load_dword v21, v[120:121], off offset:1408
	global_load_dword v22, v[120:121], off offset:1920
	global_load_dword v23, v[120:121], off offset:2432
	global_load_dword v24, v[120:121], off offset:2944
	global_load_dword v25, v[120:121], off offset:3456
	v_cmp_lt_i32_e32 vcc, v94, v95
	s_waitcnt vmcnt(0) lgkmcnt(0)
; #define MFMA32(a, b, c) __builtin_amdgcn_mfma_f32_32x32x16_bf16((a), (b), (c), 0, 0, 0)
; DI void gla_stage3(const Ctx& c0, int layer, int unit, int cb, LAS unsigned char* lds) {
;     ...
;     for (int vb = 0; vb < 4; ++vb) {
;         o[vb] = f32x16{};
; #pragma unroll
;         for (int s = 0; s < 4; ++s) { const float* s0 = sp + (size_t)(16 * s + 8 * hi) * 128 + 32 * vb + r;
;             const bf16x8 bfv = pack8(s0[0], s0[128], s0[256], s0[384], s0[512], s0[640], s0[768], s0[896]);
;             o[vb] = MFMA32(qf[s], bfv, o[vb]); }
;         asm volatile("" ::: "memory");
;     }
	global_load_dword v127, v[114:115], off offset:3840
	global_load_dword v126, v[114:115], off offset:3328
	global_load_dword v125, v[114:115], off offset:2816
	global_load_dword v124, v[114:115], off offset:2304
	global_load_dword v123, v[114:115], off offset:1792
	global_load_dword v122, v[114:115], off offset:1280
	global_load_dword v117, v[114:115], off offset:768
	global_load_dword v116, v[114:115], off offset:256
	global_load_dword v214, v[58:59], off offset:3840
	global_load_dword v212, v[58:59], off offset:3328
	global_load_dword v205, v[58:59], off offset:2816
	global_load_dword v210, v[58:59], off offset:2304
	global_load_dword v203, v[58:59], off offset:1792
	global_load_dword v208, v[58:59], off offset:1280
	global_load_dword v201, v[58:59], off offset:768
	global_load_dword v206, v[58:59], off offset:256
	global_load_dword v199, v[120:121], off offset:3712
	global_load_dword v204, v[120:121], off offset:3200
	global_load_dword v197, v[120:121], off offset:2688
	global_load_dword v202, v[120:121], off offset:2176
	global_load_dword v195, v[120:121], off offset:1664
	global_load_dword v200, v[120:121], off offset:1152
	global_load_dword v183, v[120:121], off offset:640
	global_load_dword v198, v[120:121], off offset:128
	global_load_dword v181, v[118:119], off offset:3712
	global_load_dword v196, v[118:119], off offset:3200
	global_load_dword v179, v[118:119], off offset:2688
	global_load_dword v182, v[118:119], off offset:2176
	global_load_dword v177, v[118:119], off offset:1664
	global_load_dword v180, v[118:119], off offset:1152
	global_load_dword v175, v[118:119], off offset:640
	global_load_dword v178, v[118:119], off offset:128
	global_load_dword v165, v[120:121], off offset:3584
	global_load_dword v168, v[120:121], off offset:3072
	global_load_dword v163, v[120:121], off offset:2560
	global_load_dword v166, v[120:121], off offset:2048
	global_load_dword v161, v[120:121], off offset:1536
	global_load_dword v164, v[120:121], off offset:1024
	global_load_dword v159, v[120:121], off offset:512
	global_load_dword v162, v[120:121], off
	v_cvt_pk_bf16_f32 v18, v18, v19
	v_cvt_pk_bf16_f32 v19, v20, v21
	v_cvt_pk_bf16_f32 v20, v22, v23
	v_cvt_pk_bf16_f32 v21, v24, v25
	s_nop 1
	v_mfma_f32_32x32x16_bf16 v[2:17], v[110:113], v[18:21], v[2:17]
	s_waitcnt vmcnt(40) lgkmcnt(0)
	global_load_dword v238, v[82:83], off offset:384
	global_load_dword v236, v[82:83], off offset:256
	global_load_dword v234, v[82:83], off offset:128
	global_load_dword v232, v[82:83], off
	global_load_dword v90, v[90:91], off
	global_load_dword v230, v[120:121], off offset:3328
	global_load_dword v219, v[120:121], off offset:2816
	global_load_dword v228, v[120:121], off offset:2304
	global_load_dword v217, v[120:121], off offset:1792
	global_load_dword v226, v[120:121], off offset:1280
	global_load_dword v215, v[120:121], off offset:768
	global_load_dword v224, v[120:121], off offset:256
	global_load_dword v213, v[118:119], off offset:3840
	global_load_dword v222, v[118:119], off offset:3328
	global_load_dword v211, v[118:119], off offset:2816
	global_load_dword v220, v[118:119], off offset:2304
	global_load_dword v209, v[118:119], off offset:1792
	global_load_dword v218, v[118:119], off offset:1280
	global_load_dword v207, v[118:119], off offset:768
	global_load_dword v216, v[118:119], off offset:256
	v_cvt_pk_bf16_f32 v18, v140, v139
	v_cvt_pk_bf16_f32 v34, v34, v35
	v_cvt_pk_bf16_f32 v19, v142, v141
	v_cvt_pk_bf16_f32 v35, v36, v37
	v_cvt_pk_bf16_f32 v20, v144, v143
	v_cvt_pk_bf16_f32 v36, v38, v39
	v_cvt_pk_bf16_f32 v21, v146, v145
	v_cvt_pk_bf16_f32 v37, v40, v41
	s_nop 0
	v_mfma_f32_32x32x16_bf16 v[18:33], v[50:53], v[18:21], 0
	v_mfma_f32_32x32x16_bf16 v[18:33], v[102:105], v[34:37], v[18:33]
	s_waitcnt vmcnt(60) lgkmcnt(0)
	v_cvt_pk_bf16_f32 v34, v148, v147
	v_cvt_pk_bf16_f32 v35, v156, v149
	v_cvt_pk_bf16_f32 v36, v158, v155
	v_cvt_pk_bf16_f32 v37, v160, v157
	s_nop 1
	v_mfma_f32_32x32x16_bf16 v[18:33], v[106:109], v[34:37], v[18:33]
	s_waitcnt vmcnt(20) lgkmcnt(0)
	v_cvt_pk_bf16_f32 v34, v162, v159
	v_cvt_pk_bf16_f32 v35, v164, v161
	v_cvt_pk_bf16_f32 v36, v166, v163
	v_cvt_pk_bf16_f32 v37, v168, v165
	s_nop 1
	v_mfma_f32_32x32x16_bf16 v[18:33], v[110:113], v[34:37], v[18:33]
	s_waitcnt vmcnt(62) lgkmcnt(0)
	v_cvt_pk_bf16_f32 v34, v170, v167
	v_cvt_pk_bf16_f32 v54, v54, v55
	v_cvt_pk_bf16_f32 v35, v172, v169
	v_cvt_pk_bf16_f32 v55, v56, v57
	v_cvt_pk_bf16_f32 v36, v174, v171
	v_cvt_pk_bf16_f32 v56, v60, v61
	v_cvt_pk_bf16_f32 v37, v176, v173
	v_cvt_pk_bf16_f32 v57, v62, v63
	s_nop 0
	v_mfma_f32_32x32x16_bf16 v[34:49], v[50:53], v[34:37], 0
	v_mfma_f32_32x32x16_bf16 v[34:49], v[102:105], v[54:57], v[34:49]
	s_waitcnt vmcnt(28) lgkmcnt(0)
	v_cvt_pk_bf16_f32 v54, v178, v175
	v_cvt_pk_bf16_f32 v55, v180, v177
	v_cvt_pk_bf16_f32 v56, v182, v179
	v_cvt_pk_bf16_f32 v57, v196, v181
	s_nop 1
	v_mfma_f32_32x32x16_bf16 v[34:49], v[106:109], v[54:57], v[34:49]
	s_waitcnt vmcnt(36) lgkmcnt(0)
	v_cvt_pk_bf16_f32 v54, v198, v183
	v_cvt_pk_bf16_f32 v55, v200, v195
	v_cvt_pk_bf16_f32 v56, v202, v197
	v_cvt_pk_bf16_f32 v57, v204, v199
	s_nop 1
	v_mfma_f32_32x32x16_bf16 v[34:49], v[110:113], v[54:57], v[34:49]
	s_nop 0
	s_nop 0
	s_waitcnt vmcnt(44) lgkmcnt(0)
	v_cvt_pk_bf16_f32 v54, v206, v201
	v_cvt_pk_bf16_f32 v114, v116, v117
	v_cvt_pk_bf16_f32 v55, v208, v203
	v_cvt_pk_bf16_f32 v115, v122, v123
	v_cvt_pk_bf16_f32 v56, v210, v205
	v_cvt_pk_bf16_f32 v116, v124, v125
	v_cvt_pk_bf16_f32 v57, v212, v214
	v_cvt_pk_bf16_f32 v117, v126, v127
	s_nop 0
	v_mfma_f32_32x32x16_bf16 v[50:65], v[50:53], v[54:57], 0
	v_mfma_f32_32x32x16_bf16 v[50:65], v[102:105], v[114:117], v[50:65]
	s_waitcnt vmcnt(0) lgkmcnt(0)
; #define LAS __attribute__((address_space(3)))
; #define LDS_WAIT() asm volatile("s_waitcnt lgkmcnt(0)" ::: "memory")
; DI float bf2f(bf16 b) { return __uint_as_float(((unsigned)b) << 16); }
; DI void g3_tile_in(const bf16* g, LAS unsigned char* R, int lane) {
; #pragma unroll
;     for (int it = 0; it < 8; ++it) { const int row = 4 * it + (lane >> 4), ch = lane & 15;
;         *(LAS u32x4*)(R + row * G3_PITCH + ch * 16) = *(const u32x4*)(g + (size_t)row * 512 + ch * 8); }
;     LDS_WAIT();
; }
; DI void gla_stage3(const Ctx& c0, int layer, int unit, int cb, LAS unsigned char* lds) {
;     ...
;     g3_tile_in((const bf16*)(c.ws + O_OINTRA) + row0 * 512 + h * 128, R, lane);
; #pragma unroll
;     for (int vb = 0; vb < 4; ++vb) {
; #pragma unroll
;         for (int rg = 0; rg < 16; ++rg) o[vb][rg] += bf2f(*(const LAS bf16*)(Re + ((rg & 3) + 8 * (rg >> 2)) * G3_PITCH + 64 * vb));
;         asm volatile("" ::: "memory");
;     }
	v_cvt_pk_bf16_f32 v102, v216, v207
	v_cvt_pk_bf16_f32 v103, v218, v209
	v_cvt_pk_bf16_f32 v104, v220, v211
	v_cvt_pk_bf16_f32 v105, v222, v213
	s_nop 1
	v_mfma_f32_32x32x16_bf16 v[50:65], v[106:109], v[102:105], v[50:65]
	s_nop 0
	s_waitcnt vmcnt(8) lgkmcnt(0)
	v_cvt_pk_bf16_f32 v102, v224, v215
	v_cvt_pk_bf16_f32 v103, v226, v217
	v_cvt_pk_bf16_f32 v104, v228, v219
	v_cvt_pk_bf16_f32 v105, v230, v90
	v_lshl_add_u64 v[90:91], s[0:1], 0, v[88:89]
	v_lshl_add_u64 v[106:107], v[90:91], 0, s[18:19]
	v_mfma_f32_32x32x16_bf16 v[50:65], v[110:113], v[102:105], v[50:65]
	v_lshl_add_u64 v[102:103], v[106:107], 0, v[66:67]
	global_load_dwordx4 v[102:105], v[102:103], off
	s_waitcnt vmcnt(0) lgkmcnt(0)
	v_lshl_add_u64 v[168:169], v[90:91], 0, s[20:21]
	v_lshl_add_u64 v[140:141], v[168:169], 0, v[70:71]
	global_load_dwordx4 v[174:177], v[140:141], off
	v_lshl_add_u64 v[140:141], v[106:107], 0, v[70:71]
	global_load_dwordx4 v[146:149], v[140:141], off
	v_lshl_add_u64 v[144:145], v[106:107], 0, v[68:69]
	global_load_dwordx4 v[140:143], v[144:145], off
	ds_write_b128 v92, v[102:105]
	s_waitcnt vmcnt(0) lgkmcnt(0)
	v_lshl_add_u64 v[144:145], v[168:169], 0, v[76:77]
	global_load_dwordx4 v[200:203], v[144:145], off
	v_lshl_add_u64 v[144:145], v[168:169], 0, v[74:75]
	global_load_dwordx4 v[196:199], v[144:145], off
	v_lshl_add_u64 v[144:145], v[168:169], 0, v[72:73]
	global_load_dwordx4 v[178:181], v[144:145], off
	v_lshl_add_u64 v[144:145], v[106:107], 0, v[74:75]
	global_load_dwordx4 v[156:159], v[144:145], off
	v_lshl_add_u64 v[102:103], v[106:107], 0, v[72:73]
	global_load_dwordx4 v[102:105], v[102:103], off
	ds_write_b128 v92, v[140:143] offset:1088
	s_waitcnt vmcnt(5) lgkmcnt(0)
	v_lshl_add_u64 v[140:141], v[168:169], 0, v[78:79]
	global_load_dwordx4 v[204:207], v[140:141], off
	v_lshl_add_u64 v[140:141], v[106:107], 0, v[78:79]
	global_load_dwordx4 v[160:163], v[140:141], off
	v_lshl_add_u64 v[144:145], v[106:107], 0, v[76:77]
	global_load_dwordx4 v[140:143], v[144:145], off
	ds_write_b128 v92, v[146:149] offset:2176
	s_waitcnt vmcnt(3) lgkmcnt(0)
	v_lshl_add_u64 v[144:145], v[168:169], 0, v[66:67]
	global_load_dwordx4 v[164:167], v[144:145], off
	v_lshl_add_u64 v[148:149], v[106:107], 0, v[80:81]
	global_load_dwordx4 v[144:147], v[148:149], off
	ds_write_b128 v92, v[102:105] offset:3264
	s_waitcnt vmcnt(6) lgkmcnt(0)
	v_lshl_add_u64 v[148:149], v[168:169], 0, v[68:69]
	global_load_dwordx4 v[170:173], v[148:149], off
	ds_write_b128 v92, v[156:159] offset:4352
	s_waitcnt vmcnt(3) lgkmcnt(0)
	ds_write_b128 v92, v[140:143] offset:5440
	s_waitcnt vmcnt(4) lgkmcnt(0)
	ds_write_b128 v92, v[160:163] offset:6528
	s_waitcnt vmcnt(1) lgkmcnt(0)
	ds_write_b128 v92, v[144:147] offset:7616
	s_waitcnt lgkmcnt(0)
	ds_read_u16 v102, v1
	s_waitcnt lgkmcnt(0)
	v_lshlrev_b32_e32 v102, 16, v102
	v_add_f32_e32 v138, v2, v102
	ds_read_u16 v2, v1 offset:272
	s_waitcnt lgkmcnt(0)
	v_lshlrev_b32_e32 v2, 16, v2
	v_add_f32_e32 v137, v3, v2
	ds_read_u16 v2, v1 offset:544
	s_waitcnt lgkmcnt(0)
	v_lshlrev_b32_e32 v2, 16, v2
	v_add_f32_e32 v136, v4, v2
	ds_read_u16 v2, v1 offset:816
	s_waitcnt lgkmcnt(0)
	v_lshlrev_b32_e32 v2, 16, v2
	v_add_f32_e32 v135, v5, v2
	ds_read_u16 v2, v1 offset:2176
	s_waitcnt lgkmcnt(0)
	v_lshlrev_b32_e32 v2, 16, v2
	v_add_f32_e32 v134, v6, v2
	ds_read_u16 v2, v1 offset:2448
	s_waitcnt lgkmcnt(0)
	v_lshlrev_b32_e32 v2, 16, v2
	v_add_f32_e32 v133, v7, v2
	ds_read_u16 v2, v1 offset:2720
	s_waitcnt lgkmcnt(0)
	v_lshlrev_b32_e32 v2, 16, v2
	v_add_f32_e32 v132, v8, v2
	ds_read_u16 v2, v1 offset:2992
	s_waitcnt lgkmcnt(0)
	v_lshlrev_b32_e32 v2, 16, v2
	v_add_f32_e32 v131, v9, v2
	ds_read_u16 v2, v1 offset:4352
	s_waitcnt lgkmcnt(0)
	v_lshlrev_b32_e32 v2, 16, v2
	v_add_f32_e32 v130, v10, v2
	ds_read_u16 v2, v1 offset:4624
	s_waitcnt lgkmcnt(0)
	v_lshlrev_b32_e32 v2, 16, v2
	v_add_f32_e32 v129, v11, v2
	ds_read_u16 v2, v1 offset:4896
	s_waitcnt lgkmcnt(0)
	v_lshlrev_b32_e32 v2, 16, v2
	v_add_f32_e32 v128, v12, v2
	ds_read_u16 v2, v1 offset:5168
	s_waitcnt lgkmcnt(0)
	v_lshlrev_b32_e32 v2, 16, v2
	v_add_f32_e32 v127, v13, v2
	ds_read_u16 v2, v1 offset:6528
	s_waitcnt lgkmcnt(0)
	v_lshlrev_b32_e32 v2, 16, v2
	v_add_f32_e32 v126, v14, v2
	ds_read_u16 v2, v1 offset:6800
	s_waitcnt lgkmcnt(0)
	v_lshlrev_b32_e32 v2, 16, v2
	v_add_f32_e32 v125, v15, v2
	ds_read_u16 v2, v1 offset:7072
	s_waitcnt lgkmcnt(0)
	v_lshlrev_b32_e32 v2, 16, v2
	v_add_f32_e32 v124, v16, v2
	ds_read_u16 v2, v1 offset:7344
	s_waitcnt lgkmcnt(0)
	v_lshlrev_b32_e32 v2, 16, v2
	v_add_f32_e32 v123, v17, v2
	ds_read_u16 v2, v1 offset:64
	s_waitcnt lgkmcnt(0)
	v_lshlrev_b32_e32 v2, 16, v2
	v_add_f32_e32 v122, v18, v2
	ds_read_u16 v2, v1 offset:336
	s_waitcnt lgkmcnt(0)
	v_lshlrev_b32_e32 v2, 16, v2
	v_add_f32_e32 v121, v19, v2
	ds_read_u16 v2, v1 offset:608
	s_waitcnt lgkmcnt(0)
	v_lshlrev_b32_e32 v2, 16, v2
	v_add_f32_e32 v120, v20, v2
	ds_read_u16 v2, v1 offset:880
	s_waitcnt lgkmcnt(0)
	v_lshlrev_b32_e32 v2, 16, v2
	v_add_f32_e32 v119, v21, v2
	ds_read_u16 v2, v1 offset:2240
	s_waitcnt lgkmcnt(0)
	v_lshlrev_b32_e32 v2, 16, v2
	v_add_f32_e32 v118, v22, v2
	ds_read_u16 v2, v1 offset:2512
	s_waitcnt lgkmcnt(0)
	v_lshlrev_b32_e32 v2, 16, v2
	v_add_f32_e32 v117, v23, v2
	ds_read_u16 v2, v1 offset:2784
	s_waitcnt lgkmcnt(0)
	v_lshlrev_b32_e32 v2, 16, v2
	v_add_f32_e32 v116, v24, v2
	ds_read_u16 v2, v1 offset:3056
	s_waitcnt lgkmcnt(0)
	v_lshlrev_b32_e32 v2, 16, v2
	v_add_f32_e32 v115, v25, v2
	ds_read_u16 v2, v1 offset:4416
	s_waitcnt lgkmcnt(0)
	v_lshlrev_b32_e32 v2, 16, v2
	v_add_f32_e32 v114, v26, v2
	ds_read_u16 v2, v1 offset:4688
	s_waitcnt lgkmcnt(0)
; #define LAS __attribute__((address_space(3)))
; DI float bf2f(bf16 b) { return __uint_as_float(((unsigned)b) << 16); }
; DI void gla_stage3(const Ctx& c0, int layer, int unit, int cb, LAS unsigned char* lds) {
;     ...
;     for (int vb = 0; vb < 4; ++vb) {
; #pragma unroll
;         for (int rg = 0; rg < 16; ++rg) o[vb][rg] += bf2f(*(const LAS bf16*)(Re + ((rg & 3) + 8 * (rg >> 2)) * G3_PITCH + 64 * vb));
;         asm volatile("" ::: "memory");
;     }
	v_lshlrev_b32_e32 v2, 16, v2
	v_add_f32_e32 v113, v27, v2
	ds_read_u16 v2, v1 offset:4960
	s_waitcnt lgkmcnt(0)
	v_lshlrev_b32_e32 v2, 16, v2
	v_add_f32_e32 v112, v28, v2
	ds_read_u16 v2, v1 offset:5232
	s_waitcnt lgkmcnt(0)
	v_lshlrev_b32_e32 v2, 16, v2
	v_add_f32_e32 v111, v29, v2
	ds_read_u16 v2, v1 offset:6592
	s_waitcnt lgkmcnt(0)
	v_lshlrev_b32_e32 v2, 16, v2
	v_add_f32_e32 v110, v30, v2
	ds_read_u16 v2, v1 offset:6864
	s_waitcnt lgkmcnt(0)
	v_lshlrev_b32_e32 v2, 16, v2
	v_add_f32_e32 v109, v31, v2
	ds_read_u16 v2, v1 offset:7136
	s_waitcnt lgkmcnt(0)
	v_lshlrev_b32_e32 v2, 16, v2
	v_add_f32_e32 v108, v32, v2
	ds_read_u16 v2, v1 offset:7408
	s_waitcnt lgkmcnt(0)
	v_lshlrev_b32_e32 v2, 16, v2
	v_add_f32_e32 v107, v33, v2
	ds_read_u16 v2, v1 offset:128
	s_waitcnt lgkmcnt(0)
	v_lshlrev_b32_e32 v2, 16, v2
	v_add_f32_e32 v106, v34, v2
	ds_read_u16 v2, v1 offset:400
	s_waitcnt lgkmcnt(0)
	v_lshlrev_b32_e32 v2, 16, v2
	v_add_f32_e32 v105, v35, v2
	ds_read_u16 v2, v1 offset:672
	s_waitcnt lgkmcnt(0)
	v_lshlrev_b32_e32 v2, 16, v2
	v_add_f32_e32 v104, v36, v2
	ds_read_u16 v2, v1 offset:944
	s_waitcnt lgkmcnt(0)
	v_lshlrev_b32_e32 v2, 16, v2
	v_add_f32_e32 v103, v37, v2
	ds_read_u16 v2, v1 offset:2304
	s_waitcnt lgkmcnt(0)
	v_lshlrev_b32_e32 v2, 16, v2
	v_add_f32_e32 v102, v38, v2
	ds_read_u16 v2, v1 offset:2576
	s_waitcnt lgkmcnt(0)
	v_lshlrev_b32_e32 v2, 16, v2
	v_add_f32_e32 v39, v39, v2
	ds_read_u16 v2, v1 offset:2848
	s_waitcnt lgkmcnt(0)
	v_lshlrev_b32_e32 v2, 16, v2
	v_add_f32_e32 v38, v40, v2
	ds_read_u16 v2, v1 offset:3120
	s_waitcnt lgkmcnt(0)
	v_lshlrev_b32_e32 v2, 16, v2
	v_add_f32_e32 v37, v41, v2
	ds_read_u16 v2, v1 offset:4480
	s_waitcnt lgkmcnt(0)
	v_lshlrev_b32_e32 v2, 16, v2
	v_add_f32_e32 v36, v42, v2
	ds_read_u16 v2, v1 offset:4752
	s_waitcnt lgkmcnt(0)
	v_lshlrev_b32_e32 v2, 16, v2
	v_add_f32_e32 v34, v43, v2
	ds_read_u16 v2, v1 offset:5024
	s_waitcnt lgkmcnt(0)
	v_lshlrev_b32_e32 v2, 16, v2
	v_add_f32_e32 v33, v44, v2
	ds_read_u16 v2, v1 offset:5296
	s_waitcnt lgkmcnt(0)
	v_lshlrev_b32_e32 v2, 16, v2
	v_add_f32_e32 v32, v45, v2
	ds_read_u16 v2, v1 offset:6656
	s_waitcnt lgkmcnt(0)
	v_lshlrev_b32_e32 v2, 16, v2
	v_add_f32_e32 v30, v46, v2
	ds_read_u16 v2, v1 offset:6928
	s_waitcnt lgkmcnt(0)
	v_lshlrev_b32_e32 v2, 16, v2
	v_add_f32_e32 v29, v47, v2
	ds_read_u16 v2, v1 offset:7200
	s_waitcnt lgkmcnt(0)
	v_lshlrev_b32_e32 v2, 16, v2
	v_add_f32_e32 v28, v48, v2
	ds_read_u16 v2, v1 offset:7472
	s_waitcnt lgkmcnt(0)
	v_lshlrev_b32_e32 v2, 16, v2
	v_add_f32_e32 v26, v49, v2
	ds_read_u16 v2, v1 offset:192
	s_waitcnt lgkmcnt(0)
	v_lshlrev_b32_e32 v2, 16, v2
	v_add_f32_e32 v19, v50, v2
	ds_read_u16 v2, v1 offset:464
	s_waitcnt lgkmcnt(0)
	v_lshlrev_b32_e32 v2, 16, v2
	v_add_f32_e32 v18, v51, v2
	ds_read_u16 v2, v1 offset:736
	s_waitcnt lgkmcnt(0)
	v_lshlrev_b32_e32 v2, 16, v2
	v_add_f32_e32 v17, v52, v2
	ds_read_u16 v2, v1 offset:1008
	s_waitcnt lgkmcnt(0)
	v_lshlrev_b32_e32 v2, 16, v2
	v_add_f32_e32 v16, v53, v2
	ds_read_u16 v2, v1 offset:2368
	s_waitcnt lgkmcnt(0)
	v_lshlrev_b32_e32 v2, 16, v2
	v_add_f32_e32 v15, v54, v2
	ds_read_u16 v2, v1 offset:2640
	s_waitcnt lgkmcnt(0)
	v_lshlrev_b32_e32 v2, 16, v2
	v_add_f32_e32 v14, v55, v2
	ds_read_u16 v2, v1 offset:2912
	s_waitcnt lgkmcnt(0)
	v_lshlrev_b32_e32 v2, 16, v2
	v_add_f32_e32 v13, v56, v2
	ds_read_u16 v2, v1 offset:3184
	s_waitcnt lgkmcnt(0)
	v_lshlrev_b32_e32 v2, 16, v2
	v_add_f32_e32 v12, v57, v2
	ds_read_u16 v2, v1 offset:4544
	s_waitcnt lgkmcnt(0)
	v_lshlrev_b32_e32 v2, 16, v2
	v_add_f32_e32 v11, v58, v2
	ds_read_u16 v2, v1 offset:4816
	s_waitcnt lgkmcnt(0)
	v_lshlrev_b32_e32 v2, 16, v2
	v_add_f32_e32 v10, v59, v2
	ds_read_u16 v2, v1 offset:5088
	s_waitcnt lgkmcnt(0)
	v_lshlrev_b32_e32 v2, 16, v2
	v_add_f32_e32 v9, v60, v2
	ds_read_u16 v2, v1 offset:5360
	s_waitcnt lgkmcnt(0)
	v_lshlrev_b32_e32 v2, 16, v2
	v_add_f32_e32 v8, v61, v2
	ds_read_u16 v2, v1 offset:6720
	s_waitcnt lgkmcnt(0)
	v_lshlrev_b32_e32 v2, 16, v2
	v_add_f32_e32 v7, v62, v2
	ds_read_u16 v2, v1 offset:6992
	s_waitcnt lgkmcnt(0)
	v_lshlrev_b32_e32 v2, 16, v2
	v_add_f32_e32 v6, v63, v2
	ds_read_u16 v2, v1 offset:7264
	s_waitcnt lgkmcnt(0)
	v_lshlrev_b32_e32 v2, 16, v2
	v_add_f32_e32 v5, v64, v2
	ds_read_u16 v2, v1 offset:7536
	s_waitcnt lgkmcnt(0)
	s_waitcnt lgkmcnt(0)
; DI void gla_stage3(const Ctx& c0, int layer, int unit, int cb, LAS unsigned char* lds) {
;     ...
;     float rs[16];
; #pragma unroll
;     for (int rg = 0; rg < 16; ++rg) { float ss = o[0][rg] * o[0][rg] + o[1][rg] * o[1][rg] + o[2][rg] * o[2][rg] + o[3][rg] * o[3][rg];
;         ss += __shfl_xor(ss, 1); ss += __shfl_xor(ss, 2); ss += __shfl_xor(ss, 4); ss += __shfl_xor(ss, 8); ss += __shfl_xor(ss, 16);
;         rs[rg] = 1.f / sqrtf(ss * (1.f / 128.f) + EPS); }
	v_lshlrev_b32_e32 v2, 16, v2
	v_add_f32_e32 v4, v65, v2
	v_cndmask_b32_e32 v2, v93, v94, vcc
	v_cmp_lt_i32_e32 vcc, v96, v95
	v_lshlrev_b32_e32 v2, 2, v2
	s_nop 0
	v_cndmask_b32_e32 v3, v93, v96, vcc
	v_cmp_lt_i32_e32 vcc, v97, v95
	v_lshlrev_b32_e32 v3, 2, v3
	s_nop 0
	v_cndmask_b32_e32 v20, v93, v97, vcc
	v_cmp_lt_i32_e32 vcc, v98, v95
	v_lshlrev_b32_e32 v20, 2, v20
	s_nop 0
	v_cndmask_b32_e32 v21, v93, v98, vcc
	v_cmp_lt_i32_e32 vcc, v99, v95
	v_lshlrev_b32_e32 v47, 2, v21
	s_nop 0
	v_cndmask_b32_e32 v21, v93, v99, vcc
	v_lshlrev_b32_e32 v48, 2, v21
	v_mul_f32_e32 v21, v122, v122
	v_fmac_f32_e32 v21, v138, v138
	v_fmac_f32_e32 v21, v106, v106
	v_fmac_f32_e32 v21, v19, v19
	s_nop 1
	v_add_f32_dpp v21, v21, v21 quad_perm:[1,0,3,2] row_mask:0xf bank_mask:0xf
	s_nop 1
	v_add_f32_dpp v21, v21, v21 quad_perm:[2,3,0,1] row_mask:0xf bank_mask:0xf
	s_nop 1
	v_add_f32_dpp v21, v21, v21 row_half_mirror row_mask:0xf bank_mask:0xf
	s_nop 1
	v_add_f32_dpp v21, v21, v21 row_mirror row_mask:0xf bank_mask:0xf
	v_mov_b32_e32 v22, v21
	v_mov_b32_e32 v23, v21
	s_nop 1
	v_permlane16_swap_b32_e32 v22, v23
	v_add_f32_e32 v21, v22, v23
	v_fmamk_f32 v21, v21, 0x3c000000, v100
	v_cmp_gt_f32_e32 vcc, s34, v21
	v_mul_f32_e32 v22, 0x4f800000, v21
	s_nop 0
	v_cndmask_b32_e32 v21, v21, v22, vcc
	v_sqrt_f32_e32 v22, v21
	s_nop 0
	v_add_u32_e32 v23, -1, v22
	v_fma_f32 v24, -v23, v22, v21
	v_cmp_ge_f32_e64 s[4:5], 0, v24
	v_add_u32_e32 v24, 1, v22
	s_nop 0
	v_cndmask_b32_e64 v23, v22, v23, s[4:5]
	v_fma_f32 v22, -v24, v22, v21
	v_cmp_lt_f32_e64 s[4:5], 0, v22
	s_nop 1
	v_cndmask_b32_e64 v22, v23, v24, s[4:5]
	v_mul_f32_e32 v23, 0x37800000, v22
	v_cndmask_b32_e32 v22, v22, v23, vcc
	v_cmp_class_f32_e32 vcc, v21, v101
	s_nop 1
	v_cndmask_b32_e32 v21, v22, v21, vcc
	s_nop 0
	v_div_scale_f32 v24, vcc, 1.0, v21, 1.0
	v_rcp_f32_e32 v46, v21
	v_mul_f32_e32 v21, v121, v121
	v_fmac_f32_e32 v21, v137, v137
	v_fmac_f32_e32 v21, v105, v105
	v_fmac_f32_e32 v21, v18, v18
	s_nop 1
	v_add_f32_dpp v21, v21, v21 quad_perm:[1,0,3,2] row_mask:0xf bank_mask:0xf
	v_mul_f32_e32 v19, v19, v46
	s_nop 1
	v_add_f32_dpp v21, v21, v21 quad_perm:[2,3,0,1] row_mask:0xf bank_mask:0xf
	s_nop 1
	v_add_f32_dpp v21, v21, v21 row_half_mirror row_mask:0xf bank_mask:0xf
	s_nop 1
	v_add_f32_dpp v21, v21, v21 row_mirror row_mask:0xf bank_mask:0xf
	v_mov_b32_e32 v22, v21
	v_mov_b32_e32 v23, v21
	s_nop 1
	v_permlane16_swap_b32_e32 v22, v23
	v_add_f32_e32 v21, v22, v23
	v_fmamk_f32 v21, v21, 0x3c000000, v100
	v_cmp_gt_f32_e32 vcc, s34, v21
	v_mul_f32_e32 v22, 0x4f800000, v21
	s_nop 0
	v_cndmask_b32_e32 v21, v21, v22, vcc
	v_sqrt_f32_e32 v22, v21
	s_nop 0
	v_add_u32_e32 v23, -1, v22
	v_fma_f32 v24, -v23, v22, v21
	v_cmp_ge_f32_e64 s[4:5], 0, v24
	v_add_u32_e32 v24, 1, v22
	s_nop 0
	v_cndmask_b32_e64 v23, v22, v23, s[4:5]
	v_fma_f32 v22, -v24, v22, v21
	v_cmp_lt_f32_e64 s[4:5], 0, v22
	s_nop 1
	v_cndmask_b32_e64 v22, v23, v24, s[4:5]
	v_mul_f32_e32 v23, 0x37800000, v22
	v_cndmask_b32_e32 v22, v22, v23, vcc
	v_cmp_class_f32_e32 vcc, v21, v101
	s_nop 1
	v_cndmask_b32_e32 v21, v22, v21, vcc
	s_nop 0
	v_div_scale_f32 v24, vcc, 1.0, v21, 1.0
	v_rcp_f32_e32 v45, v21
	v_mul_f32_e32 v21, v120, v120
	v_fmac_f32_e32 v21, v136, v136
	v_fmac_f32_e32 v21, v104, v104
	v_fmac_f32_e32 v21, v17, v17
	s_nop 1
	v_add_f32_dpp v21, v21, v21 quad_perm:[1,0,3,2] row_mask:0xf bank_mask:0xf
	v_mul_f32_e32 v18, v18, v45
	s_nop 1
	v_add_f32_dpp v21, v21, v21 quad_perm:[2,3,0,1] row_mask:0xf bank_mask:0xf
	s_nop 1
	v_add_f32_dpp v21, v21, v21 row_half_mirror row_mask:0xf bank_mask:0xf
	s_nop 1
	v_add_f32_dpp v21, v21, v21 row_mirror row_mask:0xf bank_mask:0xf
	v_mov_b32_e32 v22, v21
	v_mov_b32_e32 v23, v21
	s_nop 1
	v_permlane16_swap_b32_e32 v22, v23
	v_add_f32_e32 v21, v22, v23
	v_fmamk_f32 v21, v21, 0x3c000000, v100
	v_cmp_gt_f32_e32 vcc, s34, v21
	v_mul_f32_e32 v22, 0x4f800000, v21
	s_nop 0
	v_cndmask_b32_e32 v21, v21, v22, vcc
	v_sqrt_f32_e32 v22, v21
	s_nop 0
	v_add_u32_e32 v23, -1, v22
	v_fma_f32 v24, -v23, v22, v21
	v_cmp_ge_f32_e64 s[4:5], 0, v24
	v_add_u32_e32 v24, 1, v22
	s_nop 0
	v_cndmask_b32_e64 v23, v22, v23, s[4:5]
	v_fma_f32 v22, -v24, v22, v21
	v_cmp_lt_f32_e64 s[4:5], 0, v22
	s_nop 1
	v_cndmask_b32_e64 v22, v23, v24, s[4:5]
	v_mul_f32_e32 v23, 0x37800000, v22
	v_cndmask_b32_e32 v22, v22, v23, vcc
	v_cmp_class_f32_e32 vcc, v21, v101
	s_nop 1
	v_cndmask_b32_e32 v21, v22, v21, vcc
	s_nop 0
	v_div_scale_f32 v24, vcc, 1.0, v21, 1.0
	v_rcp_f32_e32 v44, v21
	v_mul_f32_e32 v21, v119, v119
	v_fmac_f32_e32 v21, v135, v135
	v_fmac_f32_e32 v21, v103, v103
	v_fmac_f32_e32 v21, v16, v16
	s_nop 1
	v_add_f32_dpp v21, v21, v21 quad_perm:[1,0,3,2] row_mask:0xf bank_mask:0xf
	v_mul_f32_e32 v17, v17, v44
	s_nop 1
	v_add_f32_dpp v21, v21, v21 quad_perm:[2,3,0,1] row_mask:0xf bank_mask:0xf
	s_nop 1
	v_add_f32_dpp v21, v21, v21 row_half_mirror row_mask:0xf bank_mask:0xf
	s_nop 1
	v_add_f32_dpp v21, v21, v21 row_mirror row_mask:0xf bank_mask:0xf
	v_mov_b32_e32 v22, v21
	v_mov_b32_e32 v23, v21
	s_nop 1
	v_permlane16_swap_b32_e32 v22, v23
	v_add_f32_e32 v21, v22, v23
	v_fmamk_f32 v21, v21, 0x3c000000, v100
	v_cmp_gt_f32_e32 vcc, s34, v21
	v_mul_f32_e32 v22, 0x4f800000, v21
	s_nop 0
	v_cndmask_b32_e32 v21, v21, v22, vcc
	v_sqrt_f32_e32 v22, v21
	s_nop 0
	v_add_u32_e32 v23, -1, v22
	v_fma_f32 v24, -v23, v22, v21
	v_cmp_ge_f32_e64 s[4:5], 0, v24
	v_add_u32_e32 v24, 1, v22
	s_nop 0
	v_cndmask_b32_e64 v23, v22, v23, s[4:5]
	v_fma_f32 v22, -v24, v22, v21
	v_cmp_lt_f32_e64 s[4:5], 0, v22
	s_nop 1
	v_cndmask_b32_e64 v22, v23, v24, s[4:5]
	v_mul_f32_e32 v23, 0x37800000, v22
	v_cndmask_b32_e32 v22, v22, v23, vcc
	v_cmp_class_f32_e32 vcc, v21, v101
	s_nop 1
; DI void gla_stage3(const Ctx& c0, int layer, int unit, int cb, LAS unsigned char* lds) {
;     ...
;     float rs[16];
; #pragma unroll
;     for (int rg = 0; rg < 16; ++rg) { float ss = o[0][rg] * o[0][rg] + o[1][rg] * o[1][rg] + o[2][rg] * o[2][rg] + o[3][rg] * o[3][rg];
;         ss += __shfl_xor(ss, 1); ss += __shfl_xor(ss, 2); ss += __shfl_xor(ss, 4); ss += __shfl_xor(ss, 8); ss += __shfl_xor(ss, 16);
;         rs[rg] = 1.f / sqrtf(ss * (1.f / 128.f) + EPS); }
	v_cndmask_b32_e32 v21, v22, v21, vcc
	s_nop 0
	v_div_scale_f32 v24, vcc, 1.0, v21, 1.0
	v_rcp_f32_e32 v43, v21
	v_mul_f32_e32 v21, v118, v118
	v_fmac_f32_e32 v21, v134, v134
	v_fmac_f32_e32 v21, v102, v102
	v_fmac_f32_e32 v21, v15, v15
	s_nop 1
	v_add_f32_dpp v21, v21, v21 quad_perm:[1,0,3,2] row_mask:0xf bank_mask:0xf
	v_mul_f32_e32 v16, v16, v43
	s_nop 1
	v_add_f32_dpp v21, v21, v21 quad_perm:[2,3,0,1] row_mask:0xf bank_mask:0xf
	s_nop 1
	v_add_f32_dpp v21, v21, v21 row_half_mirror row_mask:0xf bank_mask:0xf
	s_nop 1
	v_add_f32_dpp v21, v21, v21 row_mirror row_mask:0xf bank_mask:0xf
	v_mov_b32_e32 v22, v21
	v_mov_b32_e32 v23, v21
	s_nop 1
	v_permlane16_swap_b32_e32 v22, v23
	v_add_f32_e32 v21, v22, v23
	v_fmamk_f32 v21, v21, 0x3c000000, v100
	v_cmp_gt_f32_e32 vcc, s34, v21
	v_mul_f32_e32 v22, 0x4f800000, v21
	s_nop 0
	v_cndmask_b32_e32 v21, v21, v22, vcc
	v_sqrt_f32_e32 v22, v21
	s_nop 0
	v_add_u32_e32 v23, -1, v22
	v_fma_f32 v24, -v23, v22, v21
	v_cmp_ge_f32_e64 s[4:5], 0, v24
	v_add_u32_e32 v24, 1, v22
	s_nop 0
	v_cndmask_b32_e64 v23, v22, v23, s[4:5]
	v_fma_f32 v22, -v24, v22, v21
	v_cmp_lt_f32_e64 s[4:5], 0, v22
	s_nop 1
	v_cndmask_b32_e64 v22, v23, v24, s[4:5]
	v_mul_f32_e32 v23, 0x37800000, v22
	v_cndmask_b32_e32 v22, v22, v23, vcc
	v_cmp_class_f32_e32 vcc, v21, v101
	s_nop 1
	v_cndmask_b32_e32 v21, v22, v21, vcc
	s_nop 0
	v_div_scale_f32 v24, vcc, 1.0, v21, 1.0
	v_rcp_f32_e32 v42, v21
	v_mul_f32_e32 v21, v117, v117
	v_fmac_f32_e32 v21, v133, v133
	v_fmac_f32_e32 v21, v39, v39
	v_fmac_f32_e32 v21, v14, v14
	s_nop 1
	v_add_f32_dpp v21, v21, v21 quad_perm:[1,0,3,2] row_mask:0xf bank_mask:0xf
	v_mul_f32_e32 v15, v15, v42
	s_nop 1
	v_add_f32_dpp v21, v21, v21 quad_perm:[2,3,0,1] row_mask:0xf bank_mask:0xf
	s_nop 1
	v_add_f32_dpp v21, v21, v21 row_half_mirror row_mask:0xf bank_mask:0xf
	s_nop 1
	v_add_f32_dpp v21, v21, v21 row_mirror row_mask:0xf bank_mask:0xf
	v_mov_b32_e32 v22, v21
	v_mov_b32_e32 v23, v21
	s_nop 1
	v_permlane16_swap_b32_e32 v22, v23
	v_add_f32_e32 v21, v22, v23
	v_fmamk_f32 v21, v21, 0x3c000000, v100
	v_cmp_gt_f32_e32 vcc, s34, v21
	v_mul_f32_e32 v22, 0x4f800000, v21
	s_nop 0
	v_cndmask_b32_e32 v21, v21, v22, vcc
	v_sqrt_f32_e32 v22, v21
	s_nop 0
	v_add_u32_e32 v23, -1, v22
	v_fma_f32 v24, -v23, v22, v21
	v_cmp_ge_f32_e64 s[4:5], 0, v24
	v_add_u32_e32 v24, 1, v22
	s_nop 0
	v_cndmask_b32_e64 v23, v22, v23, s[4:5]
	v_fma_f32 v22, -v24, v22, v21
	v_cmp_lt_f32_e64 s[4:5], 0, v22
	s_nop 1
	v_cndmask_b32_e64 v22, v23, v24, s[4:5]
	v_mul_f32_e32 v23, 0x37800000, v22
	v_cndmask_b32_e32 v22, v22, v23, vcc
	v_cmp_class_f32_e32 vcc, v21, v101
	s_nop 1
	v_cndmask_b32_e32 v21, v22, v21, vcc
	s_nop 0
	v_div_scale_f32 v24, vcc, 1.0, v21, 1.0
	v_rcp_f32_e32 v41, v21
	v_mul_f32_e32 v21, v116, v116
	v_fmac_f32_e32 v21, v132, v132
	v_fmac_f32_e32 v21, v38, v38
	v_fmac_f32_e32 v21, v13, v13
	s_nop 1
	v_add_f32_dpp v21, v21, v21 quad_perm:[1,0,3,2] row_mask:0xf bank_mask:0xf
	v_mul_f32_e32 v39, v39, v41
	v_mul_f32_e32 v14, v14, v41
	s_nop 1
	v_add_f32_dpp v21, v21, v21 quad_perm:[2,3,0,1] row_mask:0xf bank_mask:0xf
	s_nop 1
	v_add_f32_dpp v21, v21, v21 row_half_mirror row_mask:0xf bank_mask:0xf
	s_nop 1
	v_add_f32_dpp v21, v21, v21 row_mirror row_mask:0xf bank_mask:0xf
	v_mov_b32_e32 v22, v21
	v_mov_b32_e32 v23, v21
	s_nop 1
	v_permlane16_swap_b32_e32 v22, v23
	v_add_f32_e32 v21, v22, v23
	v_fmamk_f32 v21, v21, 0x3c000000, v100
	v_cmp_gt_f32_e32 vcc, s34, v21
	v_mul_f32_e32 v22, 0x4f800000, v21
	s_nop 0
	v_cndmask_b32_e32 v21, v21, v22, vcc
	v_sqrt_f32_e32 v22, v21
	s_nop 0
	v_add_u32_e32 v23, -1, v22
	v_fma_f32 v24, -v23, v22, v21
	v_cmp_ge_f32_e64 s[4:5], 0, v24
	v_add_u32_e32 v24, 1, v22
	s_nop 0
	v_cndmask_b32_e64 v23, v22, v23, s[4:5]
	v_fma_f32 v22, -v24, v22, v21
	v_cmp_lt_f32_e64 s[4:5], 0, v22
	s_nop 1
	v_cndmask_b32_e64 v22, v23, v24, s[4:5]
	v_mul_f32_e32 v23, 0x37800000, v22
	v_cndmask_b32_e32 v22, v22, v23, vcc
	v_cmp_class_f32_e32 vcc, v21, v101
	s_nop 1
	v_cndmask_b32_e32 v21, v22, v21, vcc
	s_nop 0
	v_div_scale_f32 v24, vcc, 1.0, v21, 1.0
	v_rcp_f32_e32 v40, v21
	v_mul_f32_e32 v21, v115, v115
	v_fmac_f32_e32 v21, v131, v131
	v_fmac_f32_e32 v21, v37, v37
	v_fmac_f32_e32 v21, v12, v12
	s_nop 1
	v_add_f32_dpp v21, v21, v21 quad_perm:[1,0,3,2] row_mask:0xf bank_mask:0xf
	v_mul_f32_e32 v38, v38, v40
	v_mul_f32_e32 v13, v13, v40
	s_nop 1
	v_add_f32_dpp v21, v21, v21 quad_perm:[2,3,0,1] row_mask:0xf bank_mask:0xf
	s_nop 1
	v_add_f32_dpp v21, v21, v21 row_half_mirror row_mask:0xf bank_mask:0xf
	s_nop 1
	v_add_f32_dpp v21, v21, v21 row_mirror row_mask:0xf bank_mask:0xf
	v_mov_b32_e32 v22, v21
	v_mov_b32_e32 v23, v21
	s_nop 1
	v_permlane16_swap_b32_e32 v22, v23
	v_add_f32_e32 v21, v22, v23
	v_fmamk_f32 v21, v21, 0x3c000000, v100
	v_cmp_gt_f32_e32 vcc, s34, v21
	v_mul_f32_e32 v22, 0x4f800000, v21
	s_nop 0
	v_cndmask_b32_e32 v21, v21, v22, vcc
	v_sqrt_f32_e32 v22, v21
	s_nop 0
	v_add_u32_e32 v23, -1, v22
	v_fma_f32 v24, -v23, v22, v21
	v_cmp_ge_f32_e64 s[4:5], 0, v24
	v_add_u32_e32 v24, 1, v22
	s_nop 0
	v_cndmask_b32_e64 v23, v22, v23, s[4:5]
	v_fma_f32 v22, -v24, v22, v21
	v_cmp_lt_f32_e64 s[4:5], 0, v22
	s_nop 1
	v_cndmask_b32_e64 v22, v23, v24, s[4:5]
	v_mul_f32_e32 v23, 0x37800000, v22
	v_cndmask_b32_e32 v22, v22, v23, vcc
	v_cmp_class_f32_e32 vcc, v21, v101
	s_nop 1
	v_cndmask_b32_e32 v21, v22, v21, vcc
	s_nop 0
	v_div_scale_f32 v24, vcc, 1.0, v21, 1.0
	v_rcp_f32_e32 v35, v21
	v_mul_f32_e32 v21, v114, v114
	v_fmac_f32_e32 v21, v130, v130
	v_fmac_f32_e32 v21, v36, v36
	v_fmac_f32_e32 v21, v11, v11
	s_nop 1
	v_add_f32_dpp v21, v21, v21 quad_perm:[1,0,3,2] row_mask:0xf bank_mask:0xf
	v_mul_f32_e32 v37, v37, v35
	v_mul_f32_e32 v12, v12, v35
; DI void gla_stage3(const Ctx& c0, int layer, int unit, int cb, LAS unsigned char* lds) {
;     ...
;     float rs[16];
; #pragma unroll
;     for (int rg = 0; rg < 16; ++rg) { float ss = o[0][rg] * o[0][rg] + o[1][rg] * o[1][rg] + o[2][rg] * o[2][rg] + o[3][rg] * o[3][rg];
;         ss += __shfl_xor(ss, 1); ss += __shfl_xor(ss, 2); ss += __shfl_xor(ss, 4); ss += __shfl_xor(ss, 8); ss += __shfl_xor(ss, 16);
;         rs[rg] = 1.f / sqrtf(ss * (1.f / 128.f) + EPS); }
	s_nop 1
	v_add_f32_dpp v21, v21, v21 quad_perm:[2,3,0,1] row_mask:0xf bank_mask:0xf
	s_nop 1
	v_add_f32_dpp v21, v21, v21 row_half_mirror row_mask:0xf bank_mask:0xf
	s_nop 1
	v_add_f32_dpp v21, v21, v21 row_mirror row_mask:0xf bank_mask:0xf
	v_mov_b32_e32 v22, v21
	v_mov_b32_e32 v23, v21
	s_nop 1
	v_permlane16_swap_b32_e32 v22, v23
	v_add_f32_e32 v21, v22, v23
	v_fmamk_f32 v21, v21, 0x3c000000, v100
	v_cmp_gt_f32_e32 vcc, s34, v21
	v_mul_f32_e32 v22, 0x4f800000, v21
	s_nop 0
	v_cndmask_b32_e32 v21, v21, v22, vcc
	v_sqrt_f32_e32 v22, v21
	s_nop 0
	v_add_u32_e32 v23, -1, v22
	v_fma_f32 v24, -v23, v22, v21
	v_cmp_ge_f32_e64 s[4:5], 0, v24
	v_add_u32_e32 v24, 1, v22
	s_nop 0
	v_cndmask_b32_e64 v23, v22, v23, s[4:5]
	v_fma_f32 v22, -v24, v22, v21
	v_cmp_lt_f32_e64 s[4:5], 0, v22
	s_nop 1
	v_cndmask_b32_e64 v22, v23, v24, s[4:5]
	v_mul_f32_e32 v23, 0x37800000, v22
	v_cndmask_b32_e32 v22, v22, v23, vcc
	v_cmp_class_f32_e32 vcc, v21, v101
	s_nop 1
	v_cndmask_b32_e32 v21, v22, v21, vcc
	s_nop 0
	v_div_scale_f32 v24, vcc, 1.0, v21, 1.0
	v_rcp_f32_e32 v31, v21
	v_mul_f32_e32 v21, v113, v113
	v_fmac_f32_e32 v21, v129, v129
	v_fmac_f32_e32 v21, v34, v34
	v_fmac_f32_e32 v21, v10, v10
	s_nop 1
	v_add_f32_dpp v21, v21, v21 quad_perm:[1,0,3,2] row_mask:0xf bank_mask:0xf
	v_mul_f32_e32 v36, v36, v31
	v_mul_f32_e32 v11, v11, v31
	s_nop 1
	v_add_f32_dpp v21, v21, v21 quad_perm:[2,3,0,1] row_mask:0xf bank_mask:0xf
	s_nop 1
	v_add_f32_dpp v21, v21, v21 row_half_mirror row_mask:0xf bank_mask:0xf
	s_nop 1
	v_add_f32_dpp v21, v21, v21 row_mirror row_mask:0xf bank_mask:0xf
	v_mov_b32_e32 v22, v21
	v_mov_b32_e32 v23, v21
	s_nop 1
	v_permlane16_swap_b32_e32 v22, v23
	v_add_f32_e32 v21, v22, v23
	v_fmamk_f32 v21, v21, 0x3c000000, v100
	v_cmp_gt_f32_e32 vcc, s34, v21
	v_mul_f32_e32 v22, 0x4f800000, v21
	s_nop 0
	v_cndmask_b32_e32 v21, v21, v22, vcc
	v_sqrt_f32_e32 v22, v21
	s_nop 0
	v_add_u32_e32 v23, -1, v22
	v_fma_f32 v24, -v23, v22, v21
	v_cmp_ge_f32_e64 s[4:5], 0, v24
	v_add_u32_e32 v24, 1, v22
	s_nop 0
	v_cndmask_b32_e64 v23, v22, v23, s[4:5]
	v_fma_f32 v22, -v24, v22, v21
	v_cmp_lt_f32_e64 s[4:5], 0, v22
	s_nop 1
	v_cndmask_b32_e64 v22, v23, v24, s[4:5]
	v_mul_f32_e32 v23, 0x37800000, v22
	v_cndmask_b32_e32 v22, v22, v23, vcc
	v_cmp_class_f32_e32 vcc, v21, v101
	s_nop 1
	v_cndmask_b32_e32 v21, v22, v21, vcc
	s_nop 0
	v_div_scale_f32 v24, vcc, 1.0, v21, 1.0
	v_rcp_f32_e32 v27, v21
	v_mul_f32_e32 v21, v112, v112
	v_fmac_f32_e32 v21, v128, v128
	v_fmac_f32_e32 v21, v33, v33
	v_fmac_f32_e32 v21, v9, v9
	s_nop 1
	v_add_f32_dpp v21, v21, v21 quad_perm:[1,0,3,2] row_mask:0xf bank_mask:0xf
	v_mul_f32_e32 v34, v34, v27
	v_mul_f32_e32 v10, v10, v27
	s_nop 1
	v_add_f32_dpp v21, v21, v21 quad_perm:[2,3,0,1] row_mask:0xf bank_mask:0xf
	s_nop 1
	v_add_f32_dpp v21, v21, v21 row_half_mirror row_mask:0xf bank_mask:0xf
	s_nop 1
	v_add_f32_dpp v21, v21, v21 row_mirror row_mask:0xf bank_mask:0xf
	v_mov_b32_e32 v22, v21
	v_mov_b32_e32 v23, v21
	s_nop 1
	v_permlane16_swap_b32_e32 v22, v23
	v_add_f32_e32 v21, v22, v23
	v_fmamk_f32 v21, v21, 0x3c000000, v100
	v_cmp_gt_f32_e32 vcc, s34, v21
	v_mul_f32_e32 v22, 0x4f800000, v21
	s_nop 0
	v_cndmask_b32_e32 v21, v21, v22, vcc
	v_sqrt_f32_e32 v22, v21
	s_nop 0
	v_add_u32_e32 v23, -1, v22
	v_fma_f32 v24, -v23, v22, v21
	v_cmp_ge_f32_e64 s[4:5], 0, v24
	v_add_u32_e32 v24, 1, v22
	s_nop 0
	v_cndmask_b32_e64 v23, v22, v23, s[4:5]
	v_fma_f32 v22, -v24, v22, v21
	v_cmp_lt_f32_e64 s[4:5], 0, v22
	s_nop 1
	v_cndmask_b32_e64 v22, v23, v24, s[4:5]
	v_mul_f32_e32 v23, 0x37800000, v22
	v_cndmask_b32_e32 v22, v22, v23, vcc
	v_cmp_class_f32_e32 vcc, v21, v101
	s_nop 1
	v_cndmask_b32_e32 v21, v22, v21, vcc
	s_nop 0
	v_div_scale_f32 v24, vcc, 1.0, v21, 1.0
	v_rcp_f32_e32 v25, v21
	v_mul_f32_e32 v21, v111, v111
	v_fmac_f32_e32 v21, v127, v127
	v_fmac_f32_e32 v21, v32, v32
	v_fmac_f32_e32 v21, v8, v8
	s_nop 1
	v_add_f32_dpp v21, v21, v21 quad_perm:[1,0,3,2] row_mask:0xf bank_mask:0xf
	v_mul_f32_e32 v33, v33, v25
	v_mul_f32_e32 v9, v9, v25
	s_nop 1
	v_add_f32_dpp v21, v21, v21 quad_perm:[2,3,0,1] row_mask:0xf bank_mask:0xf
	s_nop 1
	v_add_f32_dpp v21, v21, v21 row_half_mirror row_mask:0xf bank_mask:0xf
	s_nop 1
	v_add_f32_dpp v21, v21, v21 row_mirror row_mask:0xf bank_mask:0xf
	v_mov_b32_e32 v22, v21
	v_mov_b32_e32 v23, v21
	s_nop 1
	v_permlane16_swap_b32_e32 v22, v23
	v_add_f32_e32 v21, v22, v23
	v_fmamk_f32 v21, v21, 0x3c000000, v100
	v_cmp_gt_f32_e32 vcc, s34, v21
	v_mul_f32_e32 v22, 0x4f800000, v21
	s_nop 0
	v_cndmask_b32_e32 v21, v21, v22, vcc
	v_sqrt_f32_e32 v22, v21
	s_nop 0
	v_add_u32_e32 v23, -1, v22
	v_fma_f32 v24, -v23, v22, v21
	v_cmp_ge_f32_e64 s[4:5], 0, v24
	v_add_u32_e32 v24, 1, v22
	s_nop 0
	v_cndmask_b32_e64 v23, v22, v23, s[4:5]
	v_fma_f32 v22, -v24, v22, v21
	v_cmp_lt_f32_e64 s[4:5], 0, v22
	s_nop 1
	v_cndmask_b32_e64 v22, v23, v24, s[4:5]
	v_mul_f32_e32 v23, 0x37800000, v22
	v_cndmask_b32_e32 v22, v22, v23, vcc
	v_cmp_class_f32_e32 vcc, v21, v101
	s_nop 1
	v_cndmask_b32_e32 v21, v22, v21, vcc
	s_nop 0
	v_div_scale_f32 v24, vcc, 1.0, v21, 1.0
	v_rcp_f32_e32 v24, v21
	v_mul_f32_e32 v21, v110, v110
	v_fmac_f32_e32 v21, v126, v126
	v_fmac_f32_e32 v21, v30, v30
	v_fmac_f32_e32 v21, v7, v7
	s_nop 1
	v_add_f32_dpp v21, v21, v21 quad_perm:[1,0,3,2] row_mask:0xf bank_mask:0xf
	v_mul_f32_e32 v32, v32, v24
	v_mul_f32_e32 v8, v8, v24
	s_nop 1
	v_add_f32_dpp v21, v21, v21 quad_perm:[2,3,0,1] row_mask:0xf bank_mask:0xf
	s_nop 1
	v_add_f32_dpp v21, v21, v21 row_half_mirror row_mask:0xf bank_mask:0xf
	s_nop 1
	v_add_f32_dpp v21, v21, v21 row_mirror row_mask:0xf bank_mask:0xf
	v_mov_b32_e32 v22, v21
	v_mov_b32_e32 v23, v21
	s_nop 1
	v_permlane16_swap_b32_e32 v22, v23
; #define LAS __attribute__((address_space(3)))
; #define LDS_WAIT() asm volatile("s_waitcnt lgkmcnt(0)" ::: "memory")
; DI unsigned cvtpk(float lo, float hi) { f32x2 v = {lo, hi}; bf16x2_t b = __builtin_convertvector(v, bf16x2_t); return __builtin_bit_cast(unsigned, b); }
; DI float bf2f(bf16 b) { return __uint_as_float(((unsigned)b) << 16); }
; DI float siluf_(float x) { return x / (1.f + __expf(-x)); }
; DI void gla_stage3(const Ctx& c0, int layer, int unit, int cb, LAS unsigned char* lds) {
;     ...
;     float rs[16];
; #pragma unroll
;     for (int rg = 0; rg < 16; ++rg) { float ss = o[0][rg] * o[0][rg] + o[1][rg] * o[1][rg] + o[2][rg] * o[2][rg] + o[3][rg] * o[3][rg];
;         ss += __shfl_xor(ss, 1); ss += __shfl_xor(ss, 2); ss += __shfl_xor(ss, 4); ss += __shfl_xor(ss, 8); ss += __shfl_xor(ss, 16);
;         rs[rg] = 1.f / sqrtf(ss * (1.f / 128.f) + EPS); }
;     LDS_WAIT();
;     g3_tile_in((const bf16*)(c.ws + O_GR) + row0 * 512 + h * 128, R, lane);
; #pragma unroll
;     for (int vb = 0; vb < 4; ++vb) { const float g = gn[32 * vb + r];
; #pragma unroll
;         for (int rg = 0; rg < 16; ++rg) { LAS bf16* e = (LAS bf16*)(R + (4 * hi) * G3_PITCH + r * 2 + ((rg & 3) + 8 * (rg >> 2)) * G3_PITCH + 64 * vb);
;             const float z = bf2f(*e);
;             *e = (bf16)(cvtpk(o[vb][rg] * rs[rg] * g * siluf_(z), 0.f) & 0xffffu); }
	v_add_f32_e32 v21, v22, v23
	v_fmamk_f32 v21, v21, 0x3c000000, v100
	v_cmp_gt_f32_e32 vcc, s34, v21
	v_mul_f32_e32 v22, 0x4f800000, v21
	s_nop 0
	v_cndmask_b32_e32 v21, v21, v22, vcc
	v_sqrt_f32_e32 v22, v21
	s_nop 0
	v_add_u32_e32 v23, -1, v22
	v_fma_f32 v49, -v23, v22, v21
	v_cmp_ge_f32_e64 s[4:5], 0, v49
	v_add_u32_e32 v49, 1, v22
	s_nop 0
	v_cndmask_b32_e64 v23, v22, v23, s[4:5]
	v_fma_f32 v22, -v49, v22, v21
	v_cmp_lt_f32_e64 s[4:5], 0, v22
	s_nop 1
	v_cndmask_b32_e64 v22, v23, v49, s[4:5]
	v_mul_f32_e32 v23, 0x37800000, v22
	v_cndmask_b32_e32 v22, v22, v23, vcc
	v_cmp_class_f32_e32 vcc, v21, v101
	s_nop 1
	v_cndmask_b32_e32 v21, v22, v21, vcc
	s_nop 0
	v_div_scale_f32 v49, vcc, 1.0, v21, 1.0
	v_rcp_f32_e32 v23, v21
	v_mul_f32_e32 v21, v109, v109
	v_fmac_f32_e32 v21, v125, v125
	v_fmac_f32_e32 v21, v29, v29
	v_fmac_f32_e32 v21, v6, v6
	s_nop 1
	v_add_f32_dpp v21, v21, v21 quad_perm:[1,0,3,2] row_mask:0xf bank_mask:0xf
	v_mul_f32_e32 v30, v30, v23
	v_mul_f32_e32 v7, v7, v23
	s_nop 1
	v_add_f32_dpp v21, v21, v21 quad_perm:[2,3,0,1] row_mask:0xf bank_mask:0xf
	s_nop 1
	v_add_f32_dpp v21, v21, v21 row_half_mirror row_mask:0xf bank_mask:0xf
	s_nop 1
	v_add_f32_dpp v21, v21, v21 row_mirror row_mask:0xf bank_mask:0xf
	v_mov_b32_e32 v22, v21
	v_mov_b32_e32 v49, v21
	s_nop 1
	v_permlane16_swap_b32_e32 v22, v49
	v_add_f32_e32 v21, v22, v49
	v_fmamk_f32 v21, v21, 0x3c000000, v100
	v_cmp_gt_f32_e32 vcc, s34, v21
	v_mul_f32_e32 v22, 0x4f800000, v21
	s_nop 0
	v_cndmask_b32_e32 v21, v21, v22, vcc
	v_sqrt_f32_e32 v22, v21
	s_nop 0
	v_add_u32_e32 v49, -1, v22
	v_fma_f32 v50, -v49, v22, v21
	v_cmp_ge_f32_e64 s[4:5], 0, v50
	v_add_u32_e32 v50, 1, v22
	s_nop 0
	v_cndmask_b32_e64 v49, v22, v49, s[4:5]
	v_fma_f32 v22, -v50, v22, v21
	v_cmp_lt_f32_e64 s[4:5], 0, v22
	s_nop 1
	v_cndmask_b32_e64 v22, v49, v50, s[4:5]
	v_mul_f32_e32 v49, 0x37800000, v22
	v_cndmask_b32_e32 v22, v22, v49, vcc
	v_cmp_class_f32_e32 vcc, v21, v101
	s_nop 1
	v_cndmask_b32_e32 v21, v22, v21, vcc
	s_nop 0
	v_div_scale_f32 v50, vcc, 1.0, v21, 1.0
	v_rcp_f32_e32 v22, v21
	v_mul_f32_e32 v21, v108, v108
	v_fmac_f32_e32 v21, v124, v124
	v_fmac_f32_e32 v21, v28, v28
	v_fmac_f32_e32 v21, v5, v5
	s_nop 1
	v_add_f32_dpp v21, v21, v21 quad_perm:[1,0,3,2] row_mask:0xf bank_mask:0xf
	v_mul_f32_e32 v29, v29, v22
	v_mul_f32_e32 v6, v6, v22
	s_nop 1
	v_add_f32_dpp v21, v21, v21 quad_perm:[2,3,0,1] row_mask:0xf bank_mask:0xf
	s_nop 1
	v_add_f32_dpp v21, v21, v21 row_half_mirror row_mask:0xf bank_mask:0xf
	s_nop 1
	v_add_f32_dpp v21, v21, v21 row_mirror row_mask:0xf bank_mask:0xf
	v_mov_b32_e32 v49, v21
	v_mov_b32_e32 v50, v21
	s_nop 1
	v_permlane16_swap_b32_e32 v49, v50
	v_add_f32_e32 v21, v49, v50
	v_fmamk_f32 v21, v21, 0x3c000000, v100
	v_cmp_gt_f32_e32 vcc, s34, v21
	v_mul_f32_e32 v49, 0x4f800000, v21
	s_nop 0
	v_cndmask_b32_e32 v21, v21, v49, vcc
	v_sqrt_f32_e32 v49, v21
	s_nop 0
	v_add_u32_e32 v50, -1, v49
	v_fma_f32 v51, -v50, v49, v21
	v_cmp_ge_f32_e64 s[4:5], 0, v51
	v_add_u32_e32 v51, 1, v49
	s_nop 0
	v_cndmask_b32_e64 v50, v49, v50, s[4:5]
	v_fma_f32 v49, -v51, v49, v21
	v_cmp_lt_f32_e64 s[4:5], 0, v49
	s_nop 1
	v_cndmask_b32_e64 v49, v50, v51, s[4:5]
	v_mul_f32_e32 v50, 0x37800000, v49
	v_cndmask_b32_e32 v49, v49, v50, vcc
	v_cmp_class_f32_e32 vcc, v21, v101
	s_nop 1
	v_cndmask_b32_e32 v21, v49, v21, vcc
	s_nop 0
	v_div_scale_f32 v51, vcc, 1.0, v21, 1.0
	v_rcp_f32_e32 v21, v21
	v_mul_f32_e32 v49, v107, v107
	v_fmac_f32_e32 v49, v123, v123
	v_fmac_f32_e32 v49, v26, v26
	v_fmac_f32_e32 v49, v4, v4
	ds_bpermute_b32 v2, v2, v49
	v_mul_f32_e32 v28, v28, v21
	v_mul_f32_e32 v5, v5, v21
	s_waitcnt lgkmcnt(0)
	v_add_f32_e32 v2, v49, v2
	ds_bpermute_b32 v3, v3, v2
	s_waitcnt lgkmcnt(0)
	v_add_f32_e32 v2, v2, v3
	ds_bpermute_b32 v3, v20, v2
	s_waitcnt lgkmcnt(0)
	v_add_f32_e32 v2, v2, v3
	ds_bpermute_b32 v3, v47, v2
	s_waitcnt lgkmcnt(0)
	v_add_f32_e32 v2, v2, v3
	ds_bpermute_b32 v3, v48, v2
	s_waitcnt lgkmcnt(0)
	v_add_f32_e32 v2, v2, v3
	v_fmamk_f32 v2, v2, 0x3c000000, v100
	v_cmp_gt_f32_e32 vcc, s34, v2
	v_mul_f32_e32 v3, 0x4f800000, v2
	s_nop 0
	v_cndmask_b32_e32 v2, v2, v3, vcc
	v_sqrt_f32_e32 v3, v2
	s_nop 0
	v_add_u32_e32 v20, -1, v3
	v_fma_f32 v47, -v20, v3, v2
	v_cmp_ge_f32_e64 s[4:5], 0, v47
	v_add_u32_e32 v47, 1, v3
	s_nop 0
	v_cndmask_b32_e64 v20, v3, v20, s[4:5]
	v_fma_f32 v3, -v47, v3, v2
	v_cmp_lt_f32_e64 s[4:5], 0, v3
	s_nop 1
	v_cndmask_b32_e64 v3, v20, v47, s[4:5]
	v_mul_f32_e32 v20, 0x37800000, v3
	v_cndmask_b32_e32 v3, v3, v20, vcc
	v_cmp_class_f32_e32 vcc, v2, v101
	s_nop 1
	v_cndmask_b32_e32 v2, v3, v2, vcc
	s_nop 0
	v_rcp_f32_e32 v20, v2
	v_mul_f32_e32 v47, v138, v46
	v_mul_f32_e32 v26, v26, v20
	v_mul_f32_e32 v4, v4, v20
	s_waitcnt vmcnt(2) lgkmcnt(0)
	ds_write_b128 v92, v[164:167]
	s_waitcnt vmcnt(0) lgkmcnt(0)
	ds_write_b128 v92, v[170:173] offset:1088
	s_waitcnt vmcnt(13) lgkmcnt(0)
	ds_write_b128 v92, v[174:177] offset:2176
	s_waitcnt vmcnt(8) lgkmcnt(0)
	ds_write_b128 v92, v[178:181] offset:3264
	s_waitcnt vmcnt(9) lgkmcnt(0)
	ds_write_b128 v92, v[196:199] offset:4352
	s_waitcnt vmcnt(10) lgkmcnt(0)
	ds_write_b128 v92, v[200:203] offset:5440
	v_lshl_add_u64 v[2:3], v[168:169], 0, v[80:81]
	s_waitcnt vmcnt(5) lgkmcnt(0)
	ds_write_b128 v92, v[204:207] offset:6528
	global_load_dwordx4 v[48:51], v[2:3], off
	s_waitcnt vmcnt(0) lgkmcnt(0)
	ds_write_b128 v92, v[48:51] offset:7616
	s_waitcnt lgkmcnt(0)
	ds_read_u16 v3, v1
	s_waitcnt lgkmcnt(0)
	v_lshlrev_b32_e32 v3, 16, v3
	v_mul_f32_e32 v48, 0xbfb8aa3b, v3
	v_exp_f32_e32 v48, v48
	s_waitcnt vmcnt(0)
; #define LAS __attribute__((address_space(3)))
; DI unsigned cvtpk(float lo, float hi) { f32x2 v = {lo, hi}; bf16x2_t b = __builtin_convertvector(v, bf16x2_t); return __builtin_bit_cast(unsigned, b); }
; DI float bf2f(bf16 b) { return __uint_as_float(((unsigned)b) << 16); }
; DI float siluf_(float x) { return x / (1.f + __expf(-x)); }
; DI void gla_stage3(const Ctx& c0, int layer, int unit, int cb, LAS unsigned char* lds) {
;     ...
;     for (int vb = 0; vb < 4; ++vb) { const float g = gn[32 * vb + r];
; #pragma unroll
;         for (int rg = 0; rg < 16; ++rg) { LAS bf16* e = (LAS bf16*)(R + (4 * hi) * G3_PITCH + r * 2 + ((rg & 3) + 8 * (rg >> 2)) * G3_PITCH + 64 * vb);
;             const float z = bf2f(*e);
;             *e = (bf16)(cvtpk(o[vb][rg] * rs[rg] * g * siluf_(z), 0.f) & 0xffffu); }
;         asm volatile("" ::: "memory"); }
	v_mul_f32_e32 v47, v47, v232
	v_add_f32_e32 v48, 1.0, v48
	v_div_scale_f32 v49, s[0:1], v48, v48, v3
	s_nop 0
	v_rcp_f32_e32 v49, v48
	s_nop 0
	v_mul_f32_e32 v3, v3, v49
	v_mul_f32_e32 v3, v47, v3
	v_cvt_pk_bf16_f32 v3, v3, s0
	ds_write_b16 v1, v3
	ds_read_u16 v3, v1 offset:272
	v_mul_f32_e32 v47, v137, v45
	v_mul_f32_e32 v47, v47, v232
	s_waitcnt lgkmcnt(0)
	v_lshlrev_b32_e32 v3, 16, v3
	v_mul_f32_e32 v48, 0xbfb8aa3b, v3
	v_exp_f32_e32 v48, v48
	s_nop 0
	v_add_f32_e32 v48, 1.0, v48
	v_div_scale_f32 v49, s[0:1], v48, v48, v3
	s_nop 0
	v_rcp_f32_e32 v49, v48
	s_nop 0
	v_mul_f32_e32 v3, v3, v49
	v_mul_f32_e32 v3, v47, v3
	v_cvt_pk_bf16_f32 v3, v3, s0
	ds_write_b16 v1, v3 offset:272
	ds_read_u16 v3, v1 offset:544
	v_mul_f32_e32 v47, v136, v44
	v_mul_f32_e32 v47, v47, v232
	s_waitcnt lgkmcnt(0)
	v_lshlrev_b32_e32 v3, 16, v3
	v_mul_f32_e32 v48, 0xbfb8aa3b, v3
	v_exp_f32_e32 v48, v48
	s_nop 0
	v_add_f32_e32 v48, 1.0, v48
	v_div_scale_f32 v49, s[0:1], v48, v48, v3
	s_nop 0
	v_rcp_f32_e32 v49, v48
	s_nop 0
	v_mul_f32_e32 v3, v3, v49
	v_mul_f32_e32 v3, v47, v3
	v_cvt_pk_bf16_f32 v3, v3, s0
	ds_write_b16 v1, v3 offset:544
	ds_read_u16 v3, v1 offset:816
	v_mul_f32_e32 v47, v135, v43
	v_mul_f32_e32 v47, v47, v232
	s_waitcnt lgkmcnt(0)
	v_lshlrev_b32_e32 v3, 16, v3
	v_mul_f32_e32 v48, 0xbfb8aa3b, v3
	v_exp_f32_e32 v48, v48
	s_nop 0
	v_add_f32_e32 v48, 1.0, v48
	v_div_scale_f32 v49, s[0:1], v48, v48, v3
	s_nop 0
	v_rcp_f32_e32 v49, v48
	s_nop 0
	v_mul_f32_e32 v3, v3, v49
	v_mul_f32_e32 v3, v47, v3
	v_cvt_pk_bf16_f32 v3, v3, s0
	ds_write_b16 v1, v3 offset:816
	ds_read_u16 v3, v1 offset:2176
	v_mul_f32_e32 v47, v134, v42
	v_mul_f32_e32 v47, v47, v232
	s_waitcnt lgkmcnt(0)
	v_lshlrev_b32_e32 v3, 16, v3
	v_mul_f32_e32 v48, 0xbfb8aa3b, v3
	v_exp_f32_e32 v48, v48
	s_nop 0
	v_add_f32_e32 v48, 1.0, v48
	v_div_scale_f32 v49, s[0:1], v48, v48, v3
	s_nop 0
	v_rcp_f32_e32 v49, v48
	s_nop 0
	v_mul_f32_e32 v3, v3, v49
	v_mul_f32_e32 v3, v47, v3
	v_cvt_pk_bf16_f32 v3, v3, s0
	ds_write_b16 v1, v3 offset:2176
	ds_read_u16 v3, v1 offset:2448
	v_mul_f32_e32 v47, v133, v41
	v_mul_f32_e32 v47, v47, v232
	s_waitcnt lgkmcnt(0)
	v_lshlrev_b32_e32 v3, 16, v3
	v_mul_f32_e32 v48, 0xbfb8aa3b, v3
	v_exp_f32_e32 v48, v48
	s_nop 0
	v_add_f32_e32 v48, 1.0, v48
	v_div_scale_f32 v49, s[0:1], v48, v48, v3
	s_nop 0
	v_rcp_f32_e32 v49, v48
	s_nop 0
	v_mul_f32_e32 v3, v3, v49
	v_mul_f32_e32 v3, v47, v3
	v_cvt_pk_bf16_f32 v3, v3, s0
	ds_write_b16 v1, v3 offset:2448
	ds_read_u16 v3, v1 offset:2720
	v_mul_f32_e32 v47, v132, v40
	v_mul_f32_e32 v47, v47, v232
	s_waitcnt lgkmcnt(0)
	v_lshlrev_b32_e32 v3, 16, v3
	v_mul_f32_e32 v48, 0xbfb8aa3b, v3
	v_exp_f32_e32 v48, v48
	s_nop 0
	v_add_f32_e32 v48, 1.0, v48
	v_div_scale_f32 v49, s[0:1], v48, v48, v3
	s_nop 0
	v_rcp_f32_e32 v49, v48
	s_nop 0
	v_mul_f32_e32 v3, v3, v49
	v_mul_f32_e32 v3, v47, v3
	v_cvt_pk_bf16_f32 v3, v3, s0
	ds_write_b16 v1, v3 offset:2720
	ds_read_u16 v3, v1 offset:2992
	v_mul_f32_e32 v47, v131, v35
	v_mul_f32_e32 v47, v47, v232
	s_waitcnt lgkmcnt(0)
	v_lshlrev_b32_e32 v3, 16, v3
	v_mul_f32_e32 v48, 0xbfb8aa3b, v3
	v_exp_f32_e32 v48, v48
	s_nop 0
	v_add_f32_e32 v48, 1.0, v48
	v_div_scale_f32 v49, s[0:1], v48, v48, v3
	s_nop 0
	v_rcp_f32_e32 v49, v48
	s_nop 0
	v_mul_f32_e32 v3, v3, v49
	v_mul_f32_e32 v3, v47, v3
	v_cvt_pk_bf16_f32 v3, v3, s0
	ds_write_b16 v1, v3 offset:2992
	ds_read_u16 v3, v1 offset:4352
	v_mul_f32_e32 v47, v130, v31
	v_mul_f32_e32 v47, v47, v232
	s_waitcnt lgkmcnt(0)
	v_lshlrev_b32_e32 v3, 16, v3
	v_mul_f32_e32 v48, 0xbfb8aa3b, v3
	v_exp_f32_e32 v48, v48
	s_nop 0
	v_add_f32_e32 v48, 1.0, v48
	v_div_scale_f32 v49, s[0:1], v48, v48, v3
	s_nop 0
	v_rcp_f32_e32 v49, v48
	s_nop 0
	v_mul_f32_e32 v3, v3, v49
	v_mul_f32_e32 v3, v47, v3
	v_cvt_pk_bf16_f32 v3, v3, s0
	ds_write_b16 v1, v3 offset:4352
	ds_read_u16 v3, v1 offset:4624
	v_mul_f32_e32 v47, v129, v27
	v_mul_f32_e32 v47, v47, v232
	s_waitcnt lgkmcnt(0)
	v_lshlrev_b32_e32 v3, 16, v3
	v_mul_f32_e32 v48, 0xbfb8aa3b, v3
	v_exp_f32_e32 v48, v48
	s_nop 0
	v_add_f32_e32 v48, 1.0, v48
	v_div_scale_f32 v49, s[0:1], v48, v48, v3
	s_nop 0
	v_rcp_f32_e32 v49, v48
	s_nop 0
	v_mul_f32_e32 v3, v3, v49
	v_mul_f32_e32 v3, v47, v3
	v_cvt_pk_bf16_f32 v3, v3, s0
	ds_write_b16 v1, v3 offset:4624
	ds_read_u16 v3, v1 offset:4896
	v_mul_f32_e32 v47, v128, v25
	v_mul_f32_e32 v47, v47, v232
	s_waitcnt lgkmcnt(0)
	v_lshlrev_b32_e32 v3, 16, v3
	v_mul_f32_e32 v48, 0xbfb8aa3b, v3
	v_exp_f32_e32 v48, v48
	s_nop 0
	v_add_f32_e32 v48, 1.0, v48
	v_div_scale_f32 v49, s[0:1], v48, v48, v3
	s_nop 0
	v_rcp_f32_e32 v49, v48
	s_nop 0
	v_mul_f32_e32 v3, v3, v49
	v_mul_f32_e32 v3, v47, v3
	v_cvt_pk_bf16_f32 v3, v3, s0
	ds_write_b16 v1, v3 offset:4896
	ds_read_u16 v3, v1 offset:5168
	v_mul_f32_e32 v47, v127, v24
	v_mul_f32_e32 v47, v47, v232
	s_waitcnt lgkmcnt(0)
	v_lshlrev_b32_e32 v3, 16, v3
	v_mul_f32_e32 v48, 0xbfb8aa3b, v3
	v_exp_f32_e32 v48, v48
	s_nop 0
	v_add_f32_e32 v48, 1.0, v48
	v_div_scale_f32 v49, s[0:1], v48, v48, v3
	s_nop 0
	v_rcp_f32_e32 v49, v48
	s_nop 0
	v_mul_f32_e32 v3, v3, v49
	v_mul_f32_e32 v3, v47, v3
	v_cvt_pk_bf16_f32 v3, v3, s0
	ds_write_b16 v1, v3 offset:5168
	ds_read_u16 v3, v1 offset:6528
	v_mul_f32_e32 v47, v126, v23
	v_mul_f32_e32 v47, v47, v232
	s_waitcnt lgkmcnt(0)
	v_lshlrev_b32_e32 v3, 16, v3
	v_mul_f32_e32 v48, 0xbfb8aa3b, v3
	v_exp_f32_e32 v48, v48
	s_nop 0
	v_add_f32_e32 v48, 1.0, v48
	v_div_scale_f32 v49, s[0:1], v48, v48, v3
	s_nop 0
	v_rcp_f32_e32 v49, v48
	s_nop 0
	v_mul_f32_e32 v3, v3, v49
	v_mul_f32_e32 v3, v47, v3
	v_cvt_pk_bf16_f32 v3, v3, s0
	ds_write_b16 v1, v3 offset:6528
	ds_read_u16 v3, v1 offset:6800
	v_mul_f32_e32 v47, v125, v22
	v_mul_f32_e32 v47, v47, v232
	s_waitcnt lgkmcnt(0)
; #define LAS __attribute__((address_space(3)))
; DI unsigned cvtpk(float lo, float hi) { f32x2 v = {lo, hi}; bf16x2_t b = __builtin_convertvector(v, bf16x2_t); return __builtin_bit_cast(unsigned, b); }
; DI float bf2f(bf16 b) { return __uint_as_float(((unsigned)b) << 16); }
; DI float siluf_(float x) { return x / (1.f + __expf(-x)); }
; DI void gla_stage3(const Ctx& c0, int layer, int unit, int cb, LAS unsigned char* lds) {
;     ...
;     for (int vb = 0; vb < 4; ++vb) { const float g = gn[32 * vb + r];
; #pragma unroll
;         for (int rg = 0; rg < 16; ++rg) { LAS bf16* e = (LAS bf16*)(R + (4 * hi) * G3_PITCH + r * 2 + ((rg & 3) + 8 * (rg >> 2)) * G3_PITCH + 64 * vb);
;             const float z = bf2f(*e);
;             *e = (bf16)(cvtpk(o[vb][rg] * rs[rg] * g * siluf_(z), 0.f) & 0xffffu); }
;         asm volatile("" ::: "memory"); }
	v_lshlrev_b32_e32 v3, 16, v3
	v_mul_f32_e32 v48, 0xbfb8aa3b, v3
	v_exp_f32_e32 v48, v48
	s_nop 0
	v_add_f32_e32 v48, 1.0, v48
	v_div_scale_f32 v49, s[0:1], v48, v48, v3
	s_nop 0
	v_rcp_f32_e32 v49, v48
	s_nop 0
	v_mul_f32_e32 v3, v3, v49
	v_mul_f32_e32 v3, v47, v3
	v_cvt_pk_bf16_f32 v3, v3, s0
	ds_write_b16 v1, v3 offset:6800
	ds_read_u16 v3, v1 offset:7072
	v_mul_f32_e32 v47, v124, v21
	v_mul_f32_e32 v47, v47, v232
	s_waitcnt lgkmcnt(0)
	v_lshlrev_b32_e32 v3, 16, v3
	v_mul_f32_e32 v48, 0xbfb8aa3b, v3
	v_exp_f32_e32 v48, v48
	s_nop 0
	v_add_f32_e32 v48, 1.0, v48
	v_div_scale_f32 v49, s[0:1], v48, v48, v3
	s_nop 0
	v_rcp_f32_e32 v49, v48
	s_nop 0
	v_mul_f32_e32 v3, v3, v49
	v_mul_f32_e32 v3, v47, v3
	v_cvt_pk_bf16_f32 v3, v3, s0
	ds_write_b16 v1, v3 offset:7072
	ds_read_u16 v3, v1 offset:7344
	v_mul_f32_e32 v47, v123, v20
	v_mul_f32_e32 v2, v47, v232
	s_waitcnt lgkmcnt(0)
	v_lshlrev_b32_e32 v3, 16, v3
	v_mul_f32_e32 v47, 0xbfb8aa3b, v3
	v_exp_f32_e32 v47, v47
	s_nop 0
	v_add_f32_e32 v47, 1.0, v47
	v_div_scale_f32 v48, s[0:1], v47, v47, v3
	s_nop 0
	v_rcp_f32_e32 v48, v47
	s_nop 0
	v_mul_f32_e32 v3, v3, v48
	v_mul_f32_e32 v2, v2, v3
	v_cvt_pk_bf16_f32 v2, v2, s0
	ds_write_b16 v1, v2 offset:7344
	ds_read_u16 v3, v1 offset:64
	v_mul_f32_e32 v47, v122, v46
	s_waitcnt lgkmcnt(0)
	v_lshlrev_b32_e32 v3, 16, v3
	v_mul_f32_e32 v48, 0xbfb8aa3b, v3
	v_exp_f32_e32 v48, v48
	s_waitcnt vmcnt(0)
	v_mul_f32_e32 v47, v47, v234
	v_add_f32_e32 v48, 1.0, v48
	v_div_scale_f32 v49, s[0:1], v48, v48, v3
	s_nop 0
	v_rcp_f32_e32 v49, v48
	s_nop 0
	v_mul_f32_e32 v3, v3, v49
	v_mul_f32_e32 v3, v47, v3
	v_cvt_pk_bf16_f32 v3, v3, s0
	ds_write_b16 v1, v3 offset:64
	ds_read_u16 v3, v1 offset:336
	v_mul_f32_e32 v47, v121, v45
	v_mul_f32_e32 v47, v47, v234
	s_waitcnt lgkmcnt(0)
	v_lshlrev_b32_e32 v3, 16, v3
	v_mul_f32_e32 v48, 0xbfb8aa3b, v3
	v_exp_f32_e32 v48, v48
	s_nop 0
	v_add_f32_e32 v48, 1.0, v48
	v_div_scale_f32 v49, s[0:1], v48, v48, v3
	s_nop 0
	v_rcp_f32_e32 v49, v48
	s_nop 0
	v_mul_f32_e32 v3, v3, v49
	v_mul_f32_e32 v3, v47, v3
	v_cvt_pk_bf16_f32 v3, v3, s0
	ds_write_b16 v1, v3 offset:336
	ds_read_u16 v3, v1 offset:608
	v_mul_f32_e32 v47, v120, v44
	v_mul_f32_e32 v47, v47, v234
	s_waitcnt lgkmcnt(0)
	v_lshlrev_b32_e32 v3, 16, v3
	v_mul_f32_e32 v48, 0xbfb8aa3b, v3
	v_exp_f32_e32 v48, v48
	s_nop 0
	v_add_f32_e32 v48, 1.0, v48
	v_div_scale_f32 v49, s[0:1], v48, v48, v3
	s_nop 0
	v_rcp_f32_e32 v49, v48
	s_nop 0
	v_mul_f32_e32 v3, v3, v49
	v_mul_f32_e32 v3, v47, v3
	v_cvt_pk_bf16_f32 v3, v3, s0
	ds_write_b16 v1, v3 offset:608
	ds_read_u16 v3, v1 offset:880
	v_mul_f32_e32 v47, v119, v43
	v_mul_f32_e32 v47, v47, v234
	s_waitcnt lgkmcnt(0)
	v_lshlrev_b32_e32 v3, 16, v3
	v_mul_f32_e32 v48, 0xbfb8aa3b, v3
	v_exp_f32_e32 v48, v48
	s_nop 0
	v_add_f32_e32 v48, 1.0, v48
	v_div_scale_f32 v49, s[0:1], v48, v48, v3
	s_nop 0
	v_rcp_f32_e32 v49, v48
	s_nop 0
	v_mul_f32_e32 v3, v3, v49
	v_mul_f32_e32 v3, v47, v3
	v_cvt_pk_bf16_f32 v3, v3, s0
	ds_write_b16 v1, v3 offset:880
	ds_read_u16 v3, v1 offset:2240
	v_mul_f32_e32 v47, v118, v42
	v_mul_f32_e32 v47, v47, v234
	s_waitcnt lgkmcnt(0)
	v_lshlrev_b32_e32 v3, 16, v3
	v_mul_f32_e32 v48, 0xbfb8aa3b, v3
	v_exp_f32_e32 v48, v48
	s_nop 0
	v_add_f32_e32 v48, 1.0, v48
	v_div_scale_f32 v49, s[0:1], v48, v48, v3
	s_nop 0
	v_rcp_f32_e32 v49, v48
	s_nop 0
	v_mul_f32_e32 v3, v3, v49
	v_mul_f32_e32 v3, v47, v3
	v_cvt_pk_bf16_f32 v3, v3, s0
	ds_write_b16 v1, v3 offset:2240
	ds_read_u16 v3, v1 offset:2512
	v_mul_f32_e32 v47, v117, v41
	v_mul_f32_e32 v47, v47, v234
	s_waitcnt lgkmcnt(0)
	v_lshlrev_b32_e32 v3, 16, v3
	v_mul_f32_e32 v48, 0xbfb8aa3b, v3
	v_exp_f32_e32 v48, v48
	s_nop 0
	v_add_f32_e32 v48, 1.0, v48
	v_div_scale_f32 v49, s[0:1], v48, v48, v3
	s_nop 0
	v_rcp_f32_e32 v49, v48
	s_nop 0
	v_mul_f32_e32 v3, v3, v49
	v_mul_f32_e32 v3, v47, v3
	v_cvt_pk_bf16_f32 v3, v3, s0
	ds_write_b16 v1, v3 offset:2512
	ds_read_u16 v3, v1 offset:2784
	v_mul_f32_e32 v47, v116, v40
	v_mul_f32_e32 v47, v47, v234
	s_waitcnt lgkmcnt(0)
	v_lshlrev_b32_e32 v3, 16, v3
	v_mul_f32_e32 v48, 0xbfb8aa3b, v3
	v_exp_f32_e32 v48, v48
	s_nop 0
	v_add_f32_e32 v48, 1.0, v48
	v_div_scale_f32 v49, s[0:1], v48, v48, v3
	s_nop 0
	v_rcp_f32_e32 v49, v48
	s_nop 0
	v_mul_f32_e32 v3, v3, v49
	v_mul_f32_e32 v3, v47, v3
	v_cvt_pk_bf16_f32 v3, v3, s0
	ds_write_b16 v1, v3 offset:2784
	ds_read_u16 v3, v1 offset:3056
	v_mul_f32_e32 v47, v115, v35
	v_mul_f32_e32 v47, v47, v234
	s_waitcnt lgkmcnt(0)
	v_lshlrev_b32_e32 v3, 16, v3
	v_mul_f32_e32 v48, 0xbfb8aa3b, v3
	v_exp_f32_e32 v48, v48
	s_nop 0
	v_add_f32_e32 v48, 1.0, v48
	v_div_scale_f32 v49, s[0:1], v48, v48, v3
	s_nop 0
	v_rcp_f32_e32 v49, v48
	s_nop 0
	v_mul_f32_e32 v3, v3, v49
	v_mul_f32_e32 v3, v47, v3
	v_cvt_pk_bf16_f32 v3, v3, s0
	ds_write_b16 v1, v3 offset:3056
	ds_read_u16 v3, v1 offset:4416
	v_mul_f32_e32 v47, v114, v31
	v_mul_f32_e32 v47, v47, v234
	s_waitcnt lgkmcnt(0)
	v_lshlrev_b32_e32 v3, 16, v3
	v_mul_f32_e32 v48, 0xbfb8aa3b, v3
	v_exp_f32_e32 v48, v48
	s_nop 0
	v_add_f32_e32 v48, 1.0, v48
	v_div_scale_f32 v49, s[0:1], v48, v48, v3
	s_nop 0
	v_rcp_f32_e32 v49, v48
	s_nop 0
	v_mul_f32_e32 v3, v3, v49
	v_mul_f32_e32 v3, v47, v3
	v_cvt_pk_bf16_f32 v3, v3, s0
	ds_write_b16 v1, v3 offset:4416
	ds_read_u16 v3, v1 offset:4688
	v_mul_f32_e32 v47, v113, v27
	v_mul_f32_e32 v47, v47, v234
	s_waitcnt lgkmcnt(0)
	v_lshlrev_b32_e32 v3, 16, v3
	v_mul_f32_e32 v48, 0xbfb8aa3b, v3
	v_exp_f32_e32 v48, v48
	s_nop 0
	v_add_f32_e32 v48, 1.0, v48
	v_div_scale_f32 v49, s[0:1], v48, v48, v3
	s_nop 0
	v_rcp_f32_e32 v49, v48
	s_nop 0
	v_mul_f32_e32 v3, v3, v49
	v_mul_f32_e32 v3, v47, v3
	v_cvt_pk_bf16_f32 v3, v3, s0
	ds_write_b16 v1, v3 offset:4688
	ds_read_u16 v3, v1 offset:4960
	v_mul_f32_e32 v47, v112, v25
	v_mul_f32_e32 v47, v47, v234
	s_waitcnt lgkmcnt(0)
; #define LAS __attribute__((address_space(3)))
; DI unsigned cvtpk(float lo, float hi) { f32x2 v = {lo, hi}; bf16x2_t b = __builtin_convertvector(v, bf16x2_t); return __builtin_bit_cast(unsigned, b); }
; DI float bf2f(bf16 b) { return __uint_as_float(((unsigned)b) << 16); }
; DI float siluf_(float x) { return x / (1.f + __expf(-x)); }
; DI void gla_stage3(const Ctx& c0, int layer, int unit, int cb, LAS unsigned char* lds) {
;     ...
;     for (int vb = 0; vb < 4; ++vb) { const float g = gn[32 * vb + r];
; #pragma unroll
;         for (int rg = 0; rg < 16; ++rg) { LAS bf16* e = (LAS bf16*)(R + (4 * hi) * G3_PITCH + r * 2 + ((rg & 3) + 8 * (rg >> 2)) * G3_PITCH + 64 * vb);
;             const float z = bf2f(*e);
;             *e = (bf16)(cvtpk(o[vb][rg] * rs[rg] * g * siluf_(z), 0.f) & 0xffffu); }
;         asm volatile("" ::: "memory"); }
	v_lshlrev_b32_e32 v3, 16, v3
	v_mul_f32_e32 v48, 0xbfb8aa3b, v3
	v_exp_f32_e32 v48, v48
	s_nop 0
	v_add_f32_e32 v48, 1.0, v48
	v_div_scale_f32 v49, s[0:1], v48, v48, v3
	s_nop 0
	v_rcp_f32_e32 v49, v48
	s_nop 0
	v_mul_f32_e32 v3, v3, v49
	v_mul_f32_e32 v3, v47, v3
	v_cvt_pk_bf16_f32 v3, v3, s0
	ds_write_b16 v1, v3 offset:4960
	ds_read_u16 v3, v1 offset:5232
	v_mul_f32_e32 v47, v111, v24
	v_mul_f32_e32 v47, v47, v234
	s_waitcnt lgkmcnt(0)
	v_lshlrev_b32_e32 v3, 16, v3
	v_mul_f32_e32 v48, 0xbfb8aa3b, v3
	v_exp_f32_e32 v48, v48
	s_nop 0
	v_add_f32_e32 v48, 1.0, v48
	v_div_scale_f32 v49, s[0:1], v48, v48, v3
	s_nop 0
	v_rcp_f32_e32 v49, v48
	s_nop 0
	v_mul_f32_e32 v3, v3, v49
	v_mul_f32_e32 v3, v47, v3
	v_cvt_pk_bf16_f32 v3, v3, s0
	ds_write_b16 v1, v3 offset:5232
	ds_read_u16 v3, v1 offset:6592
	v_mul_f32_e32 v47, v110, v23
	v_mul_f32_e32 v47, v47, v234
	s_waitcnt lgkmcnt(0)
	v_lshlrev_b32_e32 v3, 16, v3
	v_mul_f32_e32 v48, 0xbfb8aa3b, v3
	v_exp_f32_e32 v48, v48
	s_nop 0
	v_add_f32_e32 v48, 1.0, v48
	v_div_scale_f32 v49, s[0:1], v48, v48, v3
	s_nop 0
	v_rcp_f32_e32 v49, v48
	s_nop 0
	v_mul_f32_e32 v3, v3, v49
	v_mul_f32_e32 v3, v47, v3
	v_cvt_pk_bf16_f32 v3, v3, s0
	ds_write_b16 v1, v3 offset:6592
	ds_read_u16 v3, v1 offset:6864
	v_mul_f32_e32 v47, v109, v22
	v_mul_f32_e32 v47, v47, v234
	s_waitcnt lgkmcnt(0)
	v_lshlrev_b32_e32 v3, 16, v3
	v_mul_f32_e32 v48, 0xbfb8aa3b, v3
	v_exp_f32_e32 v48, v48
	s_nop 0
	v_add_f32_e32 v48, 1.0, v48
	v_div_scale_f32 v49, s[0:1], v48, v48, v3
	s_nop 0
	v_rcp_f32_e32 v49, v48
	s_nop 0
	v_mul_f32_e32 v3, v3, v49
	v_mul_f32_e32 v3, v47, v3
	v_cvt_pk_bf16_f32 v3, v3, s0
	ds_write_b16 v1, v3 offset:6864
	ds_read_u16 v3, v1 offset:7136
	v_mul_f32_e32 v47, v108, v21
	v_mul_f32_e32 v47, v47, v234
	s_waitcnt lgkmcnt(0)
	v_lshlrev_b32_e32 v3, 16, v3
	v_mul_f32_e32 v48, 0xbfb8aa3b, v3
	v_exp_f32_e32 v48, v48
	s_nop 0
	v_add_f32_e32 v48, 1.0, v48
	v_div_scale_f32 v49, s[0:1], v48, v48, v3
	s_nop 0
	v_rcp_f32_e32 v49, v48
	s_nop 0
	v_mul_f32_e32 v3, v3, v49
	v_mul_f32_e32 v3, v47, v3
	v_cvt_pk_bf16_f32 v3, v3, s0
	ds_write_b16 v1, v3 offset:7136
	ds_read_u16 v3, v1 offset:7408
	v_mul_f32_e32 v47, v107, v20
	v_mul_f32_e32 v2, v47, v234
	s_waitcnt lgkmcnt(0)
	v_lshlrev_b32_e32 v3, 16, v3
	v_mul_f32_e32 v47, 0xbfb8aa3b, v3
	v_exp_f32_e32 v47, v47
	s_nop 0
	v_add_f32_e32 v47, 1.0, v47
	v_div_scale_f32 v48, s[0:1], v47, v47, v3
	s_nop 0
	v_rcp_f32_e32 v48, v47
	s_nop 0
	v_mul_f32_e32 v3, v3, v48
	v_mul_f32_e32 v2, v2, v3
	v_cvt_pk_bf16_f32 v2, v2, s0
	ds_write_b16 v1, v2 offset:7408
	ds_read_u16 v3, v1 offset:128
	v_mul_f32_e32 v47, v106, v46
	s_waitcnt lgkmcnt(0)
	v_lshlrev_b32_e32 v3, 16, v3
	v_mul_f32_e32 v48, 0xbfb8aa3b, v3
	v_exp_f32_e32 v48, v48
	s_waitcnt vmcnt(0)
	v_mul_f32_e32 v47, v47, v236
	v_add_f32_e32 v48, 1.0, v48
	v_div_scale_f32 v49, s[0:1], v48, v48, v3
	v_mul_f32_e32 v39, v39, v236
	v_mul_f32_e32 v38, v38, v236
	v_mul_f32_e32 v37, v37, v236
	v_rcp_f32_e32 v49, v48
	s_nop 0
	v_mul_f32_e32 v3, v3, v49
	v_mul_f32_e32 v3, v47, v3
	v_cvt_pk_bf16_f32 v3, v3, s0
	ds_write_b16 v1, v3 offset:128
	ds_read_u16 v3, v1 offset:400
	v_mul_f32_e32 v47, v105, v45
	v_mul_f32_e32 v47, v47, v236
	v_mul_f32_e32 v36, v36, v236
	v_mul_f32_e32 v34, v34, v236
	s_waitcnt lgkmcnt(0)
	v_lshlrev_b32_e32 v3, 16, v3
	v_mul_f32_e32 v48, 0xbfb8aa3b, v3
	v_exp_f32_e32 v48, v48
	v_mul_f32_e32 v33, v33, v236
	v_mul_f32_e32 v32, v32, v236
	v_mul_f32_e32 v30, v30, v236
	v_add_f32_e32 v48, 1.0, v48
	v_div_scale_f32 v49, s[0:1], v48, v48, v3
	v_mul_f32_e32 v29, v29, v236
	v_mul_f32_e32 v28, v28, v236
	v_rcp_f32_e32 v49, v48
	s_nop 0
	v_mul_f32_e32 v3, v3, v49
	v_mul_f32_e32 v3, v47, v3
	v_cvt_pk_bf16_f32 v3, v3, s0
	ds_write_b16 v1, v3 offset:400
	ds_read_u16 v3, v1 offset:672
	v_mul_f32_e32 v47, v104, v44
	v_mul_f32_e32 v47, v47, v236
	s_waitcnt lgkmcnt(0)
	v_lshlrev_b32_e32 v3, 16, v3
	v_mul_f32_e32 v48, 0xbfb8aa3b, v3
	v_exp_f32_e32 v48, v48
	s_nop 0
	v_add_f32_e32 v48, 1.0, v48
	v_div_scale_f32 v49, s[0:1], v48, v48, v3
	s_nop 0
	v_rcp_f32_e32 v49, v48
	s_nop 0
	v_mul_f32_e32 v3, v3, v49
	v_mul_f32_e32 v3, v47, v3
	v_cvt_pk_bf16_f32 v3, v3, s0
	ds_write_b16 v1, v3 offset:672
	ds_read_u16 v3, v1 offset:944
	v_mul_f32_e32 v47, v103, v43
	v_mul_f32_e32 v47, v47, v236
	s_waitcnt lgkmcnt(0)
	v_lshlrev_b32_e32 v3, 16, v3
	v_mul_f32_e32 v48, 0xbfb8aa3b, v3
	v_exp_f32_e32 v48, v48
	s_nop 0
	v_add_f32_e32 v48, 1.0, v48
	v_div_scale_f32 v49, s[0:1], v48, v48, v3
	s_nop 0
	v_rcp_f32_e32 v49, v48
	s_nop 0
	v_mul_f32_e32 v3, v3, v49
	v_mul_f32_e32 v3, v47, v3
	v_cvt_pk_bf16_f32 v3, v3, s0
	ds_write_b16 v1, v3 offset:944
	ds_read_u16 v3, v1 offset:2304
	v_mul_f32_e32 v47, v102, v42
	v_mul_f32_e32 v47, v47, v236
	v_mul_f32_e32 v2, v26, v236
	s_waitcnt lgkmcnt(0)
	v_lshlrev_b32_e32 v3, 16, v3
	v_mul_f32_e32 v48, 0xbfb8aa3b, v3
	v_exp_f32_e32 v48, v48
	s_nop 0
	v_add_f32_e32 v48, 1.0, v48
	v_div_scale_f32 v49, s[0:1], v48, v48, v3
	s_nop 0
	v_rcp_f32_e32 v49, v48
	s_nop 0
	v_mul_f32_e32 v3, v3, v49
	v_mul_f32_e32 v3, v47, v3
	v_cvt_pk_bf16_f32 v3, v3, s0
	ds_write_b16 v1, v3 offset:2304
	ds_read_u16 v3, v1 offset:2576
	s_waitcnt lgkmcnt(0)
	v_lshlrev_b32_e32 v3, 16, v3
	v_mul_f32_e32 v47, 0xbfb8aa3b, v3
	v_exp_f32_e32 v47, v47
	s_nop 0
	v_add_f32_e32 v47, 1.0, v47
	v_div_scale_f32 v48, s[0:1], v47, v47, v3
	s_nop 0
	v_rcp_f32_e32 v48, v47
	s_nop 0
	v_mul_f32_e32 v3, v3, v48
	v_mul_f32_e32 v3, v39, v3
	v_cvt_pk_bf16_f32 v3, v3, s0
	ds_write_b16 v1, v3 offset:2576
	ds_read_u16 v3, v1 offset:2848
	s_waitcnt lgkmcnt(0)
; #define LAS __attribute__((address_space(3)))
; DI unsigned cvtpk(float lo, float hi) { f32x2 v = {lo, hi}; bf16x2_t b = __builtin_convertvector(v, bf16x2_t); return __builtin_bit_cast(unsigned, b); }
; DI float bf2f(bf16 b) { return __uint_as_float(((unsigned)b) << 16); }
; DI float siluf_(float x) { return x / (1.f + __expf(-x)); }
; DI void gla_stage3(const Ctx& c0, int layer, int unit, int cb, LAS unsigned char* lds) {
;     ...
;     for (int vb = 0; vb < 4; ++vb) { const float g = gn[32 * vb + r];
; #pragma unroll
;         for (int rg = 0; rg < 16; ++rg) { LAS bf16* e = (LAS bf16*)(R + (4 * hi) * G3_PITCH + r * 2 + ((rg & 3) + 8 * (rg >> 2)) * G3_PITCH + 64 * vb);
;             const float z = bf2f(*e);
;             *e = (bf16)(cvtpk(o[vb][rg] * rs[rg] * g * siluf_(z), 0.f) & 0xffffu); }
;         asm volatile("" ::: "memory"); }
	v_lshlrev_b32_e32 v3, 16, v3
	v_mul_f32_e32 v39, 0xbfb8aa3b, v3
	v_exp_f32_e32 v39, v39
	s_nop 0
	v_add_f32_e32 v39, 1.0, v39
	v_div_scale_f32 v47, s[0:1], v39, v39, v3
	s_nop 0
	v_rcp_f32_e32 v47, v39
	s_nop 0
	v_mul_f32_e32 v3, v3, v47
	v_mul_f32_e32 v3, v38, v3
	v_cvt_pk_bf16_f32 v3, v3, s0
	ds_write_b16 v1, v3 offset:2848
	ds_read_u16 v3, v1 offset:3120
	s_waitcnt lgkmcnt(0)
	v_lshlrev_b32_e32 v3, 16, v3
	v_mul_f32_e32 v38, 0xbfb8aa3b, v3
	v_exp_f32_e32 v38, v38
	s_nop 0
	v_add_f32_e32 v38, 1.0, v38
	v_div_scale_f32 v39, s[0:1], v38, v38, v3
	s_nop 0
	v_rcp_f32_e32 v39, v38
	s_nop 0
	v_mul_f32_e32 v3, v3, v39
	v_mul_f32_e32 v3, v37, v3
	v_cvt_pk_bf16_f32 v3, v3, s0
	ds_write_b16 v1, v3 offset:3120
	ds_read_u16 v3, v1 offset:4480
	s_waitcnt lgkmcnt(0)
	v_lshlrev_b32_e32 v3, 16, v3
	v_mul_f32_e32 v37, 0xbfb8aa3b, v3
	v_exp_f32_e32 v37, v37
	s_nop 0
	v_add_f32_e32 v37, 1.0, v37
	v_div_scale_f32 v38, s[0:1], v37, v37, v3
	s_nop 0
	v_rcp_f32_e32 v38, v37
	s_nop 0
	v_mul_f32_e32 v3, v3, v38
	v_mul_f32_e32 v3, v36, v3
	v_cvt_pk_bf16_f32 v3, v3, s0
	ds_write_b16 v1, v3 offset:4480
	ds_read_u16 v3, v1 offset:4752
	s_waitcnt lgkmcnt(0)
	v_lshlrev_b32_e32 v3, 16, v3
	v_mul_f32_e32 v36, 0xbfb8aa3b, v3
	v_exp_f32_e32 v36, v36
	s_nop 0
	v_add_f32_e32 v36, 1.0, v36
	v_div_scale_f32 v37, s[0:1], v36, v36, v3
	s_nop 0
	v_rcp_f32_e32 v37, v36
	s_nop 0
	v_mul_f32_e32 v3, v3, v37
	v_mul_f32_e32 v3, v34, v3
	v_cvt_pk_bf16_f32 v3, v3, s0
	ds_write_b16 v1, v3 offset:4752
	ds_read_u16 v3, v1 offset:5024
	s_waitcnt lgkmcnt(0)
	v_lshlrev_b32_e32 v3, 16, v3
	v_mul_f32_e32 v34, 0xbfb8aa3b, v3
	v_exp_f32_e32 v34, v34
	s_nop 0
	v_add_f32_e32 v34, 1.0, v34
	v_div_scale_f32 v36, s[0:1], v34, v34, v3
	s_nop 0
	v_rcp_f32_e32 v36, v34
	s_nop 0
	v_mul_f32_e32 v3, v3, v36
	v_mul_f32_e32 v3, v33, v3
	v_cvt_pk_bf16_f32 v3, v3, s0
	ds_write_b16 v1, v3 offset:5024
	ds_read_u16 v3, v1 offset:5296
	s_waitcnt lgkmcnt(0)
	v_lshlrev_b32_e32 v3, 16, v3
	v_mul_f32_e32 v33, 0xbfb8aa3b, v3
	v_exp_f32_e32 v33, v33
	s_nop 0
	v_add_f32_e32 v33, 1.0, v33
	v_div_scale_f32 v34, s[0:1], v33, v33, v3
	s_nop 0
	v_rcp_f32_e32 v34, v33
	s_nop 0
	v_mul_f32_e32 v3, v3, v34
	v_mul_f32_e32 v3, v32, v3
	v_cvt_pk_bf16_f32 v3, v3, s0
	ds_write_b16 v1, v3 offset:5296
	ds_read_u16 v3, v1 offset:6656
	s_waitcnt lgkmcnt(0)
	v_lshlrev_b32_e32 v3, 16, v3
	v_mul_f32_e32 v32, 0xbfb8aa3b, v3
	v_exp_f32_e32 v32, v32
	s_nop 0
	v_add_f32_e32 v32, 1.0, v32
	v_div_scale_f32 v33, s[0:1], v32, v32, v3
	s_nop 0
	v_rcp_f32_e32 v33, v32
	s_nop 0
	v_mul_f32_e32 v3, v3, v33
	v_mul_f32_e32 v3, v30, v3
	v_cvt_pk_bf16_f32 v3, v3, s0
	ds_write_b16 v1, v3 offset:6656
	ds_read_u16 v3, v1 offset:6928
	s_waitcnt lgkmcnt(0)
	v_lshlrev_b32_e32 v3, 16, v3
	v_mul_f32_e32 v30, 0xbfb8aa3b, v3
	v_exp_f32_e32 v30, v30
	s_nop 0
	v_add_f32_e32 v30, 1.0, v30
	v_div_scale_f32 v32, s[0:1], v30, v30, v3
	s_nop 0
	v_rcp_f32_e32 v32, v30
	s_nop 0
	v_mul_f32_e32 v3, v3, v32
	v_mul_f32_e32 v3, v29, v3
	v_cvt_pk_bf16_f32 v3, v3, s0
	ds_write_b16 v1, v3 offset:6928
	ds_read_u16 v3, v1 offset:7200
	s_waitcnt lgkmcnt(0)
	v_lshlrev_b32_e32 v3, 16, v3
	v_mul_f32_e32 v29, 0xbfb8aa3b, v3
	v_exp_f32_e32 v29, v29
	s_nop 0
	v_add_f32_e32 v29, 1.0, v29
	v_div_scale_f32 v30, s[0:1], v29, v29, v3
	s_nop 0
	v_rcp_f32_e32 v30, v29
	s_nop 0
	v_mul_f32_e32 v3, v3, v30
	v_mul_f32_e32 v3, v28, v3
	v_cvt_pk_bf16_f32 v3, v3, s0
	ds_write_b16 v1, v3 offset:7200
	ds_read_u16 v3, v1 offset:7472
	s_waitcnt lgkmcnt(0)
	v_lshlrev_b32_e32 v3, 16, v3
	v_mul_f32_e32 v26, 0xbfb8aa3b, v3
	v_exp_f32_e32 v26, v26
	s_nop 0
	v_add_f32_e32 v26, 1.0, v26
	v_div_scale_f32 v28, s[0:1], v26, v26, v3
	s_nop 0
	v_rcp_f32_e32 v28, v26
	s_nop 0
	v_mul_f32_e32 v3, v3, v28
	v_mul_f32_e32 v2, v2, v3
	v_cvt_pk_bf16_f32 v2, v2, s0
	ds_write_b16 v1, v2 offset:7472
	ds_read_u16 v3, v1 offset:192
	s_waitcnt lgkmcnt(0)
	v_lshlrev_b32_e32 v3, 16, v3
	v_mul_f32_e32 v26, 0xbfb8aa3b, v3
	v_exp_f32_e32 v26, v26
	s_waitcnt vmcnt(31)
	v_mul_f32_e32 v19, v19, v238
	v_add_f32_e32 v26, 1.0, v26
	v_div_scale_f32 v28, s[0:1], v26, v26, v3
	v_mul_f32_e32 v18, v18, v238
	v_mul_f32_e32 v17, v17, v238
	v_mul_f32_e32 v16, v16, v238
	v_rcp_f32_e32 v28, v26
	s_nop 0
	v_mul_f32_e32 v3, v3, v28
	v_mul_f32_e32 v3, v19, v3
	v_cvt_pk_bf16_f32 v3, v3, s0
	ds_write_b16 v1, v3 offset:192
	ds_read_u16 v3, v1 offset:464
	v_mul_f32_e32 v15, v15, v238
	v_mul_f32_e32 v14, v14, v238
	v_mul_f32_e32 v13, v13, v238
	v_mul_f32_e32 v12, v12, v238
	s_waitcnt lgkmcnt(0)
	v_lshlrev_b32_e32 v3, 16, v3
	v_mul_f32_e32 v19, 0xbfb8aa3b, v3
	v_exp_f32_e32 v19, v19
	v_mul_f32_e32 v11, v11, v238
	v_mul_f32_e32 v10, v10, v238
	v_mul_f32_e32 v9, v9, v238
	v_add_f32_e32 v19, 1.0, v19
	v_div_scale_f32 v26, s[0:1], v19, v19, v3
	v_mul_f32_e32 v8, v8, v238
	v_mul_f32_e32 v7, v7, v238
	v_mul_f32_e32 v6, v6, v238
	v_rcp_f32_e32 v26, v19
	s_nop 0
	v_mul_f32_e32 v3, v3, v26
	v_mul_f32_e32 v3, v18, v3
	v_cvt_pk_bf16_f32 v3, v3, s0
	ds_write_b16 v1, v3 offset:464
	ds_read_u16 v3, v1 offset:736
	v_mul_f32_e32 v5, v5, v238
	v_mul_f32_e32 v2, v4, v238
	s_waitcnt lgkmcnt(0)
	v_lshlrev_b32_e32 v3, 16, v3
	v_mul_f32_e32 v18, 0xbfb8aa3b, v3
	v_exp_f32_e32 v18, v18
	s_nop 0
	v_add_f32_e32 v18, 1.0, v18
	v_div_scale_f32 v19, s[0:1], v18, v18, v3
	s_nop 0
	v_rcp_f32_e32 v19, v18
	s_nop 0
	v_mul_f32_e32 v3, v3, v19
	v_mul_f32_e32 v3, v17, v3
	v_cvt_pk_bf16_f32 v3, v3, s0
	ds_write_b16 v1, v3 offset:736
	ds_read_u16 v3, v1 offset:1008
	s_waitcnt lgkmcnt(0)
	v_lshlrev_b32_e32 v3, 16, v3
	v_mul_f32_e32 v17, 0xbfb8aa3b, v3
	v_exp_f32_e32 v17, v17
	s_nop 0
	v_add_f32_e32 v17, 1.0, v17
	v_div_scale_f32 v18, s[0:1], v17, v17, v3
	s_nop 0
	v_rcp_f32_e32 v18, v17
	s_nop 0
	v_mul_f32_e32 v3, v3, v18
	v_mul_f32_e32 v3, v16, v3
	v_cvt_pk_bf16_f32 v3, v3, s0
	ds_write_b16 v1, v3 offset:1008
	ds_read_u16 v3, v1 offset:2368
	s_waitcnt lgkmcnt(0)
; #define LAS __attribute__((address_space(3)))
; #define LDS_WAIT() asm volatile("s_waitcnt lgkmcnt(0)" ::: "memory")
; DI unsigned cvtpk(float lo, float hi) { f32x2 v = {lo, hi}; bf16x2_t b = __builtin_convertvector(v, bf16x2_t); return __builtin_bit_cast(unsigned, b); }
; DI float bf2f(bf16 b) { return __uint_as_float(((unsigned)b) << 16); }
; DI float siluf_(float x) { return x / (1.f + __expf(-x)); }
; DI void g3_tile_out(bf16* g, const LAS unsigned char* R, int lane) {
;     LDS_WAIT();
; #pragma unroll
;     for (int it = 0; it < 8; ++it) { const int row = 4 * it + (lane >> 4), ch = lane & 15;
;         *(u32x4*)(g + (size_t)row * 512 + ch * 8) = *(const LAS u32x4*)(R + row * G3_PITCH + ch * 16); }
;     LDS_WAIT();
; }
; DI void gla_stage3(const Ctx& c0, int layer, int unit, int cb, LAS unsigned char* lds) {
;     ...
;     for (int vb = 0; vb < 4; ++vb) { const float g = gn[32 * vb + r];
; #pragma unroll
;         for (int rg = 0; rg < 16; ++rg) { LAS bf16* e = (LAS bf16*)(R + (4 * hi) * G3_PITCH + r * 2 + ((rg & 3) + 8 * (rg >> 2)) * G3_PITCH + 64 * vb);
;             const float z = bf2f(*e);
;             *e = (bf16)(cvtpk(o[vb][rg] * rs[rg] * g * siluf_(z), 0.f) & 0xffffu); }
;         asm volatile("" ::: "memory"); }
;     g3_tile_out((bf16*)(c.ws + O_OGLA) + row0 * 512 + h * 128, R, lane);
	v_lshlrev_b32_e32 v3, 16, v3
	v_mul_f32_e32 v16, 0xbfb8aa3b, v3
	v_exp_f32_e32 v16, v16
	s_nop 0
	v_add_f32_e32 v16, 1.0, v16
	v_div_scale_f32 v17, s[0:1], v16, v16, v3
	s_nop 0
	v_rcp_f32_e32 v17, v16
	s_nop 0
	v_mul_f32_e32 v3, v3, v17
	v_mul_f32_e32 v3, v15, v3
	v_cvt_pk_bf16_f32 v3, v3, s0
	ds_write_b16 v1, v3 offset:2368
	ds_read_u16 v3, v1 offset:2640
	s_waitcnt lgkmcnt(0)
	v_lshlrev_b32_e32 v3, 16, v3
	v_mul_f32_e32 v15, 0xbfb8aa3b, v3
	v_exp_f32_e32 v15, v15
	s_nop 0
	v_add_f32_e32 v15, 1.0, v15
	v_div_scale_f32 v16, s[0:1], v15, v15, v3
	s_nop 0
	v_rcp_f32_e32 v16, v15
	s_nop 0
	v_mul_f32_e32 v3, v3, v16
	v_mul_f32_e32 v3, v14, v3
	v_cvt_pk_bf16_f32 v3, v3, s0
	ds_write_b16 v1, v3 offset:2640
	ds_read_u16 v3, v1 offset:2912
	s_waitcnt lgkmcnt(0)
	v_lshlrev_b32_e32 v3, 16, v3
	v_mul_f32_e32 v14, 0xbfb8aa3b, v3
	v_exp_f32_e32 v14, v14
	s_nop 0
	v_add_f32_e32 v14, 1.0, v14
	v_div_scale_f32 v15, s[0:1], v14, v14, v3
	s_nop 0
	v_rcp_f32_e32 v15, v14
	s_nop 0
	v_mul_f32_e32 v3, v3, v15
	v_mul_f32_e32 v3, v13, v3
	v_cvt_pk_bf16_f32 v3, v3, s0
	ds_write_b16 v1, v3 offset:2912
	ds_read_u16 v3, v1 offset:3184
	s_waitcnt lgkmcnt(0)
	v_lshlrev_b32_e32 v3, 16, v3
	v_mul_f32_e32 v13, 0xbfb8aa3b, v3
	v_exp_f32_e32 v13, v13
	s_nop 0
	v_add_f32_e32 v13, 1.0, v13
	v_div_scale_f32 v14, s[0:1], v13, v13, v3
	s_nop 0
	v_rcp_f32_e32 v14, v13
	s_nop 0
	v_mul_f32_e32 v3, v3, v14
	v_mul_f32_e32 v3, v12, v3
	v_cvt_pk_bf16_f32 v3, v3, s0
	ds_write_b16 v1, v3 offset:3184
	ds_read_u16 v3, v1 offset:4544
	s_waitcnt lgkmcnt(0)
	v_lshlrev_b32_e32 v3, 16, v3
	v_mul_f32_e32 v12, 0xbfb8aa3b, v3
	v_exp_f32_e32 v12, v12
	s_nop 0
	v_add_f32_e32 v12, 1.0, v12
	v_div_scale_f32 v13, s[0:1], v12, v12, v3
	s_nop 0
	v_rcp_f32_e32 v13, v12
	s_nop 0
	v_mul_f32_e32 v3, v3, v13
	v_mul_f32_e32 v3, v11, v3
	v_cvt_pk_bf16_f32 v3, v3, s0
	ds_write_b16 v1, v3 offset:4544
	ds_read_u16 v3, v1 offset:4816
	s_waitcnt lgkmcnt(0)
	v_lshlrev_b32_e32 v3, 16, v3
	v_mul_f32_e32 v11, 0xbfb8aa3b, v3
	v_exp_f32_e32 v11, v11
	s_nop 0
	v_add_f32_e32 v11, 1.0, v11
	v_div_scale_f32 v12, s[0:1], v11, v11, v3
	s_nop 0
	v_rcp_f32_e32 v12, v11
	s_nop 0
	v_mul_f32_e32 v3, v3, v12
	v_mul_f32_e32 v3, v10, v3
	v_cvt_pk_bf16_f32 v3, v3, s0
	ds_write_b16 v1, v3 offset:4816
	ds_read_u16 v3, v1 offset:5088
	s_waitcnt lgkmcnt(0)
	v_lshlrev_b32_e32 v3, 16, v3
	v_mul_f32_e32 v10, 0xbfb8aa3b, v3
	v_exp_f32_e32 v10, v10
	s_nop 0
	v_add_f32_e32 v10, 1.0, v10
	v_div_scale_f32 v11, s[0:1], v10, v10, v3
	s_nop 0
	v_rcp_f32_e32 v11, v10
	s_nop 0
	v_mul_f32_e32 v3, v3, v11
	v_mul_f32_e32 v3, v9, v3
	v_cvt_pk_bf16_f32 v3, v3, s0
	ds_write_b16 v1, v3 offset:5088
	ds_read_u16 v3, v1 offset:5360
	s_waitcnt lgkmcnt(0)
	v_lshlrev_b32_e32 v3, 16, v3
	v_mul_f32_e32 v9, 0xbfb8aa3b, v3
	v_exp_f32_e32 v9, v9
	s_nop 0
	v_add_f32_e32 v9, 1.0, v9
	v_div_scale_f32 v10, s[0:1], v9, v9, v3
	s_nop 0
	v_rcp_f32_e32 v10, v9
	s_nop 0
	v_mul_f32_e32 v3, v3, v10
	v_mul_f32_e32 v3, v8, v3
	v_cvt_pk_bf16_f32 v3, v3, s0
	ds_write_b16 v1, v3 offset:5360
	ds_read_u16 v3, v1 offset:6720
	s_waitcnt lgkmcnt(0)
	v_lshlrev_b32_e32 v3, 16, v3
	v_mul_f32_e32 v8, 0xbfb8aa3b, v3
	v_exp_f32_e32 v8, v8
	s_nop 0
	v_add_f32_e32 v8, 1.0, v8
	v_div_scale_f32 v9, s[0:1], v8, v8, v3
	s_nop 0
	v_rcp_f32_e32 v9, v8
	s_nop 0
	v_mul_f32_e32 v3, v3, v9
	v_mul_f32_e32 v3, v7, v3
	v_cvt_pk_bf16_f32 v3, v3, s0
	ds_write_b16 v1, v3 offset:6720
	ds_read_u16 v3, v1 offset:6992
	s_waitcnt lgkmcnt(0)
	v_lshlrev_b32_e32 v3, 16, v3
	v_mul_f32_e32 v7, 0xbfb8aa3b, v3
	v_exp_f32_e32 v7, v7
	s_nop 0
	v_add_f32_e32 v7, 1.0, v7
	v_div_scale_f32 v8, s[0:1], v7, v7, v3
	s_nop 0
	v_rcp_f32_e32 v8, v7
	s_nop 0
	v_mul_f32_e32 v3, v3, v8
	v_mul_f32_e32 v3, v6, v3
	v_cvt_pk_bf16_f32 v3, v3, s0
	ds_write_b16 v1, v3 offset:6992
	ds_read_u16 v3, v1 offset:7264
	s_waitcnt lgkmcnt(0)
	v_lshlrev_b32_e32 v3, 16, v3
	v_mul_f32_e32 v6, 0xbfb8aa3b, v3
	v_exp_f32_e32 v6, v6
	s_nop 0
	v_add_f32_e32 v6, 1.0, v6
	v_div_scale_f32 v7, s[0:1], v6, v6, v3
	s_nop 0
	v_rcp_f32_e32 v7, v6
	s_nop 0
	v_mul_f32_e32 v3, v3, v7
	v_mul_f32_e32 v3, v5, v3
	v_cvt_pk_bf16_f32 v3, v3, s0
	ds_write_b16 v1, v3 offset:7264
	ds_read_u16 v3, v1 offset:7536
	s_waitcnt lgkmcnt(0)
	v_lshlrev_b32_e32 v3, 16, v3
	v_mul_f32_e32 v4, 0xbfb8aa3b, v3
	v_exp_f32_e32 v4, v4
	s_nop 0
	v_add_f32_e32 v4, 1.0, v4
	v_div_scale_f32 v5, s[0:1], v4, v4, v3
	s_nop 0
	v_rcp_f32_e32 v5, v4
	s_nop 0
	v_mul_f32_e32 v3, v3, v5
	v_mul_f32_e32 v2, v2, v3
	v_cvt_pk_bf16_f32 v2, v2, s0
	ds_write_b16 v1, v2 offset:7536
	s_waitcnt lgkmcnt(0)
	ds_read_b128 v[2:5], v92
	v_lshl_add_u64 v[6:7], v[90:91], 0, s[22:23]
	v_lshl_add_u64 v[8:9], v[6:7], 0, v[66:67]
	s_waitcnt lgkmcnt(0)
	global_store_dwordx4 v[8:9], v[2:5], off
	ds_read_b128 v[2:5], v92 offset:1088
	v_lshl_add_u64 v[8:9], v[6:7], 0, v[68:69]
	s_waitcnt lgkmcnt(0)
	global_store_dwordx4 v[8:9], v[2:5], off
	ds_read_b128 v[2:5], v92 offset:2176
	v_lshl_add_u64 v[8:9], v[6:7], 0, v[70:71]
	s_waitcnt lgkmcnt(0)
	global_store_dwordx4 v[8:9], v[2:5], off
	ds_read_b128 v[2:5], v92 offset:3264
	v_lshl_add_u64 v[8:9], v[6:7], 0, v[72:73]
	s_waitcnt lgkmcnt(0)
	global_store_dwordx4 v[8:9], v[2:5], off
	ds_read_b128 v[2:5], v92 offset:4352
	v_lshl_add_u64 v[8:9], v[6:7], 0, v[74:75]
	s_waitcnt lgkmcnt(0)
	global_store_dwordx4 v[8:9], v[2:5], off
	ds_read_b128 v[2:5], v92 offset:5440
	v_lshl_add_u64 v[8:9], v[6:7], 0, v[76:77]
	s_waitcnt lgkmcnt(0)
	global_store_dwordx4 v[8:9], v[2:5], off
	ds_read_b128 v[2:5], v92 offset:6528
	v_lshl_add_u64 v[8:9], v[6:7], 0, v[78:79]
	v_lshl_add_u64 v[6:7], v[6:7], 0, v[80:81]
	s_waitcnt lgkmcnt(0)
	global_store_dwordx4 v[8:9], v[2:5], off
	ds_read_b128 v[2:5], v92 offset:7616
	s_waitcnt lgkmcnt(0)
	global_store_dwordx4 v[6:7], v[2:5], off
	s_waitcnt lgkmcnt(0)
	s_cbranch_scc1 .LBB0_604

; #define LAS __attribute__((address_space(3)))
; #define LDS_WAIT() asm volatile("s_waitcnt lgkmcnt(0)" ::: "memory")
; template <bool CMP> DI void tile_compute(LAS unsigned char* lds, int buf, const bf16x8 (&q)[4], int lo, int hv, ASt& st, f32x16& imp0, f32x16& imp1, int jt, LAS float* wsf, int lane) {
;     ...
;     float mx = __builtin_fmaxf(p0[0], p1[0]);
; #pragma unroll
;     for (int rg = 1; rg < 16; ++rg) mx = __builtin_fmaxf(__builtin_fmaxf(mx, p0[rg]), p1[rg]);
;     if (!anyPart && dead) mx = NEGB;
;     mx = __builtin_fmaxf(mx, __shfl_xor(mx, 32));
;     const float mnew = fmaxf(st.m, mx);
;     const float alpha = __builtin_amdgcn_exp2f(st.m - mnew);
;     st.m = mnew;
;     float sum = 0.f;
;     const float msub = (!anyPart && dead) ? 1e30f : mnew;
; #pragma unroll
;     for (int rg = 0; rg < 16; ++rg) { p0[rg] = __builtin_amdgcn_exp2f(p0[rg] - msub); p1[rg] = __builtin_amdgcn_exp2f(p1[rg] - msub); sum += p0[rg] + p1[rg]; }
;     st.l = st.l * alpha + sum;
;     if (__builtin_amdgcn_ballot_w64(alpha != 1.f) != 0ull) {
;         if (hi == 0) wsf[r] = alpha;
;         LDS_WAIT();
; #pragma unroll
;         for (int g4 = 0; g4 < 4; ++g4) { const f32x4 f = *(const LAS f32x4*)(wsf + 8 * g4 + 4 * hi);
; #pragma unroll
;             for (int k = 0; k < 4; ++k) { st.o0[4 * g4 + k] *= f[k]; st.o1[4 * g4 + k] *= f[k]; if (CMP) { imp0[4 * g4 + k] *= f[k]; imp1[4 * g4 + k] *= f[k]; } } }
.LBB0_1164:
	s_nop 10
	v_max_f32_e32 v141, v68, v68
	v_max_f32_e32 v229, v84, v84
	v_max_f32_e32 v141, v229, v141
	v_max3_f32 v141, v141, v85, v69
	v_max3_f32 v141, v141, v86, v70
	v_max3_f32 v141, v141, v87, v71
	v_max3_f32 v141, v141, v88, v72
	v_max3_f32 v141, v141, v89, v73
	v_max3_f32 v141, v141, v90, v74
	v_max3_f32 v141, v141, v91, v75
	v_max3_f32 v141, v141, v92, v76
	v_max3_f32 v141, v141, v93, v77
	v_max3_f32 v141, v141, v94, v78
	v_max3_f32 v141, v141, v95, v79
	v_max3_f32 v141, v141, v96, v80
	v_max3_f32 v141, v141, v97, v81
	v_max3_f32 v141, v141, v98, v82
	v_max3_f32 v141, v141, v99, v83
	s_and_b64 s[80:81], s[80:81], s[14:15]
	v_cndmask_b32_e64 v141, v141, v217, s[80:81]
	ds_bpermute_b32 v229, v135, v141
	s_waitcnt lgkmcnt(0)
	v_max3_f32 v141, v228, v141, v229
	v_sub_f32_e32 v229, v141, v228
	v_cmp_lt_f32_e32 vcc, 0x41000000, v229
	s_nop 1
	v_cndmask_b32_e32 v141, v228, v141, vcc
	v_sub_f32_e32 v228, v228, v141
	v_exp_f32_e32 v228, v228
	s_nop 0
	v_cmp_neq_f32_e32 vcc, 1.0, v228
	s_cbranch_vccz .LBB0_1168
	s_and_saveexec_b64 s[14:15], s[8:9]
	ds_write_b32 v197, v228 offset:32768
	s_or_b64 exec, exec, s[14:15]
	s_waitcnt lgkmcnt(0)
	v_add_u32_e32 v229, s18, v198
	ds_read_b128 v[230:233], v229 offset:32864
	ds_read_b128 v[234:237], v229 offset:32832
	ds_read_b128 v[238:241], v229 offset:32800
	ds_read_b128 v[242:245], v229 offset:32768
	s_waitcnt lgkmcnt(0)
	s_waitcnt lgkmcnt(0)
	v_pk_mul_f32 v[64:65], v[64:65], v[230:231]
	v_pk_mul_f32 v[60:61], v[60:61], v[234:235]
	v_pk_mul_f32 v[56:57], v[56:57], v[238:239]
	v_pk_mul_f32 v[66:67], v[66:67], v[232:233]
	v_pk_mul_f32 v[62:63], v[62:63], v[236:237]
	v_pk_mul_f32 v[58:59], v[58:59], v[240:241]
	v_pk_mul_f32 v[54:55], v[54:55], v[244:245]
	v_pk_mul_f32 v[52:53], v[52:53], v[242:243]
	v_pk_mul_f32 v[48:49], v[48:49], v[230:231]
	v_pk_mul_f32 v[44:45], v[44:45], v[234:235]
	v_pk_mul_f32 v[40:41], v[40:41], v[238:239]
	v_pk_mul_f32 v[50:51], v[50:51], v[232:233]
	v_pk_mul_f32 v[46:47], v[46:47], v[236:237]
	v_pk_mul_f32 v[42:43], v[42:43], v[240:241]
	v_pk_mul_f32 v[38:39], v[38:39], v[244:245]
	v_pk_mul_f32 v[36:37], v[36:37], v[242:243]
	v_pk_mul_f32 v[32:33], v[32:33], v[230:231]
	v_pk_mul_f32 v[28:29], v[28:29], v[234:235]
	v_pk_mul_f32 v[24:25], v[24:25], v[238:239]
	v_pk_mul_f32 v[34:35], v[34:35], v[232:233]
	v_pk_mul_f32 v[30:31], v[30:31], v[236:237]
	v_pk_mul_f32 v[26:27], v[26:27], v[240:241]
	v_pk_mul_f32 v[22:23], v[22:23], v[244:245]
	v_pk_mul_f32 v[20:21], v[20:21], v[242:243]
	v_pk_mul_f32 v[16:17], v[16:17], v[230:231]
	v_pk_mul_f32 v[12:13], v[12:13], v[234:235]
	v_pk_mul_f32 v[8:9], v[8:9], v[238:239]
	v_pk_mul_f32 v[18:19], v[18:19], v[232:233]
	v_pk_mul_f32 v[14:15], v[14:15], v[236:237]
	v_pk_mul_f32 v[10:11], v[10:11], v[240:241]
	v_pk_mul_f32 v[6:7], v[6:7], v[244:245]
	v_pk_mul_f32 v[4:5], v[4:5], v[242:243]

; #define LDS_WAIT() asm volatile("s_waitcnt lgkmcnt(0)" ::: "memory")
; template <bool CMP> DI void tile_compute(LAS unsigned char* lds, int buf, const bf16x8 (&q)[4], int lo, int hv, ASt& st, f32x16& imp0, f32x16& imp1, int jt, LAS float* wsf, int lane) {
;     ...
;     float mx = __builtin_fmaxf(p0[0], p1[0]);
; #pragma unroll
;     for (int rg = 1; rg < 16; ++rg) mx = __builtin_fmaxf(__builtin_fmaxf(mx, p0[rg]), p1[rg]);
;     if (!anyPart && dead) mx = NEGB;
;     mx = __builtin_fmaxf(mx, __shfl_xor(mx, 32));
;     const float mnew = fmaxf(st.m, mx);
;     const float alpha = __builtin_amdgcn_exp2f(st.m - mnew);
;     st.m = mnew;
;     float sum = 0.f;
;     const float msub = (!anyPart && dead) ? 1e30f : mnew;
; #pragma unroll
;     for (int rg = 0; rg < 16; ++rg) { p0[rg] = __builtin_amdgcn_exp2f(p0[rg] - msub); p1[rg] = __builtin_amdgcn_exp2f(p1[rg] - msub); sum += p0[rg] + p1[rg]; }
;     st.l = st.l * alpha + sum;
;     if (__builtin_amdgcn_ballot_w64(alpha != 1.f) != 0ull) {
;         if (hi == 0) wsf[r] = alpha;
;         LDS_WAIT();
.LBB0_1185:
	s_nop 10
	v_max_f32_e32 v2, v50, v50
	v_max_f32_e32 v4, v66, v66
	v_max_f32_e32 v2, v4, v2
	v_max3_f32 v2, v2, v67, v51
	v_max3_f32 v2, v2, v68, v52
	v_max3_f32 v2, v2, v69, v53
	v_max3_f32 v2, v2, v70, v54
	v_max3_f32 v2, v2, v71, v55
	v_max3_f32 v2, v2, v72, v56
	v_max3_f32 v2, v2, v73, v57
	v_max3_f32 v2, v2, v74, v58
	v_max3_f32 v2, v2, v75, v59
	v_max3_f32 v2, v2, v76, v60
	v_max3_f32 v2, v2, v77, v61
	v_max3_f32 v2, v2, v78, v62
	v_max3_f32 v2, v2, v79, v63
	v_max3_f32 v2, v2, v80, v64
	v_max3_f32 v2, v2, v81, v65
	s_and_b64 s[82:83], s[82:83], s[16:17]
	v_cndmask_b32_e64 v2, v2, v217, s[82:83]
	v_mov_b32_e32 v4, v2
	v_mov_b32_e32 v5, v2
	s_nop 1
	v_permlane32_swap_b32_e32 v4, v5
	v_max3_f32 v2, v107, v4, v5
	v_sub_f32_e32 v4, v2, v107
	v_cmp_lt_f32_e32 vcc, 0x41000000, v4
	s_nop 1
	v_cndmask_b32_e32 v2, v107, v2, vcc
	v_sub_f32_e32 v4, v107, v2
	v_exp_f32_e32 v4, v4
	s_nop 0
	v_cmp_neq_f32_e32 vcc, 1.0, v4
	s_cbranch_vccz .LBB0_1180
	s_and_saveexec_b64 s[16:17], s[8:9]
	s_cbranch_execz .LBB0_1179
	ds_write_b32 v197, v4 offset:32768
	s_branch .LBB0_1179

; #define LAS __attribute__((address_space(3)))
; #define LDS_WAIT() asm volatile("s_waitcnt lgkmcnt(0)" ::: "memory")
; template <bool CMP> DI void tile_compute(LAS unsigned char* lds, int buf, const bf16x8 (&q)[4], int lo, int hv, ASt& st, f32x16& imp0, f32x16& imp1, int jt, LAS float* wsf, int lane) {
;     ...
;     float mx = __builtin_fmaxf(p0[0], p1[0]);
; #pragma unroll
;     for (int rg = 1; rg < 16; ++rg) mx = __builtin_fmaxf(__builtin_fmaxf(mx, p0[rg]), p1[rg]);
;     if (!anyPart && dead) mx = NEGB;
;     mx = __builtin_fmaxf(mx, __shfl_xor(mx, 32));
;     const float mnew = fmaxf(st.m, mx);
;     const float alpha = __builtin_amdgcn_exp2f(st.m - mnew);
;     st.m = mnew;
;     float sum = 0.f;
;     const float msub = (!anyPart && dead) ? 1e30f : mnew;
; #pragma unroll
;     for (int rg = 0; rg < 16; ++rg) { p0[rg] = __builtin_amdgcn_exp2f(p0[rg] - msub); p1[rg] = __builtin_amdgcn_exp2f(p1[rg] - msub); sum += p0[rg] + p1[rg]; }
;     st.l = st.l * alpha + sum;
;     if (__builtin_amdgcn_ballot_w64(alpha != 1.f) != 0ull) {
;         if (hi == 0) wsf[r] = alpha;
;         LDS_WAIT();
; #pragma unroll
;         for (int g4 = 0; g4 < 4; ++g4) { const f32x4 f = *(const LAS f32x4*)(wsf + 8 * g4 + 4 * hi);
; #pragma unroll
;             for (int k = 0; k < 4; ++k) { st.o0[4 * g4 + k] *= f[k]; st.o1[4 * g4 + k] *= f[k]; if (CMP) { imp0[4 * g4 + k] *= f[k]; imp1[4 * g4 + k] *= f[k]; } } }
.LBB0_1205:
	s_nop 10
	v_max_f32_e32 v79, v52, v52
	v_max_f32_e32 v80, v36, v36
	v_max_f32_e32 v79, v80, v79
	v_max3_f32 v79, v79, v37, v53
	v_max3_f32 v79, v79, v38, v54
	v_max3_f32 v79, v79, v39, v55
	v_max3_f32 v79, v79, v40, v56
	v_max3_f32 v79, v79, v41, v57
	v_max3_f32 v79, v79, v42, v58
	v_max3_f32 v79, v79, v43, v59
	v_max3_f32 v79, v79, v44, v60
	v_max3_f32 v79, v79, v45, v61
	v_max3_f32 v79, v79, v46, v62
	v_max3_f32 v79, v79, v47, v63
	v_max3_f32 v79, v79, v48, v64
	v_max3_f32 v79, v79, v49, v65
	v_max3_f32 v79, v79, v50, v66
	v_max3_f32 v79, v79, v51, v67
	s_and_b64 s[80:81], s[80:81], s[16:17]
	v_cndmask_b32_e64 v79, v79, v217, s[80:81]
	v_mov_b32_e32 v80, v79
	v_mov_b32_e32 v81, v79
	s_nop 1
	v_permlane32_swap_b32_e32 v80, v81
	v_max3_f32 v79, v78, v80, v81
	v_sub_f32_e32 v80, v79, v78
	v_cmp_lt_f32_e32 vcc, 0x41000000, v80
	s_nop 1
	v_cndmask_b32_e32 v79, v78, v79, vcc
	v_sub_f32_e32 v78, v78, v79
	v_exp_f32_e32 v78, v78
	s_nop 0
	v_cmp_neq_f32_e32 vcc, 1.0, v78
	s_cbranch_vccz .LBB0_1209
	s_and_saveexec_b64 s[16:17], s[8:9]
	ds_write_b32 v197, v78 offset:32768
	s_or_b64 exec, exec, s[16:17]
	s_waitcnt lgkmcnt(0)
	ds_read_b128 v[98:101], v119 offset:32864
	ds_read_b128 v[102:105], v119 offset:32832
	ds_read_b128 v[106:109], v119 offset:32800
	ds_read_b128 v[110:113], v119 offset:32768
	s_waitcnt lgkmcnt(0)
	s_waitcnt lgkmcnt(0)
	v_pk_mul_f32 v[32:33], v[32:33], v[98:99]
	v_pk_mul_f32 v[28:29], v[28:29], v[102:103]
	v_pk_mul_f32 v[24:25], v[24:25], v[106:107]
	v_pk_mul_f32 v[34:35], v[34:35], v[100:101]
	v_pk_mul_f32 v[30:31], v[30:31], v[104:105]
	v_pk_mul_f32 v[26:27], v[26:27], v[108:109]
	v_pk_mul_f32 v[22:23], v[22:23], v[112:113]
	v_pk_mul_f32 v[20:21], v[20:21], v[110:111]
	v_pk_mul_f32 v[16:17], v[16:17], v[98:99]
	v_pk_mul_f32 v[12:13], v[12:13], v[102:103]
	v_pk_mul_f32 v[8:9], v[8:9], v[106:107]
	v_pk_mul_f32 v[18:19], v[18:19], v[100:101]
	v_pk_mul_f32 v[14:15], v[14:15], v[104:105]
	v_pk_mul_f32 v[10:11], v[10:11], v[108:109]
	v_pk_mul_f32 v[6:7], v[6:7], v[112:113]
	v_pk_mul_f32 v[4:5], v[4:5], v[110:111]

; #define MFMA32(a, b, c) __builtin_amdgcn_mfma_f32_32x32x16_bf16((a), (b), (c), 0, 0, 0)
; DI void gla_stage3(const Ctx& c0, int layer, int unit, int cb, LAS unsigned char* lds) {
;     ...
;     const bf16* qgp = (const bf16*)(c.ws + O_QG) + (row0 + r) * 256 + h * 64 + 8 * hi;
;     const float* sp = (const float*)(c.ws + O_UPD) + (size_t)unit * 8192;
;     const float* gn = c.a->in[I_GNORM] + (size_t)layer * 128;
;     bf16x8 qf[4];
; #pragma unroll
;     for (int s = 0; s < 4; ++s) qf[s] = *(const bf16x8*)(qgp + 16 * s);
;     f32x16 o[4];
; #pragma unroll
;     for (int vb = 0; vb < 4; ++vb) {
;         o[vb] = f32x16{};
; #pragma unroll
;         for (int s = 0; s < 4; ++s) { const float* s0 = sp + (size_t)(16 * s + 8 * hi) * 128 + 32 * vb + r;
;             const bf16x8 bfv = pack8(s0[0], s0[128], s0[256], s0[384], s0[512], s0[640], s0[768], s0[896]);
;             o[vb] = MFMA32(qf[s], bfv, o[vb]); }
;         asm volatile("" ::: "memory");
;     }
.LBB0_1216:
	s_mov_b64 s[0:1], s[74:75]
	s_mov_b64 s[2:3], s[72:73]
	s_ashr_i32 s2, s34, 8
	s_ashr_i32 s3, s2, 31
	s_lshl_b64 s[2:3], s[2:3], 12
	s_and_b32 s9, s4, 0xfc0
	s_or_b32 s2, s2, s9
	s_or_b64 s[2:3], s[2:3], s[10:11]
	v_mov_b32_e32 v3, s3
	v_or_b32_e32 v2, s2, v152
	s_bfe_u32 s8, s34, 0x20006
	v_lshlrev_b64 v[2:3], 9, v[2:3]
	v_lshl_add_u64 v[2:3], s[0:1], 0, v[2:3]
	s_lshl_b32 s12, s8, 7
	v_lshl_add_u64 v[2:3], v[2:3], 0, s[12:13]
	v_lshl_add_u64 v[2:3], v[2:3], 0, v[86:87]
	v_lshl_add_u64 v[4:5], v[2:3], 0, s[18:19]
	v_add_co_u32_e32 v2, vcc, s6, v2
	v_lshl_add_u64 v[90:91], s[0:1], 0, v[84:85]
	s_nop 0
	v_addc_co_u32_e32 v3, vcc, 0, v3, vcc
	global_load_dwordx4 v[50:53], v[2:3], off
	global_load_dwordx4 v[110:113], v[4:5], off offset:96
	global_load_dwordx4 v[106:109], v[4:5], off offset:64
	global_load_dwordx4 v[102:105], v[4:5], off offset:32
	v_add_co_u32_e32 v2, vcc, s7, v90
	s_lshl_b64 s[2:3], s[2:3], 10
	s_nop 0
	v_addc_co_u32_e32 v3, vcc, -1, v91, vcc
	v_add_co_u32_e32 v58, vcc, s28, v90
	global_load_dword v2, v[2:3], off
	s_nop 0
	v_addc_co_u32_e32 v59, vcc, -1, v91, vcc
	global_load_dword v3, v[58:59], off offset:384
	global_load_dword v4, v[58:59], off offset:896
	global_load_dword v5, v[58:59], off offset:1408
	global_load_dword v6, v[58:59], off offset:1920
	global_load_dword v7, v[58:59], off offset:2432
	global_load_dword v8, v[58:59], off offset:2944
	global_load_dword v9, v[58:59], off offset:3456
	v_add_co_u32_e32 v18, vcc, s15, v90
	s_lshl_b32 s8, s8, 8
	s_nop 0
	v_addc_co_u32_e32 v19, vcc, -1, v91, vcc
	v_add_co_u32_e32 v114, vcc, s29, v90
	global_load_dword v18, v[18:19], off
	s_nop 0
	v_addc_co_u32_e32 v115, vcc, -1, v91, vcc
	global_load_dword v19, v[114:115], off offset:384
	global_load_dword v20, v[114:115], off offset:896
	global_load_dword v21, v[114:115], off offset:1408
	global_load_dword v22, v[114:115], off offset:1920
	global_load_dword v23, v[114:115], off offset:2432
	global_load_dword v24, v[114:115], off offset:2944
	global_load_dword v25, v[114:115], off offset:3456
	s_add_u32 s0, s0, s2
	s_addc_u32 s1, s1, s3
	s_add_u32 s0, s0, s8
	s_addc_u32 s1, s1, 0
	s_add_i32 s34, s34, s14
	s_add_i32 s4, s4, s5
	v_lshl_add_u64 v[84:85], v[84:85], 0, s[16:17]
	s_cmpk_lt_i32 s34, 0x800
	s_waitcnt vmcnt(0) lgkmcnt(0)
	global_load_dword v41, v[114:115], off offset:3584
	global_load_dword v40, v[114:115], off offset:3072
	global_load_dword v39, v[114:115], off offset:2560
	global_load_dword v38, v[114:115], off offset:2048
	global_load_dword v37, v[114:115], off offset:1536
	global_load_dword v36, v[114:115], off offset:1024
	global_load_dword v35, v[114:115], off offset:512
	global_load_dword v34, v[114:115], off
	global_load_dword v145, v[58:59], off offset:3584
	global_load_dword v146, v[58:59], off offset:3072
	global_load_dword v143, v[58:59], off offset:2560
	global_load_dword v144, v[58:59], off offset:2048
	global_load_dword v141, v[58:59], off offset:1536
	global_load_dword v142, v[58:59], off offset:1024
	global_load_dword v139, v[58:59], off offset:512
	global_load_dword v140, v[58:59], off
	v_cvt_pk_bf16_f32 v2, v2, v3
	v_cvt_pk_bf16_f32 v3, v4, v5
	v_cvt_pk_bf16_f32 v4, v6, v7
	v_cvt_pk_bf16_f32 v5, v8, v9
	v_cvt_pk_bf16_f32 v18, v18, v19
	s_nop 0
	v_mfma_f32_32x32x16_bf16 v[2:17], v[50:53], v[2:5], 0
	v_cvt_pk_bf16_f32 v19, v20, v21
	v_cvt_pk_bf16_f32 v20, v22, v23
	v_cvt_pk_bf16_f32 v21, v24, v25
	s_nop 1
	v_mfma_f32_32x32x16_bf16 v[2:17], v[102:105], v[18:21], v[2:17]
	v_add_co_u32_e32 v18, vcc, s26, v90
	s_nop 1
	v_addc_co_u32_e32 v19, vcc, -1, v91, vcc
	v_add_co_u32_e32 v118, vcc, s30, v90
	global_load_dword v18, v[18:19], off
	s_nop 0
	v_addc_co_u32_e32 v119, vcc, -1, v91, vcc
	global_load_dword v19, v[118:119], off offset:384
	global_load_dword v20, v[118:119], off offset:896
	global_load_dword v21, v[118:119], off offset:1408
	global_load_dword v22, v[118:119], off offset:1920
	global_load_dword v23, v[118:119], off offset:2432
	global_load_dword v24, v[118:119], off offset:2944
	global_load_dword v25, v[118:119], off offset:3456
	s_waitcnt vmcnt(0) lgkmcnt(0)
	global_load_dword v63, v[114:115], off offset:3712
	global_load_dword v62, v[114:115], off offset:3200
	global_load_dword v61, v[114:115], off offset:2688
	global_load_dword v60, v[114:115], off offset:2176
	global_load_dword v57, v[114:115], off offset:1664
	global_load_dword v56, v[114:115], off offset:1152
	global_load_dword v55, v[114:115], off offset:640
	global_load_dword v54, v[114:115], off offset:128
	global_load_dword v173, v[58:59], off offset:3712
	global_load_dword v176, v[58:59], off offset:3200
	global_load_dword v171, v[58:59], off offset:2688
	global_load_dword v174, v[58:59], off offset:2176
	global_load_dword v169, v[58:59], off offset:1664
	global_load_dword v172, v[58:59], off offset:1152
	global_load_dword v167, v[58:59], off offset:640
	global_load_dword v170, v[58:59], off offset:128
	global_load_dword v157, v[118:119], off offset:3584
	global_load_dword v160, v[118:119], off offset:3072
	global_load_dword v155, v[118:119], off offset:2560
	global_load_dword v158, v[118:119], off offset:2048
	global_load_dword v149, v[118:119], off offset:1536
	global_load_dword v156, v[118:119], off offset:1024
	global_load_dword v147, v[118:119], off offset:512
	global_load_dword v148, v[118:119], off
	v_cvt_pk_bf16_f32 v18, v18, v19
	v_cvt_pk_bf16_f32 v19, v20, v21
	v_cvt_pk_bf16_f32 v20, v22, v23
	v_cvt_pk_bf16_f32 v21, v24, v25
	s_nop 1
	v_mfma_f32_32x32x16_bf16 v[2:17], v[106:109], v[18:21], v[2:17]
	v_add_co_u32_e32 v18, vcc, s27, v90
	s_nop 1
	v_addc_co_u32_e32 v19, vcc, -1, v91, vcc
	v_add_co_u32_e32 v120, vcc, s31, v90
	global_load_dword v18, v[18:19], off
	s_nop 0
	v_addc_co_u32_e32 v121, vcc, -1, v91, vcc
	global_load_dword v19, v[120:121], off offset:384
	global_load_dword v20, v[120:121], off offset:896
	global_load_dword v21, v[120:121], off offset:1408
	global_load_dword v22, v[120:121], off offset:1920
	global_load_dword v23, v[120:121], off offset:2432
	global_load_dword v24, v[120:121], off offset:2944
	global_load_dword v25, v[120:121], off offset:3456
	v_cmp_lt_i32_e32 vcc, v94, v95
	s_waitcnt vmcnt(0) lgkmcnt(0)
; #define MFMA32(a, b, c) __builtin_amdgcn_mfma_f32_32x32x16_bf16((a), (b), (c), 0, 0, 0)
; DI void gla_stage3(const Ctx& c0, int layer, int unit, int cb, LAS unsigned char* lds) {
;     ...
;     for (int vb = 0; vb < 4; ++vb) {
;         o[vb] = f32x16{};
; #pragma unroll
;         for (int s = 0; s < 4; ++s) { const float* s0 = sp + (size_t)(16 * s + 8 * hi) * 128 + 32 * vb + r;
;             const bf16x8 bfv = pack8(s0[0], s0[128], s0[256], s0[384], s0[512], s0[640], s0[768], s0[896]);
;             o[vb] = MFMA32(qf[s], bfv, o[vb]); }
;         asm volatile("" ::: "memory");
;     }
	global_load_dword v127, v[114:115], off offset:3840
	global_load_dword v126, v[114:115], off offset:3328
	global_load_dword v125, v[114:115], off offset:2816
	global_load_dword v124, v[114:115], off offset:2304
	global_load_dword v123, v[114:115], off offset:1792
	global_load_dword v122, v[114:115], off offset:1280
	global_load_dword v117, v[114:115], off offset:768
	global_load_dword v116, v[114:115], off offset:256
	global_load_dword v214, v[58:59], off offset:3840
	global_load_dword v212, v[58:59], off offset:3328
	global_load_dword v205, v[58:59], off offset:2816
	global_load_dword v210, v[58:59], off offset:2304
	global_load_dword v203, v[58:59], off offset:1792
	global_load_dword v208, v[58:59], off offset:1280
	global_load_dword v201, v[58:59], off offset:768
	global_load_dword v206, v[58:59], off offset:256
	global_load_dword v199, v[120:121], off offset:3712
	global_load_dword v204, v[120:121], off offset:3200
	global_load_dword v197, v[120:121], off offset:2688
	global_load_dword v202, v[120:121], off offset:2176
	global_load_dword v195, v[120:121], off offset:1664
	global_load_dword v200, v[120:121], off offset:1152
	global_load_dword v183, v[120:121], off offset:640
	global_load_dword v198, v[120:121], off offset:128
	global_load_dword v181, v[118:119], off offset:3712
	global_load_dword v196, v[118:119], off offset:3200
	global_load_dword v179, v[118:119], off offset:2688
	global_load_dword v182, v[118:119], off offset:2176
	global_load_dword v177, v[118:119], off offset:1664
	global_load_dword v180, v[118:119], off offset:1152
	global_load_dword v175, v[118:119], off offset:640
	global_load_dword v178, v[118:119], off offset:128
	global_load_dword v165, v[120:121], off offset:3584
	global_load_dword v168, v[120:121], off offset:3072
	global_load_dword v163, v[120:121], off offset:2560
	global_load_dword v166, v[120:121], off offset:2048
	global_load_dword v161, v[120:121], off offset:1536
	global_load_dword v164, v[120:121], off offset:1024
	global_load_dword v159, v[120:121], off offset:512
	global_load_dword v162, v[120:121], off
	v_cvt_pk_bf16_f32 v18, v18, v19
	v_cvt_pk_bf16_f32 v19, v20, v21
	v_cvt_pk_bf16_f32 v20, v22, v23
	v_cvt_pk_bf16_f32 v21, v24, v25
	s_nop 1
	v_mfma_f32_32x32x16_bf16 v[2:17], v[110:113], v[18:21], v[2:17]
	s_waitcnt vmcnt(40) lgkmcnt(0)
	global_load_dword v238, v[82:83], off offset:896
	global_load_dword v236, v[82:83], off offset:768
	global_load_dword v234, v[82:83], off offset:640
	global_load_dword v232, v[82:83], off offset:512
	global_load_dword v90, v[90:91], off
	global_load_dword v230, v[120:121], off offset:3328
	global_load_dword v219, v[120:121], off offset:2816
	global_load_dword v228, v[120:121], off offset:2304
	global_load_dword v217, v[120:121], off offset:1792
	global_load_dword v226, v[120:121], off offset:1280
	global_load_dword v215, v[120:121], off offset:768
	global_load_dword v224, v[120:121], off offset:256
	global_load_dword v213, v[118:119], off offset:3840
	global_load_dword v222, v[118:119], off offset:3328
	global_load_dword v211, v[118:119], off offset:2816
	global_load_dword v220, v[118:119], off offset:2304
	global_load_dword v209, v[118:119], off offset:1792
	global_load_dword v218, v[118:119], off offset:1280
	global_load_dword v207, v[118:119], off offset:768
	global_load_dword v216, v[118:119], off offset:256
	v_cvt_pk_bf16_f32 v18, v140, v139
	v_cvt_pk_bf16_f32 v34, v34, v35
	v_cvt_pk_bf16_f32 v19, v142, v141
	v_cvt_pk_bf16_f32 v35, v36, v37
	v_cvt_pk_bf16_f32 v20, v144, v143
	v_cvt_pk_bf16_f32 v36, v38, v39
	v_cvt_pk_bf16_f32 v21, v146, v145
	v_cvt_pk_bf16_f32 v37, v40, v41
	s_nop 0
	v_mfma_f32_32x32x16_bf16 v[18:33], v[50:53], v[18:21], 0
	v_mfma_f32_32x32x16_bf16 v[18:33], v[102:105], v[34:37], v[18:33]
	s_waitcnt vmcnt(60) lgkmcnt(0)
	v_cvt_pk_bf16_f32 v34, v148, v147
	v_cvt_pk_bf16_f32 v35, v156, v149
	v_cvt_pk_bf16_f32 v36, v158, v155
	v_cvt_pk_bf16_f32 v37, v160, v157
	s_nop 1
	v_mfma_f32_32x32x16_bf16 v[18:33], v[106:109], v[34:37], v[18:33]
	s_waitcnt vmcnt(20) lgkmcnt(0)
	v_cvt_pk_bf16_f32 v34, v162, v159
	v_cvt_pk_bf16_f32 v35, v164, v161
	v_cvt_pk_bf16_f32 v36, v166, v163
	v_cvt_pk_bf16_f32 v37, v168, v165
	s_nop 1
	v_mfma_f32_32x32x16_bf16 v[18:33], v[110:113], v[34:37], v[18:33]
	s_waitcnt vmcnt(62) lgkmcnt(0)
	v_cvt_pk_bf16_f32 v34, v170, v167
	v_cvt_pk_bf16_f32 v54, v54, v55
	v_cvt_pk_bf16_f32 v35, v172, v169
	v_cvt_pk_bf16_f32 v55, v56, v57
	v_cvt_pk_bf16_f32 v36, v174, v171
	v_cvt_pk_bf16_f32 v56, v60, v61
	v_cvt_pk_bf16_f32 v37, v176, v173
	v_cvt_pk_bf16_f32 v57, v62, v63
	s_nop 0
	v_mfma_f32_32x32x16_bf16 v[34:49], v[50:53], v[34:37], 0
	v_mfma_f32_32x32x16_bf16 v[34:49], v[102:105], v[54:57], v[34:49]
	s_waitcnt vmcnt(28) lgkmcnt(0)
	v_cvt_pk_bf16_f32 v54, v178, v175
	v_cvt_pk_bf16_f32 v55, v180, v177
	v_cvt_pk_bf16_f32 v56, v182, v179
	v_cvt_pk_bf16_f32 v57, v196, v181
	s_nop 1
	v_mfma_f32_32x32x16_bf16 v[34:49], v[106:109], v[54:57], v[34:49]
	s_waitcnt vmcnt(36) lgkmcnt(0)
	v_cvt_pk_bf16_f32 v54, v198, v183
	v_cvt_pk_bf16_f32 v55, v200, v195
	v_cvt_pk_bf16_f32 v56, v202, v197
	v_cvt_pk_bf16_f32 v57, v204, v199
	s_nop 1
	v_mfma_f32_32x32x16_bf16 v[34:49], v[110:113], v[54:57], v[34:49]
	s_nop 0
	s_nop 0
	s_waitcnt vmcnt(44) lgkmcnt(0)
	v_cvt_pk_bf16_f32 v54, v206, v201
	v_cvt_pk_bf16_f32 v114, v116, v117
	v_cvt_pk_bf16_f32 v55, v208, v203
	v_cvt_pk_bf16_f32 v115, v122, v123
	v_cvt_pk_bf16_f32 v56, v210, v205
	v_cvt_pk_bf16_f32 v116, v124, v125
	v_cvt_pk_bf16_f32 v57, v212, v214
	v_cvt_pk_bf16_f32 v117, v126, v127
	s_nop 0
	v_mfma_f32_32x32x16_bf16 v[50:65], v[50:53], v[54:57], 0
	v_mfma_f32_32x32x16_bf16 v[50:65], v[102:105], v[114:117], v[50:65]
	s_waitcnt vmcnt(0) lgkmcnt(0)
; #define LAS __attribute__((address_space(3)))
; #define LDS_WAIT() asm volatile("s_waitcnt lgkmcnt(0)" ::: "memory")
; DI float bf2f(bf16 b) { return __uint_as_float(((unsigned)b) << 16); }
; DI void g3_tile_in(const bf16* g, LAS unsigned char* R, int lane) {
; #pragma unroll
;     for (int it = 0; it < 8; ++it) { const int row = 4 * it + (lane >> 4), ch = lane & 15;
;         *(LAS u32x4*)(R + row * G3_PITCH + ch * 16) = *(const u32x4*)(g + (size_t)row * 512 + ch * 8); }
;     LDS_WAIT();
; }
; DI void gla_stage3(const Ctx& c0, int layer, int unit, int cb, LAS unsigned char* lds) {
;     ...
;     g3_tile_in((const bf16*)(c.ws + O_OINTRA) + row0 * 512 + h * 128, R, lane);
; #pragma unroll
;     for (int vb = 0; vb < 4; ++vb) {
; #pragma unroll
;         for (int rg = 0; rg < 16; ++rg) o[vb][rg] += bf2f(*(const LAS bf16*)(Re + ((rg & 3) + 8 * (rg >> 2)) * G3_PITCH + 64 * vb));
	v_cvt_pk_bf16_f32 v102, v216, v207
	v_cvt_pk_bf16_f32 v103, v218, v209
	v_cvt_pk_bf16_f32 v104, v220, v211
	v_cvt_pk_bf16_f32 v105, v222, v213
	s_nop 1
	v_mfma_f32_32x32x16_bf16 v[50:65], v[106:109], v[102:105], v[50:65]
	s_nop 0
	s_waitcnt vmcnt(8) lgkmcnt(0)
	v_cvt_pk_bf16_f32 v102, v224, v215
	v_cvt_pk_bf16_f32 v103, v226, v217
	v_cvt_pk_bf16_f32 v104, v228, v219
	v_cvt_pk_bf16_f32 v105, v230, v90
	v_lshl_add_u64 v[90:91], s[0:1], 0, v[88:89]
	v_lshl_add_u64 v[106:107], v[90:91], 0, s[20:21]
	v_mfma_f32_32x32x16_bf16 v[50:65], v[110:113], v[102:105], v[50:65]
	v_lshl_add_u64 v[102:103], v[106:107], 0, v[66:67]
	global_load_dwordx4 v[102:105], v[102:103], off
	s_waitcnt vmcnt(0) lgkmcnt(0)
	v_lshl_add_u64 v[168:169], v[90:91], 0, s[22:23]
	v_lshl_add_u64 v[140:141], v[168:169], 0, v[70:71]
	global_load_dwordx4 v[174:177], v[140:141], off
	v_lshl_add_u64 v[140:141], v[106:107], 0, v[70:71]
	global_load_dwordx4 v[146:149], v[140:141], off
	v_lshl_add_u64 v[144:145], v[106:107], 0, v[68:69]
	global_load_dwordx4 v[140:143], v[144:145], off
	ds_write_b128 v92, v[102:105]
	s_waitcnt vmcnt(0) lgkmcnt(0)
	v_lshl_add_u64 v[144:145], v[168:169], 0, v[76:77]
	global_load_dwordx4 v[200:203], v[144:145], off
	v_lshl_add_u64 v[144:145], v[168:169], 0, v[74:75]
	global_load_dwordx4 v[196:199], v[144:145], off
	v_lshl_add_u64 v[144:145], v[168:169], 0, v[72:73]
	global_load_dwordx4 v[178:181], v[144:145], off
	v_lshl_add_u64 v[144:145], v[106:107], 0, v[74:75]
	global_load_dwordx4 v[156:159], v[144:145], off
	v_lshl_add_u64 v[102:103], v[106:107], 0, v[72:73]
	global_load_dwordx4 v[102:105], v[102:103], off
	ds_write_b128 v92, v[140:143] offset:1088
	s_waitcnt vmcnt(5) lgkmcnt(0)
	v_lshl_add_u64 v[140:141], v[168:169], 0, v[78:79]
	global_load_dwordx4 v[204:207], v[140:141], off
	v_lshl_add_u64 v[140:141], v[106:107], 0, v[78:79]
	global_load_dwordx4 v[160:163], v[140:141], off
	v_lshl_add_u64 v[144:145], v[106:107], 0, v[76:77]
	global_load_dwordx4 v[140:143], v[144:145], off
	ds_write_b128 v92, v[146:149] offset:2176
	s_waitcnt vmcnt(3) lgkmcnt(0)
	v_lshl_add_u64 v[144:145], v[168:169], 0, v[66:67]
	global_load_dwordx4 v[164:167], v[144:145], off
	v_lshl_add_u64 v[148:149], v[106:107], 0, v[80:81]
	global_load_dwordx4 v[144:147], v[148:149], off
	ds_write_b128 v92, v[102:105] offset:3264
	s_waitcnt vmcnt(6) lgkmcnt(0)
	v_lshl_add_u64 v[148:149], v[168:169], 0, v[68:69]
	global_load_dwordx4 v[170:173], v[148:149], off
	ds_write_b128 v92, v[156:159] offset:4352
	s_waitcnt vmcnt(3) lgkmcnt(0)
	ds_write_b128 v92, v[140:143] offset:5440
	s_waitcnt vmcnt(4) lgkmcnt(0)
	ds_write_b128 v92, v[160:163] offset:6528
	s_waitcnt vmcnt(1) lgkmcnt(0)
	ds_write_b128 v92, v[144:147] offset:7616
	s_waitcnt lgkmcnt(0)
	ds_read_u16 v102, v1
	s_waitcnt lgkmcnt(0)
	v_lshlrev_b32_e32 v102, 16, v102
	v_add_f32_e32 v138, v2, v102
	ds_read_u16 v2, v1 offset:272
	s_waitcnt lgkmcnt(0)
	v_lshlrev_b32_e32 v2, 16, v2
	v_add_f32_e32 v137, v3, v2
	ds_read_u16 v2, v1 offset:544
	s_waitcnt lgkmcnt(0)
	v_lshlrev_b32_e32 v2, 16, v2
	v_add_f32_e32 v136, v4, v2
	ds_read_u16 v2, v1 offset:816
	s_waitcnt lgkmcnt(0)
	v_lshlrev_b32_e32 v2, 16, v2
	v_add_f32_e32 v135, v5, v2
	ds_read_u16 v2, v1 offset:2176
	s_waitcnt lgkmcnt(0)
	v_lshlrev_b32_e32 v2, 16, v2
	v_add_f32_e32 v134, v6, v2
	ds_read_u16 v2, v1 offset:2448
	s_waitcnt lgkmcnt(0)
	v_lshlrev_b32_e32 v2, 16, v2
	v_add_f32_e32 v133, v7, v2
	ds_read_u16 v2, v1 offset:2720
	s_waitcnt lgkmcnt(0)
	v_lshlrev_b32_e32 v2, 16, v2
	v_add_f32_e32 v132, v8, v2
	ds_read_u16 v2, v1 offset:2992
	s_waitcnt lgkmcnt(0)
	v_lshlrev_b32_e32 v2, 16, v2
	v_add_f32_e32 v131, v9, v2
	ds_read_u16 v2, v1 offset:4352
	s_waitcnt lgkmcnt(0)
	v_lshlrev_b32_e32 v2, 16, v2
	v_add_f32_e32 v130, v10, v2
	ds_read_u16 v2, v1 offset:4624
	s_waitcnt lgkmcnt(0)
	v_lshlrev_b32_e32 v2, 16, v2
	v_add_f32_e32 v129, v11, v2
	ds_read_u16 v2, v1 offset:4896
	s_waitcnt lgkmcnt(0)
	v_lshlrev_b32_e32 v2, 16, v2
	v_add_f32_e32 v128, v12, v2
	ds_read_u16 v2, v1 offset:5168
	s_waitcnt lgkmcnt(0)
	v_lshlrev_b32_e32 v2, 16, v2
	v_add_f32_e32 v127, v13, v2
	ds_read_u16 v2, v1 offset:6528
	s_waitcnt lgkmcnt(0)
	v_lshlrev_b32_e32 v2, 16, v2
	v_add_f32_e32 v126, v14, v2
	ds_read_u16 v2, v1 offset:6800
	s_waitcnt lgkmcnt(0)
	v_lshlrev_b32_e32 v2, 16, v2
	v_add_f32_e32 v125, v15, v2
	ds_read_u16 v2, v1 offset:7072
	s_waitcnt lgkmcnt(0)
	v_lshlrev_b32_e32 v2, 16, v2
	v_add_f32_e32 v124, v16, v2
	ds_read_u16 v2, v1 offset:7344
	s_waitcnt lgkmcnt(0)
	v_lshlrev_b32_e32 v2, 16, v2
	v_add_f32_e32 v123, v17, v2
	ds_read_u16 v2, v1 offset:64
	s_waitcnt lgkmcnt(0)
	v_lshlrev_b32_e32 v2, 16, v2
	v_add_f32_e32 v122, v18, v2
	ds_read_u16 v2, v1 offset:336
	s_waitcnt lgkmcnt(0)
	v_lshlrev_b32_e32 v2, 16, v2
	v_add_f32_e32 v121, v19, v2
	ds_read_u16 v2, v1 offset:608
	s_waitcnt lgkmcnt(0)
	v_lshlrev_b32_e32 v2, 16, v2
	v_add_f32_e32 v120, v20, v2
	ds_read_u16 v2, v1 offset:880
	s_waitcnt lgkmcnt(0)
	v_lshlrev_b32_e32 v2, 16, v2
	v_add_f32_e32 v119, v21, v2
	ds_read_u16 v2, v1 offset:2240
	s_waitcnt lgkmcnt(0)
	v_lshlrev_b32_e32 v2, 16, v2
	v_add_f32_e32 v118, v22, v2
	ds_read_u16 v2, v1 offset:2512
	s_waitcnt lgkmcnt(0)
	v_lshlrev_b32_e32 v2, 16, v2
	v_add_f32_e32 v117, v23, v2
	ds_read_u16 v2, v1 offset:2784
	s_waitcnt lgkmcnt(0)
	v_lshlrev_b32_e32 v2, 16, v2
	v_add_f32_e32 v116, v24, v2
	ds_read_u16 v2, v1 offset:3056
	s_waitcnt lgkmcnt(0)
	v_lshlrev_b32_e32 v2, 16, v2
	v_add_f32_e32 v115, v25, v2
	ds_read_u16 v2, v1 offset:4416
	s_waitcnt lgkmcnt(0)
	v_lshlrev_b32_e32 v2, 16, v2
	v_add_f32_e32 v114, v26, v2
	ds_read_u16 v2, v1 offset:4688
	s_waitcnt lgkmcnt(0)
; #define LAS __attribute__((address_space(3)))
; DI float bf2f(bf16 b) { return __uint_as_float(((unsigned)b) << 16); }
; DI void gla_stage3(const Ctx& c0, int layer, int unit, int cb, LAS unsigned char* lds) {
;     ...
;     for (int vb = 0; vb < 4; ++vb) {
; #pragma unroll
;         for (int rg = 0; rg < 16; ++rg) o[vb][rg] += bf2f(*(const LAS bf16*)(Re + ((rg & 3) + 8 * (rg >> 2)) * G3_PITCH + 64 * vb));
;         asm volatile("" ::: "memory");
	v_lshlrev_b32_e32 v2, 16, v2
	v_add_f32_e32 v113, v27, v2
	ds_read_u16 v2, v1 offset:4960
	s_waitcnt lgkmcnt(0)
	v_lshlrev_b32_e32 v2, 16, v2
	v_add_f32_e32 v112, v28, v2
	ds_read_u16 v2, v1 offset:5232
	s_waitcnt lgkmcnt(0)
	v_lshlrev_b32_e32 v2, 16, v2
	v_add_f32_e32 v111, v29, v2
	ds_read_u16 v2, v1 offset:6592
	s_waitcnt lgkmcnt(0)
	v_lshlrev_b32_e32 v2, 16, v2
	v_add_f32_e32 v110, v30, v2
	ds_read_u16 v2, v1 offset:6864
	s_waitcnt lgkmcnt(0)
	v_lshlrev_b32_e32 v2, 16, v2
	v_add_f32_e32 v109, v31, v2
	ds_read_u16 v2, v1 offset:7136
	s_waitcnt lgkmcnt(0)
	v_lshlrev_b32_e32 v2, 16, v2
	v_add_f32_e32 v108, v32, v2
	ds_read_u16 v2, v1 offset:7408
	s_waitcnt lgkmcnt(0)
	v_lshlrev_b32_e32 v2, 16, v2
	v_add_f32_e32 v107, v33, v2
	ds_read_u16 v2, v1 offset:128
	s_waitcnt lgkmcnt(0)
	v_lshlrev_b32_e32 v2, 16, v2
	v_add_f32_e32 v106, v34, v2
	ds_read_u16 v2, v1 offset:400
	s_waitcnt lgkmcnt(0)
	v_lshlrev_b32_e32 v2, 16, v2
	v_add_f32_e32 v105, v35, v2
	ds_read_u16 v2, v1 offset:672
	s_waitcnt lgkmcnt(0)
	v_lshlrev_b32_e32 v2, 16, v2
	v_add_f32_e32 v104, v36, v2
	ds_read_u16 v2, v1 offset:944
	s_waitcnt lgkmcnt(0)
	v_lshlrev_b32_e32 v2, 16, v2
	v_add_f32_e32 v103, v37, v2
	ds_read_u16 v2, v1 offset:2304
	s_waitcnt lgkmcnt(0)
	v_lshlrev_b32_e32 v2, 16, v2
	v_add_f32_e32 v102, v38, v2
	ds_read_u16 v2, v1 offset:2576
	s_waitcnt lgkmcnt(0)
	v_lshlrev_b32_e32 v2, 16, v2
	v_add_f32_e32 v39, v39, v2
	ds_read_u16 v2, v1 offset:2848
	s_waitcnt lgkmcnt(0)
	v_lshlrev_b32_e32 v2, 16, v2
	v_add_f32_e32 v38, v40, v2
	ds_read_u16 v2, v1 offset:3120
	s_waitcnt lgkmcnt(0)
	v_lshlrev_b32_e32 v2, 16, v2
	v_add_f32_e32 v37, v41, v2
	ds_read_u16 v2, v1 offset:4480
	s_waitcnt lgkmcnt(0)
	v_lshlrev_b32_e32 v2, 16, v2
	v_add_f32_e32 v36, v42, v2
	ds_read_u16 v2, v1 offset:4752
	s_waitcnt lgkmcnt(0)
	v_lshlrev_b32_e32 v2, 16, v2
	v_add_f32_e32 v34, v43, v2
	ds_read_u16 v2, v1 offset:5024
	s_waitcnt lgkmcnt(0)
	v_lshlrev_b32_e32 v2, 16, v2
	v_add_f32_e32 v33, v44, v2
	ds_read_u16 v2, v1 offset:5296
	s_waitcnt lgkmcnt(0)
	v_lshlrev_b32_e32 v2, 16, v2
	v_add_f32_e32 v32, v45, v2
	ds_read_u16 v2, v1 offset:6656
	s_waitcnt lgkmcnt(0)
	v_lshlrev_b32_e32 v2, 16, v2
	v_add_f32_e32 v30, v46, v2
	ds_read_u16 v2, v1 offset:6928
	s_waitcnt lgkmcnt(0)
	v_lshlrev_b32_e32 v2, 16, v2
	v_add_f32_e32 v29, v47, v2
	ds_read_u16 v2, v1 offset:7200
	s_waitcnt lgkmcnt(0)
	v_lshlrev_b32_e32 v2, 16, v2
	v_add_f32_e32 v28, v48, v2
	ds_read_u16 v2, v1 offset:7472
	s_waitcnt lgkmcnt(0)
	v_lshlrev_b32_e32 v2, 16, v2
	v_add_f32_e32 v26, v49, v2
	ds_read_u16 v2, v1 offset:192
	s_waitcnt lgkmcnt(0)
	v_lshlrev_b32_e32 v2, 16, v2
	v_add_f32_e32 v19, v50, v2
	ds_read_u16 v2, v1 offset:464
	s_waitcnt lgkmcnt(0)
	v_lshlrev_b32_e32 v2, 16, v2
	v_add_f32_e32 v18, v51, v2
	ds_read_u16 v2, v1 offset:736
	s_waitcnt lgkmcnt(0)
	v_lshlrev_b32_e32 v2, 16, v2
	v_add_f32_e32 v17, v52, v2
	ds_read_u16 v2, v1 offset:1008
	s_waitcnt lgkmcnt(0)
	v_lshlrev_b32_e32 v2, 16, v2
	v_add_f32_e32 v16, v53, v2
	ds_read_u16 v2, v1 offset:2368
	s_waitcnt lgkmcnt(0)
	v_lshlrev_b32_e32 v2, 16, v2
	v_add_f32_e32 v15, v54, v2
	ds_read_u16 v2, v1 offset:2640
	s_waitcnt lgkmcnt(0)
	v_lshlrev_b32_e32 v2, 16, v2
	v_add_f32_e32 v14, v55, v2
	ds_read_u16 v2, v1 offset:2912
	s_waitcnt lgkmcnt(0)
	v_lshlrev_b32_e32 v2, 16, v2
	v_add_f32_e32 v13, v56, v2
	ds_read_u16 v2, v1 offset:3184
	s_waitcnt lgkmcnt(0)
	v_lshlrev_b32_e32 v2, 16, v2
	v_add_f32_e32 v12, v57, v2
	ds_read_u16 v2, v1 offset:4544
	s_waitcnt lgkmcnt(0)
	v_lshlrev_b32_e32 v2, 16, v2
	v_add_f32_e32 v11, v58, v2
	ds_read_u16 v2, v1 offset:4816
	s_waitcnt lgkmcnt(0)
	v_lshlrev_b32_e32 v2, 16, v2
	v_add_f32_e32 v10, v59, v2
	ds_read_u16 v2, v1 offset:5088
	s_waitcnt lgkmcnt(0)
	v_lshlrev_b32_e32 v2, 16, v2
	v_add_f32_e32 v9, v60, v2
	ds_read_u16 v2, v1 offset:5360
	s_waitcnt lgkmcnt(0)
	v_lshlrev_b32_e32 v2, 16, v2
	v_add_f32_e32 v8, v61, v2
	ds_read_u16 v2, v1 offset:6720
	s_waitcnt lgkmcnt(0)
	v_lshlrev_b32_e32 v2, 16, v2
	v_add_f32_e32 v7, v62, v2
	ds_read_u16 v2, v1 offset:6992
	s_waitcnt lgkmcnt(0)
	v_lshlrev_b32_e32 v2, 16, v2
	v_add_f32_e32 v6, v63, v2
	ds_read_u16 v2, v1 offset:7264
	s_waitcnt lgkmcnt(0)
	v_lshlrev_b32_e32 v2, 16, v2
	v_add_f32_e32 v5, v64, v2
	ds_read_u16 v2, v1 offset:7536
	s_waitcnt lgkmcnt(0)
	s_waitcnt lgkmcnt(0)
; DI void gla_stage3(const Ctx& c0, int layer, int unit, int cb, LAS unsigned char* lds) {
;     ...
;     float rs[16];
; #pragma unroll
;     for (int rg = 0; rg < 16; ++rg) { float ss = o[0][rg] * o[0][rg] + o[1][rg] * o[1][rg] + o[2][rg] * o[2][rg] + o[3][rg] * o[3][rg];
;         ss += __shfl_xor(ss, 1); ss += __shfl_xor(ss, 2); ss += __shfl_xor(ss, 4); ss += __shfl_xor(ss, 8); ss += __shfl_xor(ss, 16);
;         rs[rg] = 1.f / sqrtf(ss * (1.f / 128.f) + EPS); }
	v_lshlrev_b32_e32 v2, 16, v2
	v_add_f32_e32 v4, v65, v2
	v_cndmask_b32_e32 v2, v93, v94, vcc
	v_cmp_lt_i32_e32 vcc, v96, v95
	v_lshlrev_b32_e32 v2, 2, v2
	s_nop 0
	v_cndmask_b32_e32 v3, v93, v96, vcc
	v_cmp_lt_i32_e32 vcc, v97, v95
	v_lshlrev_b32_e32 v3, 2, v3
	s_nop 0
	v_cndmask_b32_e32 v20, v93, v97, vcc
	v_cmp_lt_i32_e32 vcc, v98, v95
	v_lshlrev_b32_e32 v20, 2, v20
	s_nop 0
	v_cndmask_b32_e32 v21, v93, v98, vcc
	v_cmp_lt_i32_e32 vcc, v99, v95
	v_lshlrev_b32_e32 v47, 2, v21
	s_nop 0
	v_cndmask_b32_e32 v21, v93, v99, vcc
	v_lshlrev_b32_e32 v48, 2, v21
	v_mul_f32_e32 v21, v122, v122
	v_fmac_f32_e32 v21, v138, v138
	v_fmac_f32_e32 v21, v106, v106
	v_fmac_f32_e32 v21, v19, v19
	s_nop 1
	v_add_f32_dpp v21, v21, v21 quad_perm:[1,0,3,2] row_mask:0xf bank_mask:0xf
	s_nop 1
	v_add_f32_dpp v21, v21, v21 quad_perm:[2,3,0,1] row_mask:0xf bank_mask:0xf
	s_nop 1
	v_add_f32_dpp v21, v21, v21 row_half_mirror row_mask:0xf bank_mask:0xf
	s_nop 1
	v_add_f32_dpp v21, v21, v21 row_mirror row_mask:0xf bank_mask:0xf
	v_mov_b32_e32 v22, v21
	v_mov_b32_e32 v23, v21
	s_nop 1
	v_permlane16_swap_b32_e32 v22, v23
	v_add_f32_e32 v21, v22, v23
	v_fmamk_f32 v21, v21, 0x3c000000, v100
	v_cmp_gt_f32_e32 vcc, s33, v21
	v_mul_f32_e32 v22, 0x4f800000, v21
	s_nop 0
	v_cndmask_b32_e32 v21, v21, v22, vcc
	v_sqrt_f32_e32 v22, v21
	s_nop 0
	v_add_u32_e32 v23, -1, v22
	v_fma_f32 v24, -v23, v22, v21
	v_cmp_ge_f32_e64 s[8:9], 0, v24
	v_add_u32_e32 v24, 1, v22
	s_nop 0
	v_cndmask_b32_e64 v23, v22, v23, s[8:9]
	v_fma_f32 v22, -v24, v22, v21
	v_cmp_lt_f32_e64 s[8:9], 0, v22
	s_nop 1
	v_cndmask_b32_e64 v22, v23, v24, s[8:9]
	v_mul_f32_e32 v23, 0x37800000, v22
	v_cndmask_b32_e32 v22, v22, v23, vcc
	v_cmp_class_f32_e32 vcc, v21, v101
	s_nop 1
	v_cndmask_b32_e32 v21, v22, v21, vcc
	s_nop 0
	v_div_scale_f32 v24, vcc, 1.0, v21, 1.0
	v_rcp_f32_e32 v46, v21
	v_mul_f32_e32 v21, v121, v121
	v_fmac_f32_e32 v21, v137, v137
	v_fmac_f32_e32 v21, v105, v105
	v_fmac_f32_e32 v21, v18, v18
	s_nop 1
	v_add_f32_dpp v21, v21, v21 quad_perm:[1,0,3,2] row_mask:0xf bank_mask:0xf
	v_mul_f32_e32 v19, v19, v46
	s_nop 1
	v_add_f32_dpp v21, v21, v21 quad_perm:[2,3,0,1] row_mask:0xf bank_mask:0xf
	s_nop 1
	v_add_f32_dpp v21, v21, v21 row_half_mirror row_mask:0xf bank_mask:0xf
	s_nop 1
	v_add_f32_dpp v21, v21, v21 row_mirror row_mask:0xf bank_mask:0xf
	v_mov_b32_e32 v22, v21
	v_mov_b32_e32 v23, v21
	s_nop 1
	v_permlane16_swap_b32_e32 v22, v23
	v_add_f32_e32 v21, v22, v23
	v_fmamk_f32 v21, v21, 0x3c000000, v100
	v_cmp_gt_f32_e32 vcc, s33, v21
	v_mul_f32_e32 v22, 0x4f800000, v21
	s_nop 0
	v_cndmask_b32_e32 v21, v21, v22, vcc
	v_sqrt_f32_e32 v22, v21
	s_nop 0
	v_add_u32_e32 v23, -1, v22
	v_fma_f32 v24, -v23, v22, v21
	v_cmp_ge_f32_e64 s[8:9], 0, v24
	v_add_u32_e32 v24, 1, v22
	s_nop 0
	v_cndmask_b32_e64 v23, v22, v23, s[8:9]
	v_fma_f32 v22, -v24, v22, v21
	v_cmp_lt_f32_e64 s[8:9], 0, v22
	s_nop 1
	v_cndmask_b32_e64 v22, v23, v24, s[8:9]
	v_mul_f32_e32 v23, 0x37800000, v22
	v_cndmask_b32_e32 v22, v22, v23, vcc
	v_cmp_class_f32_e32 vcc, v21, v101
	s_nop 1
	v_cndmask_b32_e32 v21, v22, v21, vcc
	s_nop 0
	v_div_scale_f32 v24, vcc, 1.0, v21, 1.0
	v_rcp_f32_e32 v45, v21
	v_mul_f32_e32 v21, v120, v120
	v_fmac_f32_e32 v21, v136, v136
	v_fmac_f32_e32 v21, v104, v104
	v_fmac_f32_e32 v21, v17, v17
	s_nop 1
	v_add_f32_dpp v21, v21, v21 quad_perm:[1,0,3,2] row_mask:0xf bank_mask:0xf
	v_mul_f32_e32 v18, v18, v45
	s_nop 1
	v_add_f32_dpp v21, v21, v21 quad_perm:[2,3,0,1] row_mask:0xf bank_mask:0xf
	s_nop 1
	v_add_f32_dpp v21, v21, v21 row_half_mirror row_mask:0xf bank_mask:0xf
	s_nop 1
	v_add_f32_dpp v21, v21, v21 row_mirror row_mask:0xf bank_mask:0xf
	v_mov_b32_e32 v22, v21
	v_mov_b32_e32 v23, v21
	s_nop 1
	v_permlane16_swap_b32_e32 v22, v23
	v_add_f32_e32 v21, v22, v23
	v_fmamk_f32 v21, v21, 0x3c000000, v100
	v_cmp_gt_f32_e32 vcc, s33, v21
	v_mul_f32_e32 v22, 0x4f800000, v21
	s_nop 0
	v_cndmask_b32_e32 v21, v21, v22, vcc
	v_sqrt_f32_e32 v22, v21
	s_nop 0
	v_add_u32_e32 v23, -1, v22
	v_fma_f32 v24, -v23, v22, v21
	v_cmp_ge_f32_e64 s[8:9], 0, v24
	v_add_u32_e32 v24, 1, v22
	s_nop 0
	v_cndmask_b32_e64 v23, v22, v23, s[8:9]
	v_fma_f32 v22, -v24, v22, v21
	v_cmp_lt_f32_e64 s[8:9], 0, v22
	s_nop 1
	v_cndmask_b32_e64 v22, v23, v24, s[8:9]
	v_mul_f32_e32 v23, 0x37800000, v22
	v_cndmask_b32_e32 v22, v22, v23, vcc
	v_cmp_class_f32_e32 vcc, v21, v101
	s_nop 1
	v_cndmask_b32_e32 v21, v22, v21, vcc
	s_nop 0
	v_div_scale_f32 v24, vcc, 1.0, v21, 1.0
	v_rcp_f32_e32 v44, v21
	v_mul_f32_e32 v21, v119, v119
	v_fmac_f32_e32 v21, v135, v135
	v_fmac_f32_e32 v21, v103, v103
	v_fmac_f32_e32 v21, v16, v16
	s_nop 1
	v_add_f32_dpp v21, v21, v21 quad_perm:[1,0,3,2] row_mask:0xf bank_mask:0xf
	v_mul_f32_e32 v17, v17, v44
	s_nop 1
	v_add_f32_dpp v21, v21, v21 quad_perm:[2,3,0,1] row_mask:0xf bank_mask:0xf
	s_nop 1
	v_add_f32_dpp v21, v21, v21 row_half_mirror row_mask:0xf bank_mask:0xf
	s_nop 1
	v_add_f32_dpp v21, v21, v21 row_mirror row_mask:0xf bank_mask:0xf
	v_mov_b32_e32 v22, v21
	v_mov_b32_e32 v23, v21
	s_nop 1
	v_permlane16_swap_b32_e32 v22, v23
	v_add_f32_e32 v21, v22, v23
	v_fmamk_f32 v21, v21, 0x3c000000, v100
	v_cmp_gt_f32_e32 vcc, s33, v21
	v_mul_f32_e32 v22, 0x4f800000, v21
	s_nop 0
	v_cndmask_b32_e32 v21, v21, v22, vcc
	v_sqrt_f32_e32 v22, v21
	s_nop 0
	v_add_u32_e32 v23, -1, v22
	v_fma_f32 v24, -v23, v22, v21
	v_cmp_ge_f32_e64 s[8:9], 0, v24
	v_add_u32_e32 v24, 1, v22
	s_nop 0
	v_cndmask_b32_e64 v23, v22, v23, s[8:9]
	v_fma_f32 v22, -v24, v22, v21
	v_cmp_lt_f32_e64 s[8:9], 0, v22
	s_nop 1
	v_cndmask_b32_e64 v22, v23, v24, s[8:9]
	v_mul_f32_e32 v23, 0x37800000, v22
	v_cndmask_b32_e32 v22, v22, v23, vcc
	v_cmp_class_f32_e32 vcc, v21, v101
	s_nop 1
; DI void gla_stage3(const Ctx& c0, int layer, int unit, int cb, LAS unsigned char* lds) {
;     ...
;     float rs[16];
; #pragma unroll
;     for (int rg = 0; rg < 16; ++rg) { float ss = o[0][rg] * o[0][rg] + o[1][rg] * o[1][rg] + o[2][rg] * o[2][rg] + o[3][rg] * o[3][rg];
;         ss += __shfl_xor(ss, 1); ss += __shfl_xor(ss, 2); ss += __shfl_xor(ss, 4); ss += __shfl_xor(ss, 8); ss += __shfl_xor(ss, 16);
;         rs[rg] = 1.f / sqrtf(ss * (1.f / 128.f) + EPS); }
	v_cndmask_b32_e32 v21, v22, v21, vcc
	s_nop 0
	v_div_scale_f32 v24, vcc, 1.0, v21, 1.0
	v_rcp_f32_e32 v43, v21
	v_mul_f32_e32 v21, v118, v118
	v_fmac_f32_e32 v21, v134, v134
	v_fmac_f32_e32 v21, v102, v102
	v_fmac_f32_e32 v21, v15, v15
	s_nop 1
	v_add_f32_dpp v21, v21, v21 quad_perm:[1,0,3,2] row_mask:0xf bank_mask:0xf
	v_mul_f32_e32 v16, v16, v43
	s_nop 1
	v_add_f32_dpp v21, v21, v21 quad_perm:[2,3,0,1] row_mask:0xf bank_mask:0xf
	s_nop 1
	v_add_f32_dpp v21, v21, v21 row_half_mirror row_mask:0xf bank_mask:0xf
	s_nop 1
	v_add_f32_dpp v21, v21, v21 row_mirror row_mask:0xf bank_mask:0xf
	v_mov_b32_e32 v22, v21
	v_mov_b32_e32 v23, v21
	s_nop 1
	v_permlane16_swap_b32_e32 v22, v23
	v_add_f32_e32 v21, v22, v23
	v_fmamk_f32 v21, v21, 0x3c000000, v100
	v_cmp_gt_f32_e32 vcc, s33, v21
	v_mul_f32_e32 v22, 0x4f800000, v21
	s_nop 0
	v_cndmask_b32_e32 v21, v21, v22, vcc
	v_sqrt_f32_e32 v22, v21
	s_nop 0
	v_add_u32_e32 v23, -1, v22
	v_fma_f32 v24, -v23, v22, v21
	v_cmp_ge_f32_e64 s[8:9], 0, v24
	v_add_u32_e32 v24, 1, v22
	s_nop 0
	v_cndmask_b32_e64 v23, v22, v23, s[8:9]
	v_fma_f32 v22, -v24, v22, v21
	v_cmp_lt_f32_e64 s[8:9], 0, v22
	s_nop 1
	v_cndmask_b32_e64 v22, v23, v24, s[8:9]
	v_mul_f32_e32 v23, 0x37800000, v22
	v_cndmask_b32_e32 v22, v22, v23, vcc
	v_cmp_class_f32_e32 vcc, v21, v101
	s_nop 1
	v_cndmask_b32_e32 v21, v22, v21, vcc
	s_nop 0
	v_div_scale_f32 v24, vcc, 1.0, v21, 1.0
	v_rcp_f32_e32 v42, v21
	v_mul_f32_e32 v21, v117, v117
	v_fmac_f32_e32 v21, v133, v133
	v_fmac_f32_e32 v21, v39, v39
	v_fmac_f32_e32 v21, v14, v14
	s_nop 1
	v_add_f32_dpp v21, v21, v21 quad_perm:[1,0,3,2] row_mask:0xf bank_mask:0xf
	v_mul_f32_e32 v15, v15, v42
	s_nop 1
	v_add_f32_dpp v21, v21, v21 quad_perm:[2,3,0,1] row_mask:0xf bank_mask:0xf
	s_nop 1
	v_add_f32_dpp v21, v21, v21 row_half_mirror row_mask:0xf bank_mask:0xf
	s_nop 1
	v_add_f32_dpp v21, v21, v21 row_mirror row_mask:0xf bank_mask:0xf
	v_mov_b32_e32 v22, v21
	v_mov_b32_e32 v23, v21
	s_nop 1
	v_permlane16_swap_b32_e32 v22, v23
	v_add_f32_e32 v21, v22, v23
	v_fmamk_f32 v21, v21, 0x3c000000, v100
	v_cmp_gt_f32_e32 vcc, s33, v21
	v_mul_f32_e32 v22, 0x4f800000, v21
	s_nop 0
	v_cndmask_b32_e32 v21, v21, v22, vcc
	v_sqrt_f32_e32 v22, v21
	s_nop 0
	v_add_u32_e32 v23, -1, v22
	v_fma_f32 v24, -v23, v22, v21
	v_cmp_ge_f32_e64 s[8:9], 0, v24
	v_add_u32_e32 v24, 1, v22
	s_nop 0
	v_cndmask_b32_e64 v23, v22, v23, s[8:9]
	v_fma_f32 v22, -v24, v22, v21
	v_cmp_lt_f32_e64 s[8:9], 0, v22
	s_nop 1
	v_cndmask_b32_e64 v22, v23, v24, s[8:9]
	v_mul_f32_e32 v23, 0x37800000, v22
	v_cndmask_b32_e32 v22, v22, v23, vcc
	v_cmp_class_f32_e32 vcc, v21, v101
	s_nop 1
	v_cndmask_b32_e32 v21, v22, v21, vcc
	s_nop 0
	v_div_scale_f32 v24, vcc, 1.0, v21, 1.0
	v_rcp_f32_e32 v41, v21
	v_mul_f32_e32 v21, v116, v116
	v_fmac_f32_e32 v21, v132, v132
	v_fmac_f32_e32 v21, v38, v38
	v_fmac_f32_e32 v21, v13, v13
	s_nop 1
	v_add_f32_dpp v21, v21, v21 quad_perm:[1,0,3,2] row_mask:0xf bank_mask:0xf
	v_mul_f32_e32 v39, v39, v41
	v_mul_f32_e32 v14, v14, v41
	s_nop 1
	v_add_f32_dpp v21, v21, v21 quad_perm:[2,3,0,1] row_mask:0xf bank_mask:0xf
	s_nop 1
	v_add_f32_dpp v21, v21, v21 row_half_mirror row_mask:0xf bank_mask:0xf
	s_nop 1
	v_add_f32_dpp v21, v21, v21 row_mirror row_mask:0xf bank_mask:0xf
	v_mov_b32_e32 v22, v21
	v_mov_b32_e32 v23, v21
	s_nop 1
	v_permlane16_swap_b32_e32 v22, v23
	v_add_f32_e32 v21, v22, v23
	v_fmamk_f32 v21, v21, 0x3c000000, v100
	v_cmp_gt_f32_e32 vcc, s33, v21
	v_mul_f32_e32 v22, 0x4f800000, v21
	s_nop 0
	v_cndmask_b32_e32 v21, v21, v22, vcc
	v_sqrt_f32_e32 v22, v21
	s_nop 0
	v_add_u32_e32 v23, -1, v22
	v_fma_f32 v24, -v23, v22, v21
	v_cmp_ge_f32_e64 s[8:9], 0, v24
	v_add_u32_e32 v24, 1, v22
	s_nop 0
	v_cndmask_b32_e64 v23, v22, v23, s[8:9]
	v_fma_f32 v22, -v24, v22, v21
	v_cmp_lt_f32_e64 s[8:9], 0, v22
	s_nop 1
	v_cndmask_b32_e64 v22, v23, v24, s[8:9]
	v_mul_f32_e32 v23, 0x37800000, v22
	v_cndmask_b32_e32 v22, v22, v23, vcc
	v_cmp_class_f32_e32 vcc, v21, v101
	s_nop 1
	v_cndmask_b32_e32 v21, v22, v21, vcc
	s_nop 0
	v_div_scale_f32 v24, vcc, 1.0, v21, 1.0
	v_rcp_f32_e32 v40, v21
	v_mul_f32_e32 v21, v115, v115
	v_fmac_f32_e32 v21, v131, v131
	v_fmac_f32_e32 v21, v37, v37
	v_fmac_f32_e32 v21, v12, v12
	s_nop 1
	v_add_f32_dpp v21, v21, v21 quad_perm:[1,0,3,2] row_mask:0xf bank_mask:0xf
	v_mul_f32_e32 v38, v38, v40
	v_mul_f32_e32 v13, v13, v40
	s_nop 1
	v_add_f32_dpp v21, v21, v21 quad_perm:[2,3,0,1] row_mask:0xf bank_mask:0xf
	s_nop 1
	v_add_f32_dpp v21, v21, v21 row_half_mirror row_mask:0xf bank_mask:0xf
	s_nop 1
	v_add_f32_dpp v21, v21, v21 row_mirror row_mask:0xf bank_mask:0xf
	v_mov_b32_e32 v22, v21
	v_mov_b32_e32 v23, v21
	s_nop 1
	v_permlane16_swap_b32_e32 v22, v23
	v_add_f32_e32 v21, v22, v23
	v_fmamk_f32 v21, v21, 0x3c000000, v100
	v_cmp_gt_f32_e32 vcc, s33, v21
	v_mul_f32_e32 v22, 0x4f800000, v21
	s_nop 0
	v_cndmask_b32_e32 v21, v21, v22, vcc
	v_sqrt_f32_e32 v22, v21
	s_nop 0
	v_add_u32_e32 v23, -1, v22
	v_fma_f32 v24, -v23, v22, v21
	v_cmp_ge_f32_e64 s[8:9], 0, v24
	v_add_u32_e32 v24, 1, v22
	s_nop 0
	v_cndmask_b32_e64 v23, v22, v23, s[8:9]
	v_fma_f32 v22, -v24, v22, v21
	v_cmp_lt_f32_e64 s[8:9], 0, v22
	s_nop 1
	v_cndmask_b32_e64 v22, v23, v24, s[8:9]
	v_mul_f32_e32 v23, 0x37800000, v22
	v_cndmask_b32_e32 v22, v22, v23, vcc
	v_cmp_class_f32_e32 vcc, v21, v101
	s_nop 1
	v_cndmask_b32_e32 v21, v22, v21, vcc
	s_nop 0
	v_div_scale_f32 v24, vcc, 1.0, v21, 1.0
	v_rcp_f32_e32 v35, v21
	v_mul_f32_e32 v21, v114, v114
	v_fmac_f32_e32 v21, v130, v130
	v_fmac_f32_e32 v21, v36, v36
	v_fmac_f32_e32 v21, v11, v11
	s_nop 1
	v_add_f32_dpp v21, v21, v21 quad_perm:[1,0,3,2] row_mask:0xf bank_mask:0xf
	v_mul_f32_e32 v37, v37, v35
	v_mul_f32_e32 v12, v12, v35
; DI void gla_stage3(const Ctx& c0, int layer, int unit, int cb, LAS unsigned char* lds) {
;     ...
;     float rs[16];
; #pragma unroll
;     for (int rg = 0; rg < 16; ++rg) { float ss = o[0][rg] * o[0][rg] + o[1][rg] * o[1][rg] + o[2][rg] * o[2][rg] + o[3][rg] * o[3][rg];
;         ss += __shfl_xor(ss, 1); ss += __shfl_xor(ss, 2); ss += __shfl_xor(ss, 4); ss += __shfl_xor(ss, 8); ss += __shfl_xor(ss, 16);
;         rs[rg] = 1.f / sqrtf(ss * (1.f / 128.f) + EPS); }
	s_nop 1
	v_add_f32_dpp v21, v21, v21 quad_perm:[2,3,0,1] row_mask:0xf bank_mask:0xf
	s_nop 1
	v_add_f32_dpp v21, v21, v21 row_half_mirror row_mask:0xf bank_mask:0xf
	s_nop 1
	v_add_f32_dpp v21, v21, v21 row_mirror row_mask:0xf bank_mask:0xf
	v_mov_b32_e32 v22, v21
	v_mov_b32_e32 v23, v21
	s_nop 1
	v_permlane16_swap_b32_e32 v22, v23
	v_add_f32_e32 v21, v22, v23
	v_fmamk_f32 v21, v21, 0x3c000000, v100
	v_cmp_gt_f32_e32 vcc, s33, v21
	v_mul_f32_e32 v22, 0x4f800000, v21
	s_nop 0
	v_cndmask_b32_e32 v21, v21, v22, vcc
	v_sqrt_f32_e32 v22, v21
	s_nop 0
	v_add_u32_e32 v23, -1, v22
	v_fma_f32 v24, -v23, v22, v21
	v_cmp_ge_f32_e64 s[8:9], 0, v24
	v_add_u32_e32 v24, 1, v22
	s_nop 0
	v_cndmask_b32_e64 v23, v22, v23, s[8:9]
	v_fma_f32 v22, -v24, v22, v21
	v_cmp_lt_f32_e64 s[8:9], 0, v22
	s_nop 1
	v_cndmask_b32_e64 v22, v23, v24, s[8:9]
	v_mul_f32_e32 v23, 0x37800000, v22
	v_cndmask_b32_e32 v22, v22, v23, vcc
	v_cmp_class_f32_e32 vcc, v21, v101
	s_nop 1
	v_cndmask_b32_e32 v21, v22, v21, vcc
	s_nop 0
	v_div_scale_f32 v24, vcc, 1.0, v21, 1.0
	v_rcp_f32_e32 v31, v21
	v_mul_f32_e32 v21, v113, v113
	v_fmac_f32_e32 v21, v129, v129
	v_fmac_f32_e32 v21, v34, v34
	v_fmac_f32_e32 v21, v10, v10
	s_nop 1
	v_add_f32_dpp v21, v21, v21 quad_perm:[1,0,3,2] row_mask:0xf bank_mask:0xf
	v_mul_f32_e32 v36, v36, v31
	v_mul_f32_e32 v11, v11, v31
	s_nop 1
	v_add_f32_dpp v21, v21, v21 quad_perm:[2,3,0,1] row_mask:0xf bank_mask:0xf
	s_nop 1
	v_add_f32_dpp v21, v21, v21 row_half_mirror row_mask:0xf bank_mask:0xf
	s_nop 1
	v_add_f32_dpp v21, v21, v21 row_mirror row_mask:0xf bank_mask:0xf
	v_mov_b32_e32 v22, v21
	v_mov_b32_e32 v23, v21
	s_nop 1
	v_permlane16_swap_b32_e32 v22, v23
	v_add_f32_e32 v21, v22, v23
	v_fmamk_f32 v21, v21, 0x3c000000, v100
	v_cmp_gt_f32_e32 vcc, s33, v21
	v_mul_f32_e32 v22, 0x4f800000, v21
	s_nop 0
	v_cndmask_b32_e32 v21, v21, v22, vcc
	v_sqrt_f32_e32 v22, v21
	s_nop 0
	v_add_u32_e32 v23, -1, v22
	v_fma_f32 v24, -v23, v22, v21
	v_cmp_ge_f32_e64 s[8:9], 0, v24
	v_add_u32_e32 v24, 1, v22
	s_nop 0
	v_cndmask_b32_e64 v23, v22, v23, s[8:9]
	v_fma_f32 v22, -v24, v22, v21
	v_cmp_lt_f32_e64 s[8:9], 0, v22
	s_nop 1
	v_cndmask_b32_e64 v22, v23, v24, s[8:9]
	v_mul_f32_e32 v23, 0x37800000, v22
	v_cndmask_b32_e32 v22, v22, v23, vcc
	v_cmp_class_f32_e32 vcc, v21, v101
	s_nop 1
	v_cndmask_b32_e32 v21, v22, v21, vcc
	s_nop 0
	v_div_scale_f32 v24, vcc, 1.0, v21, 1.0
	v_rcp_f32_e32 v27, v21
	v_mul_f32_e32 v21, v112, v112
	v_fmac_f32_e32 v21, v128, v128
	v_fmac_f32_e32 v21, v33, v33
	v_fmac_f32_e32 v21, v9, v9
	s_nop 1
	v_add_f32_dpp v21, v21, v21 quad_perm:[1,0,3,2] row_mask:0xf bank_mask:0xf
	v_mul_f32_e32 v34, v34, v27
	v_mul_f32_e32 v10, v10, v27
	s_nop 1
	v_add_f32_dpp v21, v21, v21 quad_perm:[2,3,0,1] row_mask:0xf bank_mask:0xf
	s_nop 1
	v_add_f32_dpp v21, v21, v21 row_half_mirror row_mask:0xf bank_mask:0xf
	s_nop 1
	v_add_f32_dpp v21, v21, v21 row_mirror row_mask:0xf bank_mask:0xf
	v_mov_b32_e32 v22, v21
	v_mov_b32_e32 v23, v21
	s_nop 1
	v_permlane16_swap_b32_e32 v22, v23
	v_add_f32_e32 v21, v22, v23
	v_fmamk_f32 v21, v21, 0x3c000000, v100
	v_cmp_gt_f32_e32 vcc, s33, v21
	v_mul_f32_e32 v22, 0x4f800000, v21
	s_nop 0
	v_cndmask_b32_e32 v21, v21, v22, vcc
	v_sqrt_f32_e32 v22, v21
	s_nop 0
	v_add_u32_e32 v23, -1, v22
	v_fma_f32 v24, -v23, v22, v21
	v_cmp_ge_f32_e64 s[8:9], 0, v24
	v_add_u32_e32 v24, 1, v22
	s_nop 0
	v_cndmask_b32_e64 v23, v22, v23, s[8:9]
	v_fma_f32 v22, -v24, v22, v21
	v_cmp_lt_f32_e64 s[8:9], 0, v22
	s_nop 1
	v_cndmask_b32_e64 v22, v23, v24, s[8:9]
	v_mul_f32_e32 v23, 0x37800000, v22
	v_cndmask_b32_e32 v22, v22, v23, vcc
	v_cmp_class_f32_e32 vcc, v21, v101
	s_nop 1
	v_cndmask_b32_e32 v21, v22, v21, vcc
	s_nop 0
	v_div_scale_f32 v24, vcc, 1.0, v21, 1.0
	v_rcp_f32_e32 v25, v21
	v_mul_f32_e32 v21, v111, v111
	v_fmac_f32_e32 v21, v127, v127
	v_fmac_f32_e32 v21, v32, v32
	v_fmac_f32_e32 v21, v8, v8
	s_nop 1
	v_add_f32_dpp v21, v21, v21 quad_perm:[1,0,3,2] row_mask:0xf bank_mask:0xf
	v_mul_f32_e32 v33, v33, v25
	v_mul_f32_e32 v9, v9, v25
	s_nop 1
	v_add_f32_dpp v21, v21, v21 quad_perm:[2,3,0,1] row_mask:0xf bank_mask:0xf
	s_nop 1
	v_add_f32_dpp v21, v21, v21 row_half_mirror row_mask:0xf bank_mask:0xf
	s_nop 1
	v_add_f32_dpp v21, v21, v21 row_mirror row_mask:0xf bank_mask:0xf
	v_mov_b32_e32 v22, v21
	v_mov_b32_e32 v23, v21
	s_nop 1
	v_permlane16_swap_b32_e32 v22, v23
	v_add_f32_e32 v21, v22, v23
	v_fmamk_f32 v21, v21, 0x3c000000, v100
	v_cmp_gt_f32_e32 vcc, s33, v21
	v_mul_f32_e32 v22, 0x4f800000, v21
	s_nop 0
	v_cndmask_b32_e32 v21, v21, v22, vcc
	v_sqrt_f32_e32 v22, v21
	s_nop 0
	v_add_u32_e32 v23, -1, v22
	v_fma_f32 v24, -v23, v22, v21
	v_cmp_ge_f32_e64 s[8:9], 0, v24
	v_add_u32_e32 v24, 1, v22
	s_nop 0
	v_cndmask_b32_e64 v23, v22, v23, s[8:9]
	v_fma_f32 v22, -v24, v22, v21
	v_cmp_lt_f32_e64 s[8:9], 0, v22
	s_nop 1
	v_cndmask_b32_e64 v22, v23, v24, s[8:9]
	v_mul_f32_e32 v23, 0x37800000, v22
	v_cndmask_b32_e32 v22, v22, v23, vcc
	v_cmp_class_f32_e32 vcc, v21, v101
	s_nop 1
	v_cndmask_b32_e32 v21, v22, v21, vcc
	s_nop 0
	v_div_scale_f32 v24, vcc, 1.0, v21, 1.0
	v_rcp_f32_e32 v24, v21
	v_mul_f32_e32 v21, v110, v110
	v_fmac_f32_e32 v21, v126, v126
	v_fmac_f32_e32 v21, v30, v30
	v_fmac_f32_e32 v21, v7, v7
	s_nop 1
	v_add_f32_dpp v21, v21, v21 quad_perm:[1,0,3,2] row_mask:0xf bank_mask:0xf
	v_mul_f32_e32 v32, v32, v24
	v_mul_f32_e32 v8, v8, v24
	s_nop 1
	v_add_f32_dpp v21, v21, v21 quad_perm:[2,3,0,1] row_mask:0xf bank_mask:0xf
	s_nop 1
	v_add_f32_dpp v21, v21, v21 row_half_mirror row_mask:0xf bank_mask:0xf
	s_nop 1
	v_add_f32_dpp v21, v21, v21 row_mirror row_mask:0xf bank_mask:0xf
	v_mov_b32_e32 v22, v21
	v_mov_b32_e32 v23, v21
	s_nop 1
	v_permlane16_swap_b32_e32 v22, v23
; #define LAS __attribute__((address_space(3)))
; #define LDS_WAIT() asm volatile("s_waitcnt lgkmcnt(0)" ::: "memory")
; DI unsigned cvtpk(float lo, float hi) { f32x2 v = {lo, hi}; bf16x2_t b = __builtin_convertvector(v, bf16x2_t); return __builtin_bit_cast(unsigned, b); }
; DI float bf2f(bf16 b) { return __uint_as_float(((unsigned)b) << 16); }
; DI float siluf_(float x) { return x / (1.f + __expf(-x)); }
; DI void gla_stage3(const Ctx& c0, int layer, int unit, int cb, LAS unsigned char* lds) {
;     ...
;     float rs[16];
; #pragma unroll
;     for (int rg = 0; rg < 16; ++rg) { float ss = o[0][rg] * o[0][rg] + o[1][rg] * o[1][rg] + o[2][rg] * o[2][rg] + o[3][rg] * o[3][rg];
;         ss += __shfl_xor(ss, 1); ss += __shfl_xor(ss, 2); ss += __shfl_xor(ss, 4); ss += __shfl_xor(ss, 8); ss += __shfl_xor(ss, 16);
;         rs[rg] = 1.f / sqrtf(ss * (1.f / 128.f) + EPS); }
;     LDS_WAIT();
;     g3_tile_in((const bf16*)(c.ws + O_GR) + row0 * 512 + h * 128, R, lane);
; #pragma unroll
;     for (int vb = 0; vb < 4; ++vb) { const float g = gn[32 * vb + r];
; #pragma unroll
;         for (int rg = 0; rg < 16; ++rg) { LAS bf16* e = (LAS bf16*)(R + (4 * hi) * G3_PITCH + r * 2 + ((rg & 3) + 8 * (rg >> 2)) * G3_PITCH + 64 * vb);
;             const float z = bf2f(*e);
;             *e = (bf16)(cvtpk(o[vb][rg] * rs[rg] * g * siluf_(z), 0.f) & 0xffffu); }
	v_add_f32_e32 v21, v22, v23
	v_fmamk_f32 v21, v21, 0x3c000000, v100
	v_cmp_gt_f32_e32 vcc, s33, v21
	v_mul_f32_e32 v22, 0x4f800000, v21
	s_nop 0
	v_cndmask_b32_e32 v21, v21, v22, vcc
	v_sqrt_f32_e32 v22, v21
	s_nop 0
	v_add_u32_e32 v23, -1, v22
	v_fma_f32 v49, -v23, v22, v21
	v_cmp_ge_f32_e64 s[8:9], 0, v49
	v_add_u32_e32 v49, 1, v22
	s_nop 0
	v_cndmask_b32_e64 v23, v22, v23, s[8:9]
	v_fma_f32 v22, -v49, v22, v21
	v_cmp_lt_f32_e64 s[8:9], 0, v22
	s_nop 1
	v_cndmask_b32_e64 v22, v23, v49, s[8:9]
	v_mul_f32_e32 v23, 0x37800000, v22
	v_cndmask_b32_e32 v22, v22, v23, vcc
	v_cmp_class_f32_e32 vcc, v21, v101
	s_nop 1
	v_cndmask_b32_e32 v21, v22, v21, vcc
	s_nop 0
	v_div_scale_f32 v49, vcc, 1.0, v21, 1.0
	v_rcp_f32_e32 v23, v21
	v_mul_f32_e32 v21, v109, v109
	v_fmac_f32_e32 v21, v125, v125
	v_fmac_f32_e32 v21, v29, v29
	v_fmac_f32_e32 v21, v6, v6
	s_nop 1
	v_add_f32_dpp v21, v21, v21 quad_perm:[1,0,3,2] row_mask:0xf bank_mask:0xf
	v_mul_f32_e32 v30, v30, v23
	v_mul_f32_e32 v7, v7, v23
	s_nop 1
	v_add_f32_dpp v21, v21, v21 quad_perm:[2,3,0,1] row_mask:0xf bank_mask:0xf
	s_nop 1
	v_add_f32_dpp v21, v21, v21 row_half_mirror row_mask:0xf bank_mask:0xf
	s_nop 1
	v_add_f32_dpp v21, v21, v21 row_mirror row_mask:0xf bank_mask:0xf
	v_mov_b32_e32 v22, v21
	v_mov_b32_e32 v49, v21
	s_nop 1
	v_permlane16_swap_b32_e32 v22, v49
	v_add_f32_e32 v21, v22, v49
	v_fmamk_f32 v21, v21, 0x3c000000, v100
	v_cmp_gt_f32_e32 vcc, s33, v21
	v_mul_f32_e32 v22, 0x4f800000, v21
	s_nop 0
	v_cndmask_b32_e32 v21, v21, v22, vcc
	v_sqrt_f32_e32 v22, v21
	s_nop 0
	v_add_u32_e32 v49, -1, v22
	v_fma_f32 v50, -v49, v22, v21
	v_cmp_ge_f32_e64 s[8:9], 0, v50
	v_add_u32_e32 v50, 1, v22
	s_nop 0
	v_cndmask_b32_e64 v49, v22, v49, s[8:9]
	v_fma_f32 v22, -v50, v22, v21
	v_cmp_lt_f32_e64 s[8:9], 0, v22
	s_nop 1
	v_cndmask_b32_e64 v22, v49, v50, s[8:9]
	v_mul_f32_e32 v49, 0x37800000, v22
	v_cndmask_b32_e32 v22, v22, v49, vcc
	v_cmp_class_f32_e32 vcc, v21, v101
	s_nop 1
	v_cndmask_b32_e32 v21, v22, v21, vcc
	s_nop 0
	v_div_scale_f32 v50, vcc, 1.0, v21, 1.0
	v_rcp_f32_e32 v22, v21
	v_mul_f32_e32 v21, v108, v108
	v_fmac_f32_e32 v21, v124, v124
	v_fmac_f32_e32 v21, v28, v28
	v_fmac_f32_e32 v21, v5, v5
	s_nop 1
	v_add_f32_dpp v21, v21, v21 quad_perm:[1,0,3,2] row_mask:0xf bank_mask:0xf
	v_mul_f32_e32 v29, v29, v22
	v_mul_f32_e32 v6, v6, v22
	s_nop 1
	v_add_f32_dpp v21, v21, v21 quad_perm:[2,3,0,1] row_mask:0xf bank_mask:0xf
	s_nop 1
	v_add_f32_dpp v21, v21, v21 row_half_mirror row_mask:0xf bank_mask:0xf
	s_nop 1
	v_add_f32_dpp v21, v21, v21 row_mirror row_mask:0xf bank_mask:0xf
	v_mov_b32_e32 v49, v21
	v_mov_b32_e32 v50, v21
	s_nop 1
	v_permlane16_swap_b32_e32 v49, v50
	v_add_f32_e32 v21, v49, v50
	v_fmamk_f32 v21, v21, 0x3c000000, v100
	v_cmp_gt_f32_e32 vcc, s33, v21
	v_mul_f32_e32 v49, 0x4f800000, v21
	s_nop 0
	v_cndmask_b32_e32 v21, v21, v49, vcc
	v_sqrt_f32_e32 v49, v21
	s_nop 0
	v_add_u32_e32 v50, -1, v49
	v_fma_f32 v51, -v50, v49, v21
	v_cmp_ge_f32_e64 s[8:9], 0, v51
	v_add_u32_e32 v51, 1, v49
	s_nop 0
	v_cndmask_b32_e64 v50, v49, v50, s[8:9]
	v_fma_f32 v49, -v51, v49, v21
	v_cmp_lt_f32_e64 s[8:9], 0, v49
	s_nop 1
	v_cndmask_b32_e64 v49, v50, v51, s[8:9]
	v_mul_f32_e32 v50, 0x37800000, v49
	v_cndmask_b32_e32 v49, v49, v50, vcc
	v_cmp_class_f32_e32 vcc, v21, v101
	s_nop 1
	v_cndmask_b32_e32 v21, v49, v21, vcc
	s_nop 0
	v_div_scale_f32 v51, vcc, 1.0, v21, 1.0
	v_rcp_f32_e32 v21, v21
	v_mul_f32_e32 v49, v107, v107
	v_fmac_f32_e32 v49, v123, v123
	v_fmac_f32_e32 v49, v26, v26
	v_fmac_f32_e32 v49, v4, v4
	ds_bpermute_b32 v2, v2, v49
	v_mul_f32_e32 v28, v28, v21
	v_mul_f32_e32 v5, v5, v21
	s_waitcnt lgkmcnt(0)
	v_add_f32_e32 v2, v49, v2
	ds_bpermute_b32 v3, v3, v2
	s_waitcnt lgkmcnt(0)
	v_add_f32_e32 v2, v2, v3
	ds_bpermute_b32 v3, v20, v2
	s_waitcnt lgkmcnt(0)
	v_add_f32_e32 v2, v2, v3
	ds_bpermute_b32 v3, v47, v2
	s_waitcnt lgkmcnt(0)
	v_add_f32_e32 v2, v2, v3
	ds_bpermute_b32 v3, v48, v2
	s_waitcnt lgkmcnt(0)
	v_add_f32_e32 v2, v2, v3
	v_fmamk_f32 v2, v2, 0x3c000000, v100
	v_cmp_gt_f32_e32 vcc, s33, v2
	v_mul_f32_e32 v3, 0x4f800000, v2
	s_nop 0
	v_cndmask_b32_e32 v2, v2, v3, vcc
	v_sqrt_f32_e32 v3, v2
	s_nop 0
	v_add_u32_e32 v20, -1, v3
	v_fma_f32 v47, -v20, v3, v2
	v_cmp_ge_f32_e64 s[8:9], 0, v47
	v_add_u32_e32 v47, 1, v3
	s_nop 0
	v_cndmask_b32_e64 v20, v3, v20, s[8:9]
	v_fma_f32 v3, -v47, v3, v2
	v_cmp_lt_f32_e64 s[8:9], 0, v3
	s_nop 1
	v_cndmask_b32_e64 v3, v20, v47, s[8:9]
	v_mul_f32_e32 v20, 0x37800000, v3
	v_cndmask_b32_e32 v3, v3, v20, vcc
	v_cmp_class_f32_e32 vcc, v2, v101
	s_nop 1
	v_cndmask_b32_e32 v2, v3, v2, vcc
	s_nop 0
	v_rcp_f32_e32 v20, v2
	v_mul_f32_e32 v47, v138, v46
	v_mul_f32_e32 v26, v26, v20
	v_mul_f32_e32 v4, v4, v20
	s_waitcnt vmcnt(2) lgkmcnt(0)
	ds_write_b128 v92, v[164:167]
	s_waitcnt vmcnt(0) lgkmcnt(0)
	ds_write_b128 v92, v[170:173] offset:1088
	s_waitcnt vmcnt(13) lgkmcnt(0)
	ds_write_b128 v92, v[174:177] offset:2176
	s_waitcnt vmcnt(8) lgkmcnt(0)
	ds_write_b128 v92, v[178:181] offset:3264
	s_waitcnt vmcnt(9) lgkmcnt(0)
	ds_write_b128 v92, v[196:199] offset:4352
	s_waitcnt vmcnt(10) lgkmcnt(0)
	ds_write_b128 v92, v[200:203] offset:5440
	v_lshl_add_u64 v[2:3], v[168:169], 0, v[80:81]
	s_waitcnt vmcnt(5) lgkmcnt(0)
	ds_write_b128 v92, v[204:207] offset:6528
	global_load_dwordx4 v[48:51], v[2:3], off
	s_waitcnt vmcnt(0) lgkmcnt(0)
	ds_write_b128 v92, v[48:51] offset:7616
	s_waitcnt lgkmcnt(0)
	ds_read_u16 v3, v1
	s_waitcnt lgkmcnt(0)
	v_lshlrev_b32_e32 v3, 16, v3
	v_mul_f32_e32 v48, 0xbfb8aa3b, v3
	v_exp_f32_e32 v48, v48
	s_waitcnt vmcnt(0)
; #define LAS __attribute__((address_space(3)))
; DI unsigned cvtpk(float lo, float hi) { f32x2 v = {lo, hi}; bf16x2_t b = __builtin_convertvector(v, bf16x2_t); return __builtin_bit_cast(unsigned, b); }
; DI float bf2f(bf16 b) { return __uint_as_float(((unsigned)b) << 16); }
; DI float siluf_(float x) { return x / (1.f + __expf(-x)); }
; DI void gla_stage3(const Ctx& c0, int layer, int unit, int cb, LAS unsigned char* lds) {
;     ...
; #pragma unroll
;     for (int vb = 0; vb < 4; ++vb) { const float g = gn[32 * vb + r];
; #pragma unroll
;         for (int rg = 0; rg < 16; ++rg) { LAS bf16* e = (LAS bf16*)(R + (4 * hi) * G3_PITCH + r * 2 + ((rg & 3) + 8 * (rg >> 2)) * G3_PITCH + 64 * vb);
;             const float z = bf2f(*e);
;             *e = (bf16)(cvtpk(o[vb][rg] * rs[rg] * g * siluf_(z), 0.f) & 0xffffu); }
;         asm volatile("" ::: "memory"); }
	v_mul_f32_e32 v47, v47, v232
	v_add_f32_e32 v48, 1.0, v48
	v_div_scale_f32 v49, s[0:1], v48, v48, v3
	s_nop 0
	v_rcp_f32_e32 v49, v48
	s_nop 0
	v_mul_f32_e32 v3, v3, v49
	v_mul_f32_e32 v3, v47, v3
	v_cvt_pk_bf16_f32 v3, v3, s0
	ds_write_b16 v1, v3
	ds_read_u16 v3, v1 offset:272
	v_mul_f32_e32 v47, v137, v45
	v_mul_f32_e32 v47, v47, v232
	s_waitcnt lgkmcnt(0)
	v_lshlrev_b32_e32 v3, 16, v3
	v_mul_f32_e32 v48, 0xbfb8aa3b, v3
	v_exp_f32_e32 v48, v48
	s_nop 0
	v_add_f32_e32 v48, 1.0, v48
	v_div_scale_f32 v49, s[0:1], v48, v48, v3
	s_nop 0
	v_rcp_f32_e32 v49, v48
	s_nop 0
	v_mul_f32_e32 v3, v3, v49
	v_mul_f32_e32 v3, v47, v3
	v_cvt_pk_bf16_f32 v3, v3, s0
	ds_write_b16 v1, v3 offset:272
	ds_read_u16 v3, v1 offset:544
	v_mul_f32_e32 v47, v136, v44
	v_mul_f32_e32 v47, v47, v232
	s_waitcnt lgkmcnt(0)
	v_lshlrev_b32_e32 v3, 16, v3
	v_mul_f32_e32 v48, 0xbfb8aa3b, v3
	v_exp_f32_e32 v48, v48
	s_nop 0
	v_add_f32_e32 v48, 1.0, v48
	v_div_scale_f32 v49, s[0:1], v48, v48, v3
	s_nop 0
	v_rcp_f32_e32 v49, v48
	s_nop 0
	v_mul_f32_e32 v3, v3, v49
	v_mul_f32_e32 v3, v47, v3
	v_cvt_pk_bf16_f32 v3, v3, s0
	ds_write_b16 v1, v3 offset:544
	ds_read_u16 v3, v1 offset:816
	v_mul_f32_e32 v47, v135, v43
	v_mul_f32_e32 v47, v47, v232
	s_waitcnt lgkmcnt(0)
	v_lshlrev_b32_e32 v3, 16, v3
	v_mul_f32_e32 v48, 0xbfb8aa3b, v3
	v_exp_f32_e32 v48, v48
	s_nop 0
	v_add_f32_e32 v48, 1.0, v48
	v_div_scale_f32 v49, s[0:1], v48, v48, v3
	s_nop 0
	v_rcp_f32_e32 v49, v48
	s_nop 0
	v_mul_f32_e32 v3, v3, v49
	v_mul_f32_e32 v3, v47, v3
	v_cvt_pk_bf16_f32 v3, v3, s0
	ds_write_b16 v1, v3 offset:816
	ds_read_u16 v3, v1 offset:2176
	v_mul_f32_e32 v47, v134, v42
	v_mul_f32_e32 v47, v47, v232
	s_waitcnt lgkmcnt(0)
	v_lshlrev_b32_e32 v3, 16, v3
	v_mul_f32_e32 v48, 0xbfb8aa3b, v3
	v_exp_f32_e32 v48, v48
	s_nop 0
	v_add_f32_e32 v48, 1.0, v48
	v_div_scale_f32 v49, s[0:1], v48, v48, v3
	s_nop 0
	v_rcp_f32_e32 v49, v48
	s_nop 0
	v_mul_f32_e32 v3, v3, v49
	v_mul_f32_e32 v3, v47, v3
	v_cvt_pk_bf16_f32 v3, v3, s0
	ds_write_b16 v1, v3 offset:2176
	ds_read_u16 v3, v1 offset:2448
	v_mul_f32_e32 v47, v133, v41
	v_mul_f32_e32 v47, v47, v232
	s_waitcnt lgkmcnt(0)
	v_lshlrev_b32_e32 v3, 16, v3
	v_mul_f32_e32 v48, 0xbfb8aa3b, v3
	v_exp_f32_e32 v48, v48
	s_nop 0
	v_add_f32_e32 v48, 1.0, v48
	v_div_scale_f32 v49, s[0:1], v48, v48, v3
	s_nop 0
	v_rcp_f32_e32 v49, v48
	s_nop 0
	v_mul_f32_e32 v3, v3, v49
	v_mul_f32_e32 v3, v47, v3
	v_cvt_pk_bf16_f32 v3, v3, s0
	ds_write_b16 v1, v3 offset:2448
	ds_read_u16 v3, v1 offset:2720
	v_mul_f32_e32 v47, v132, v40
	v_mul_f32_e32 v47, v47, v232
	s_waitcnt lgkmcnt(0)
	v_lshlrev_b32_e32 v3, 16, v3
	v_mul_f32_e32 v48, 0xbfb8aa3b, v3
	v_exp_f32_e32 v48, v48
	s_nop 0
	v_add_f32_e32 v48, 1.0, v48
	v_div_scale_f32 v49, s[0:1], v48, v48, v3
	s_nop 0
	v_rcp_f32_e32 v49, v48
	s_nop 0
	v_mul_f32_e32 v3, v3, v49
	v_mul_f32_e32 v3, v47, v3
	v_cvt_pk_bf16_f32 v3, v3, s0
	ds_write_b16 v1, v3 offset:2720
	ds_read_u16 v3, v1 offset:2992
	v_mul_f32_e32 v47, v131, v35
	v_mul_f32_e32 v47, v47, v232
	s_waitcnt lgkmcnt(0)
	v_lshlrev_b32_e32 v3, 16, v3
	v_mul_f32_e32 v48, 0xbfb8aa3b, v3
	v_exp_f32_e32 v48, v48
	s_nop 0
	v_add_f32_e32 v48, 1.0, v48
	v_div_scale_f32 v49, s[0:1], v48, v48, v3
	s_nop 0
	v_rcp_f32_e32 v49, v48
	s_nop 0
	v_mul_f32_e32 v3, v3, v49
	v_mul_f32_e32 v3, v47, v3
	v_cvt_pk_bf16_f32 v3, v3, s0
	ds_write_b16 v1, v3 offset:2992
	ds_read_u16 v3, v1 offset:4352
	v_mul_f32_e32 v47, v130, v31
	v_mul_f32_e32 v47, v47, v232
	s_waitcnt lgkmcnt(0)
	v_lshlrev_b32_e32 v3, 16, v3
	v_mul_f32_e32 v48, 0xbfb8aa3b, v3
	v_exp_f32_e32 v48, v48
	s_nop 0
	v_add_f32_e32 v48, 1.0, v48
	v_div_scale_f32 v49, s[0:1], v48, v48, v3
	s_nop 0
	v_rcp_f32_e32 v49, v48
	s_nop 0
	v_mul_f32_e32 v3, v3, v49
	v_mul_f32_e32 v3, v47, v3
	v_cvt_pk_bf16_f32 v3, v3, s0
	ds_write_b16 v1, v3 offset:4352
	ds_read_u16 v3, v1 offset:4624
	v_mul_f32_e32 v47, v129, v27
	v_mul_f32_e32 v47, v47, v232
	s_waitcnt lgkmcnt(0)
	v_lshlrev_b32_e32 v3, 16, v3
	v_mul_f32_e32 v48, 0xbfb8aa3b, v3
	v_exp_f32_e32 v48, v48
	s_nop 0
	v_add_f32_e32 v48, 1.0, v48
	v_div_scale_f32 v49, s[0:1], v48, v48, v3
	s_nop 0
	v_rcp_f32_e32 v49, v48
	s_nop 0
	v_mul_f32_e32 v3, v3, v49
	v_mul_f32_e32 v3, v47, v3
	v_cvt_pk_bf16_f32 v3, v3, s0
	ds_write_b16 v1, v3 offset:4624
	ds_read_u16 v3, v1 offset:4896
	v_mul_f32_e32 v47, v128, v25
	v_mul_f32_e32 v47, v47, v232
	s_waitcnt lgkmcnt(0)
	v_lshlrev_b32_e32 v3, 16, v3
	v_mul_f32_e32 v48, 0xbfb8aa3b, v3
	v_exp_f32_e32 v48, v48
	s_nop 0
	v_add_f32_e32 v48, 1.0, v48
	v_div_scale_f32 v49, s[0:1], v48, v48, v3
	s_nop 0
	v_rcp_f32_e32 v49, v48
	s_nop 0
	v_mul_f32_e32 v3, v3, v49
	v_mul_f32_e32 v3, v47, v3
	v_cvt_pk_bf16_f32 v3, v3, s0
	ds_write_b16 v1, v3 offset:4896
	ds_read_u16 v3, v1 offset:5168
	v_mul_f32_e32 v47, v127, v24
	v_mul_f32_e32 v47, v47, v232
	s_waitcnt lgkmcnt(0)
	v_lshlrev_b32_e32 v3, 16, v3
	v_mul_f32_e32 v48, 0xbfb8aa3b, v3
	v_exp_f32_e32 v48, v48
	s_nop 0
	v_add_f32_e32 v48, 1.0, v48
	v_div_scale_f32 v49, s[0:1], v48, v48, v3
	s_nop 0
	v_rcp_f32_e32 v49, v48
	s_nop 0
	v_mul_f32_e32 v3, v3, v49
	v_mul_f32_e32 v3, v47, v3
	v_cvt_pk_bf16_f32 v3, v3, s0
	ds_write_b16 v1, v3 offset:5168
	ds_read_u16 v3, v1 offset:6528
	v_mul_f32_e32 v47, v126, v23
	v_mul_f32_e32 v47, v47, v232
	s_waitcnt lgkmcnt(0)
	v_lshlrev_b32_e32 v3, 16, v3
	v_mul_f32_e32 v48, 0xbfb8aa3b, v3
	v_exp_f32_e32 v48, v48
	s_nop 0
	v_add_f32_e32 v48, 1.0, v48
	v_div_scale_f32 v49, s[0:1], v48, v48, v3
	s_nop 0
	v_rcp_f32_e32 v49, v48
	s_nop 0
	v_mul_f32_e32 v3, v3, v49
	v_mul_f32_e32 v3, v47, v3
	v_cvt_pk_bf16_f32 v3, v3, s0
	ds_write_b16 v1, v3 offset:6528
	ds_read_u16 v3, v1 offset:6800
	v_mul_f32_e32 v47, v125, v22
	v_mul_f32_e32 v47, v47, v232
	s_waitcnt lgkmcnt(0)
; #define LAS __attribute__((address_space(3)))
; DI unsigned cvtpk(float lo, float hi) { f32x2 v = {lo, hi}; bf16x2_t b = __builtin_convertvector(v, bf16x2_t); return __builtin_bit_cast(unsigned, b); }
; DI float bf2f(bf16 b) { return __uint_as_float(((unsigned)b) << 16); }
; DI float siluf_(float x) { return x / (1.f + __expf(-x)); }
; DI void gla_stage3(const Ctx& c0, int layer, int unit, int cb, LAS unsigned char* lds) {
;     ...
; #pragma unroll
;     for (int vb = 0; vb < 4; ++vb) { const float g = gn[32 * vb + r];
; #pragma unroll
;         for (int rg = 0; rg < 16; ++rg) { LAS bf16* e = (LAS bf16*)(R + (4 * hi) * G3_PITCH + r * 2 + ((rg & 3) + 8 * (rg >> 2)) * G3_PITCH + 64 * vb);
;             const float z = bf2f(*e);
;             *e = (bf16)(cvtpk(o[vb][rg] * rs[rg] * g * siluf_(z), 0.f) & 0xffffu); }
;         asm volatile("" ::: "memory"); }
	v_lshlrev_b32_e32 v3, 16, v3
	v_mul_f32_e32 v48, 0xbfb8aa3b, v3
	v_exp_f32_e32 v48, v48
	s_nop 0
	v_add_f32_e32 v48, 1.0, v48
	v_div_scale_f32 v49, s[0:1], v48, v48, v3
	s_nop 0
	v_rcp_f32_e32 v49, v48
	s_nop 0
	v_mul_f32_e32 v3, v3, v49
	v_mul_f32_e32 v3, v47, v3
	v_cvt_pk_bf16_f32 v3, v3, s0
	ds_write_b16 v1, v3 offset:6800
	ds_read_u16 v3, v1 offset:7072
	v_mul_f32_e32 v47, v124, v21
	v_mul_f32_e32 v47, v47, v232
	s_waitcnt lgkmcnt(0)
	v_lshlrev_b32_e32 v3, 16, v3
	v_mul_f32_e32 v48, 0xbfb8aa3b, v3
	v_exp_f32_e32 v48, v48
	s_nop 0
	v_add_f32_e32 v48, 1.0, v48
	v_div_scale_f32 v49, s[0:1], v48, v48, v3
	s_nop 0
	v_rcp_f32_e32 v49, v48
	s_nop 0
	v_mul_f32_e32 v3, v3, v49
	v_mul_f32_e32 v3, v47, v3
	v_cvt_pk_bf16_f32 v3, v3, s0
	ds_write_b16 v1, v3 offset:7072
	ds_read_u16 v3, v1 offset:7344
	v_mul_f32_e32 v47, v123, v20
	v_mul_f32_e32 v2, v47, v232
	s_waitcnt lgkmcnt(0)
	v_lshlrev_b32_e32 v3, 16, v3
	v_mul_f32_e32 v47, 0xbfb8aa3b, v3
	v_exp_f32_e32 v47, v47
	s_nop 0
	v_add_f32_e32 v47, 1.0, v47
	v_div_scale_f32 v48, s[0:1], v47, v47, v3
	s_nop 0
	v_rcp_f32_e32 v48, v47
	s_nop 0
	v_mul_f32_e32 v3, v3, v48
	v_mul_f32_e32 v2, v2, v3
	v_cvt_pk_bf16_f32 v2, v2, s0
	ds_write_b16 v1, v2 offset:7344
	ds_read_u16 v3, v1 offset:64
	v_mul_f32_e32 v47, v122, v46
	s_waitcnt lgkmcnt(0)
	v_lshlrev_b32_e32 v3, 16, v3
	v_mul_f32_e32 v48, 0xbfb8aa3b, v3
	v_exp_f32_e32 v48, v48
	s_waitcnt vmcnt(0)
	v_mul_f32_e32 v47, v47, v234
	v_add_f32_e32 v48, 1.0, v48
	v_div_scale_f32 v49, s[0:1], v48, v48, v3
	s_nop 0
	v_rcp_f32_e32 v49, v48
	s_nop 0
	v_mul_f32_e32 v3, v3, v49
	v_mul_f32_e32 v3, v47, v3
	v_cvt_pk_bf16_f32 v3, v3, s0
	ds_write_b16 v1, v3 offset:64
	ds_read_u16 v3, v1 offset:336
	v_mul_f32_e32 v47, v121, v45
	v_mul_f32_e32 v47, v47, v234
	s_waitcnt lgkmcnt(0)
	v_lshlrev_b32_e32 v3, 16, v3
	v_mul_f32_e32 v48, 0xbfb8aa3b, v3
	v_exp_f32_e32 v48, v48
	s_nop 0
	v_add_f32_e32 v48, 1.0, v48
	v_div_scale_f32 v49, s[0:1], v48, v48, v3
	s_nop 0
	v_rcp_f32_e32 v49, v48
	s_nop 0
	v_mul_f32_e32 v3, v3, v49
	v_mul_f32_e32 v3, v47, v3
	v_cvt_pk_bf16_f32 v3, v3, s0
	ds_write_b16 v1, v3 offset:336
	ds_read_u16 v3, v1 offset:608
	v_mul_f32_e32 v47, v120, v44
	v_mul_f32_e32 v47, v47, v234
	s_waitcnt lgkmcnt(0)
	v_lshlrev_b32_e32 v3, 16, v3
	v_mul_f32_e32 v48, 0xbfb8aa3b, v3
	v_exp_f32_e32 v48, v48
	s_nop 0
	v_add_f32_e32 v48, 1.0, v48
	v_div_scale_f32 v49, s[0:1], v48, v48, v3
	s_nop 0
	v_rcp_f32_e32 v49, v48
	s_nop 0
	v_mul_f32_e32 v3, v3, v49
	v_mul_f32_e32 v3, v47, v3
	v_cvt_pk_bf16_f32 v3, v3, s0
	ds_write_b16 v1, v3 offset:608
	ds_read_u16 v3, v1 offset:880
	v_mul_f32_e32 v47, v119, v43
	v_mul_f32_e32 v47, v47, v234
	s_waitcnt lgkmcnt(0)
	v_lshlrev_b32_e32 v3, 16, v3
	v_mul_f32_e32 v48, 0xbfb8aa3b, v3
	v_exp_f32_e32 v48, v48
	s_nop 0
	v_add_f32_e32 v48, 1.0, v48
	v_div_scale_f32 v49, s[0:1], v48, v48, v3
	s_nop 0
	v_rcp_f32_e32 v49, v48
	s_nop 0
	v_mul_f32_e32 v3, v3, v49
	v_mul_f32_e32 v3, v47, v3
	v_cvt_pk_bf16_f32 v3, v3, s0
	ds_write_b16 v1, v3 offset:880
	ds_read_u16 v3, v1 offset:2240
	v_mul_f32_e32 v47, v118, v42
	v_mul_f32_e32 v47, v47, v234
	s_waitcnt lgkmcnt(0)
	v_lshlrev_b32_e32 v3, 16, v3
	v_mul_f32_e32 v48, 0xbfb8aa3b, v3
	v_exp_f32_e32 v48, v48
	s_nop 0
	v_add_f32_e32 v48, 1.0, v48
	v_div_scale_f32 v49, s[0:1], v48, v48, v3
	s_nop 0
	v_rcp_f32_e32 v49, v48
	s_nop 0
	v_mul_f32_e32 v3, v3, v49
	v_mul_f32_e32 v3, v47, v3
	v_cvt_pk_bf16_f32 v3, v3, s0
	ds_write_b16 v1, v3 offset:2240
	ds_read_u16 v3, v1 offset:2512
	v_mul_f32_e32 v47, v117, v41
	v_mul_f32_e32 v47, v47, v234
	s_waitcnt lgkmcnt(0)
	v_lshlrev_b32_e32 v3, 16, v3
	v_mul_f32_e32 v48, 0xbfb8aa3b, v3
	v_exp_f32_e32 v48, v48
	s_nop 0
	v_add_f32_e32 v48, 1.0, v48
	v_div_scale_f32 v49, s[0:1], v48, v48, v3
	s_nop 0
	v_rcp_f32_e32 v49, v48
	s_nop 0
	v_mul_f32_e32 v3, v3, v49
	v_mul_f32_e32 v3, v47, v3
	v_cvt_pk_bf16_f32 v3, v3, s0
	ds_write_b16 v1, v3 offset:2512
	ds_read_u16 v3, v1 offset:2784
	v_mul_f32_e32 v47, v116, v40
	v_mul_f32_e32 v47, v47, v234
	s_waitcnt lgkmcnt(0)
	v_lshlrev_b32_e32 v3, 16, v3
	v_mul_f32_e32 v48, 0xbfb8aa3b, v3
	v_exp_f32_e32 v48, v48
	s_nop 0
	v_add_f32_e32 v48, 1.0, v48
	v_div_scale_f32 v49, s[0:1], v48, v48, v3
	s_nop 0
	v_rcp_f32_e32 v49, v48
	s_nop 0
	v_mul_f32_e32 v3, v3, v49
	v_mul_f32_e32 v3, v47, v3
	v_cvt_pk_bf16_f32 v3, v3, s0
	ds_write_b16 v1, v3 offset:2784
	ds_read_u16 v3, v1 offset:3056
	v_mul_f32_e32 v47, v115, v35
	v_mul_f32_e32 v47, v47, v234
	s_waitcnt lgkmcnt(0)
	v_lshlrev_b32_e32 v3, 16, v3
	v_mul_f32_e32 v48, 0xbfb8aa3b, v3
	v_exp_f32_e32 v48, v48
	s_nop 0
	v_add_f32_e32 v48, 1.0, v48
	v_div_scale_f32 v49, s[0:1], v48, v48, v3
	s_nop 0
	v_rcp_f32_e32 v49, v48
	s_nop 0
	v_mul_f32_e32 v3, v3, v49
	v_mul_f32_e32 v3, v47, v3
	v_cvt_pk_bf16_f32 v3, v3, s0
	ds_write_b16 v1, v3 offset:3056
	ds_read_u16 v3, v1 offset:4416
	v_mul_f32_e32 v47, v114, v31
	v_mul_f32_e32 v47, v47, v234
	s_waitcnt lgkmcnt(0)
	v_lshlrev_b32_e32 v3, 16, v3
	v_mul_f32_e32 v48, 0xbfb8aa3b, v3
	v_exp_f32_e32 v48, v48
	s_nop 0
	v_add_f32_e32 v48, 1.0, v48
	v_div_scale_f32 v49, s[0:1], v48, v48, v3
	s_nop 0
	v_rcp_f32_e32 v49, v48
	s_nop 0
	v_mul_f32_e32 v3, v3, v49
	v_mul_f32_e32 v3, v47, v3
	v_cvt_pk_bf16_f32 v3, v3, s0
	ds_write_b16 v1, v3 offset:4416
	ds_read_u16 v3, v1 offset:4688
	v_mul_f32_e32 v47, v113, v27
	v_mul_f32_e32 v47, v47, v234
	s_waitcnt lgkmcnt(0)
	v_lshlrev_b32_e32 v3, 16, v3
	v_mul_f32_e32 v48, 0xbfb8aa3b, v3
	v_exp_f32_e32 v48, v48
	s_nop 0
	v_add_f32_e32 v48, 1.0, v48
	v_div_scale_f32 v49, s[0:1], v48, v48, v3
	s_nop 0
	v_rcp_f32_e32 v49, v48
	s_nop 0
	v_mul_f32_e32 v3, v3, v49
	v_mul_f32_e32 v3, v47, v3
	v_cvt_pk_bf16_f32 v3, v3, s0
	ds_write_b16 v1, v3 offset:4688
	ds_read_u16 v3, v1 offset:4960
	v_mul_f32_e32 v47, v112, v25
	v_mul_f32_e32 v47, v47, v234
	s_waitcnt lgkmcnt(0)
; #define LAS __attribute__((address_space(3)))
; DI unsigned cvtpk(float lo, float hi) { f32x2 v = {lo, hi}; bf16x2_t b = __builtin_convertvector(v, bf16x2_t); return __builtin_bit_cast(unsigned, b); }
; DI float bf2f(bf16 b) { return __uint_as_float(((unsigned)b) << 16); }
; DI float siluf_(float x) { return x / (1.f + __expf(-x)); }
; DI void gla_stage3(const Ctx& c0, int layer, int unit, int cb, LAS unsigned char* lds) {
;     ...
; #pragma unroll
;     for (int vb = 0; vb < 4; ++vb) { const float g = gn[32 * vb + r];
; #pragma unroll
;         for (int rg = 0; rg < 16; ++rg) { LAS bf16* e = (LAS bf16*)(R + (4 * hi) * G3_PITCH + r * 2 + ((rg & 3) + 8 * (rg >> 2)) * G3_PITCH + 64 * vb);
;             const float z = bf2f(*e);
;             *e = (bf16)(cvtpk(o[vb][rg] * rs[rg] * g * siluf_(z), 0.f) & 0xffffu); }
;         asm volatile("" ::: "memory"); }
	v_lshlrev_b32_e32 v3, 16, v3
	v_mul_f32_e32 v48, 0xbfb8aa3b, v3
	v_exp_f32_e32 v48, v48
	s_nop 0
	v_add_f32_e32 v48, 1.0, v48
	v_div_scale_f32 v49, s[0:1], v48, v48, v3
	s_nop 0
	v_rcp_f32_e32 v49, v48
	s_nop 0
	v_mul_f32_e32 v3, v3, v49
	v_mul_f32_e32 v3, v47, v3
	v_cvt_pk_bf16_f32 v3, v3, s0
	ds_write_b16 v1, v3 offset:4960
	ds_read_u16 v3, v1 offset:5232
	v_mul_f32_e32 v47, v111, v24
	v_mul_f32_e32 v47, v47, v234
	s_waitcnt lgkmcnt(0)
	v_lshlrev_b32_e32 v3, 16, v3
	v_mul_f32_e32 v48, 0xbfb8aa3b, v3
	v_exp_f32_e32 v48, v48
	s_nop 0
	v_add_f32_e32 v48, 1.0, v48
	v_div_scale_f32 v49, s[0:1], v48, v48, v3
	s_nop 0
	v_rcp_f32_e32 v49, v48
	s_nop 0
	v_mul_f32_e32 v3, v3, v49
	v_mul_f32_e32 v3, v47, v3
	v_cvt_pk_bf16_f32 v3, v3, s0
	ds_write_b16 v1, v3 offset:5232
	ds_read_u16 v3, v1 offset:6592
	v_mul_f32_e32 v47, v110, v23
	v_mul_f32_e32 v47, v47, v234
	s_waitcnt lgkmcnt(0)
	v_lshlrev_b32_e32 v3, 16, v3
	v_mul_f32_e32 v48, 0xbfb8aa3b, v3
	v_exp_f32_e32 v48, v48
	s_nop 0
	v_add_f32_e32 v48, 1.0, v48
	v_div_scale_f32 v49, s[0:1], v48, v48, v3
	s_nop 0
	v_rcp_f32_e32 v49, v48
	s_nop 0
	v_mul_f32_e32 v3, v3, v49
	v_mul_f32_e32 v3, v47, v3
	v_cvt_pk_bf16_f32 v3, v3, s0
	ds_write_b16 v1, v3 offset:6592
	ds_read_u16 v3, v1 offset:6864
	v_mul_f32_e32 v47, v109, v22
	v_mul_f32_e32 v47, v47, v234
	s_waitcnt lgkmcnt(0)
	v_lshlrev_b32_e32 v3, 16, v3
	v_mul_f32_e32 v48, 0xbfb8aa3b, v3
	v_exp_f32_e32 v48, v48
	s_nop 0
	v_add_f32_e32 v48, 1.0, v48
	v_div_scale_f32 v49, s[0:1], v48, v48, v3
	s_nop 0
	v_rcp_f32_e32 v49, v48
	s_nop 0
	v_mul_f32_e32 v3, v3, v49
	v_mul_f32_e32 v3, v47, v3
	v_cvt_pk_bf16_f32 v3, v3, s0
	ds_write_b16 v1, v3 offset:6864
	ds_read_u16 v3, v1 offset:7136
	v_mul_f32_e32 v47, v108, v21
	v_mul_f32_e32 v47, v47, v234
	s_waitcnt lgkmcnt(0)
	v_lshlrev_b32_e32 v3, 16, v3
	v_mul_f32_e32 v48, 0xbfb8aa3b, v3
	v_exp_f32_e32 v48, v48
	s_nop 0
	v_add_f32_e32 v48, 1.0, v48
	v_div_scale_f32 v49, s[0:1], v48, v48, v3
	s_nop 0
	v_rcp_f32_e32 v49, v48
	s_nop 0
	v_mul_f32_e32 v3, v3, v49
	v_mul_f32_e32 v3, v47, v3
	v_cvt_pk_bf16_f32 v3, v3, s0
	ds_write_b16 v1, v3 offset:7136
	ds_read_u16 v3, v1 offset:7408
	v_mul_f32_e32 v47, v107, v20
	v_mul_f32_e32 v2, v47, v234
	s_waitcnt lgkmcnt(0)
	v_lshlrev_b32_e32 v3, 16, v3
	v_mul_f32_e32 v47, 0xbfb8aa3b, v3
	v_exp_f32_e32 v47, v47
	s_nop 0
	v_add_f32_e32 v47, 1.0, v47
	v_div_scale_f32 v48, s[0:1], v47, v47, v3
	s_nop 0
	v_rcp_f32_e32 v48, v47
	s_nop 0
	v_mul_f32_e32 v3, v3, v48
	v_mul_f32_e32 v2, v2, v3
	v_cvt_pk_bf16_f32 v2, v2, s0
	ds_write_b16 v1, v2 offset:7408
	ds_read_u16 v3, v1 offset:128
	v_mul_f32_e32 v47, v106, v46
	s_waitcnt lgkmcnt(0)
	v_lshlrev_b32_e32 v3, 16, v3
	v_mul_f32_e32 v48, 0xbfb8aa3b, v3
	v_exp_f32_e32 v48, v48
	s_waitcnt vmcnt(0)
	v_mul_f32_e32 v47, v47, v236
	v_add_f32_e32 v48, 1.0, v48
	v_div_scale_f32 v49, s[0:1], v48, v48, v3
	v_mul_f32_e32 v39, v39, v236
	v_mul_f32_e32 v38, v38, v236
	v_mul_f32_e32 v37, v37, v236
	v_rcp_f32_e32 v49, v48
	s_nop 0
	v_mul_f32_e32 v3, v3, v49
	v_mul_f32_e32 v3, v47, v3
	v_cvt_pk_bf16_f32 v3, v3, s0
	ds_write_b16 v1, v3 offset:128
	ds_read_u16 v3, v1 offset:400
	v_mul_f32_e32 v47, v105, v45
	v_mul_f32_e32 v47, v47, v236
	v_mul_f32_e32 v36, v36, v236
	v_mul_f32_e32 v34, v34, v236
	s_waitcnt lgkmcnt(0)
	v_lshlrev_b32_e32 v3, 16, v3
	v_mul_f32_e32 v48, 0xbfb8aa3b, v3
	v_exp_f32_e32 v48, v48
	v_mul_f32_e32 v33, v33, v236
	v_mul_f32_e32 v32, v32, v236
	v_mul_f32_e32 v30, v30, v236
	v_add_f32_e32 v48, 1.0, v48
	v_div_scale_f32 v49, s[0:1], v48, v48, v3
	v_mul_f32_e32 v29, v29, v236
	v_mul_f32_e32 v28, v28, v236
	v_rcp_f32_e32 v49, v48
	s_nop 0
	v_mul_f32_e32 v3, v3, v49
	v_mul_f32_e32 v3, v47, v3
	v_cvt_pk_bf16_f32 v3, v3, s0
	ds_write_b16 v1, v3 offset:400
	ds_read_u16 v3, v1 offset:672
	v_mul_f32_e32 v47, v104, v44
	v_mul_f32_e32 v47, v47, v236
	s_waitcnt lgkmcnt(0)
	v_lshlrev_b32_e32 v3, 16, v3
	v_mul_f32_e32 v48, 0xbfb8aa3b, v3
	v_exp_f32_e32 v48, v48
	s_nop 0
	v_add_f32_e32 v48, 1.0, v48
	v_div_scale_f32 v49, s[0:1], v48, v48, v3
	s_nop 0
	v_rcp_f32_e32 v49, v48
	s_nop 0
	v_mul_f32_e32 v3, v3, v49
	v_mul_f32_e32 v3, v47, v3
	v_cvt_pk_bf16_f32 v3, v3, s0
	ds_write_b16 v1, v3 offset:672
	ds_read_u16 v3, v1 offset:944
	v_mul_f32_e32 v47, v103, v43
	v_mul_f32_e32 v47, v47, v236
	s_waitcnt lgkmcnt(0)
	v_lshlrev_b32_e32 v3, 16, v3
	v_mul_f32_e32 v48, 0xbfb8aa3b, v3
	v_exp_f32_e32 v48, v48
	s_nop 0
	v_add_f32_e32 v48, 1.0, v48
	v_div_scale_f32 v49, s[0:1], v48, v48, v3
	s_nop 0
	v_rcp_f32_e32 v49, v48
	s_nop 0
	v_mul_f32_e32 v3, v3, v49
	v_mul_f32_e32 v3, v47, v3
	v_cvt_pk_bf16_f32 v3, v3, s0
	ds_write_b16 v1, v3 offset:944
	ds_read_u16 v3, v1 offset:2304
	v_mul_f32_e32 v47, v102, v42
	v_mul_f32_e32 v47, v47, v236
	v_mul_f32_e32 v2, v26, v236
	s_waitcnt lgkmcnt(0)
	v_lshlrev_b32_e32 v3, 16, v3
	v_mul_f32_e32 v48, 0xbfb8aa3b, v3
	v_exp_f32_e32 v48, v48
	s_nop 0
	v_add_f32_e32 v48, 1.0, v48
	v_div_scale_f32 v49, s[0:1], v48, v48, v3
	s_nop 0
	v_rcp_f32_e32 v49, v48
	s_nop 0
	v_mul_f32_e32 v3, v3, v49
	v_mul_f32_e32 v3, v47, v3
	v_cvt_pk_bf16_f32 v3, v3, s0
	ds_write_b16 v1, v3 offset:2304
	ds_read_u16 v3, v1 offset:2576
	s_waitcnt lgkmcnt(0)
	v_lshlrev_b32_e32 v3, 16, v3
	v_mul_f32_e32 v47, 0xbfb8aa3b, v3
	v_exp_f32_e32 v47, v47
	s_nop 0
	v_add_f32_e32 v47, 1.0, v47
	v_div_scale_f32 v48, s[0:1], v47, v47, v3
	s_nop 0
	v_rcp_f32_e32 v48, v47
	s_nop 0
	v_mul_f32_e32 v3, v3, v48
	v_mul_f32_e32 v3, v39, v3
	v_cvt_pk_bf16_f32 v3, v3, s0
	ds_write_b16 v1, v3 offset:2576
	ds_read_u16 v3, v1 offset:2848
	s_waitcnt lgkmcnt(0)
; #define LAS __attribute__((address_space(3)))
; DI unsigned cvtpk(float lo, float hi) { f32x2 v = {lo, hi}; bf16x2_t b = __builtin_convertvector(v, bf16x2_t); return __builtin_bit_cast(unsigned, b); }
; DI float bf2f(bf16 b) { return __uint_as_float(((unsigned)b) << 16); }
; DI float siluf_(float x) { return x / (1.f + __expf(-x)); }
; DI void gla_stage3(const Ctx& c0, int layer, int unit, int cb, LAS unsigned char* lds) {
;     ...
; #pragma unroll
;     for (int vb = 0; vb < 4; ++vb) { const float g = gn[32 * vb + r];
; #pragma unroll
;         for (int rg = 0; rg < 16; ++rg) { LAS bf16* e = (LAS bf16*)(R + (4 * hi) * G3_PITCH + r * 2 + ((rg & 3) + 8 * (rg >> 2)) * G3_PITCH + 64 * vb);
;             const float z = bf2f(*e);
;             *e = (bf16)(cvtpk(o[vb][rg] * rs[rg] * g * siluf_(z), 0.f) & 0xffffu); }
;         asm volatile("" ::: "memory"); }
	v_lshlrev_b32_e32 v3, 16, v3
	v_mul_f32_e32 v39, 0xbfb8aa3b, v3
	v_exp_f32_e32 v39, v39
	s_nop 0
	v_add_f32_e32 v39, 1.0, v39
	v_div_scale_f32 v47, s[0:1], v39, v39, v3
	s_nop 0
	v_rcp_f32_e32 v47, v39
	s_nop 0
	v_mul_f32_e32 v3, v3, v47
	v_mul_f32_e32 v3, v38, v3
	v_cvt_pk_bf16_f32 v3, v3, s0
	ds_write_b16 v1, v3 offset:2848
	ds_read_u16 v3, v1 offset:3120
	s_waitcnt lgkmcnt(0)
	v_lshlrev_b32_e32 v3, 16, v3
	v_mul_f32_e32 v38, 0xbfb8aa3b, v3
	v_exp_f32_e32 v38, v38
	s_nop 0
	v_add_f32_e32 v38, 1.0, v38
	v_div_scale_f32 v39, s[0:1], v38, v38, v3
	s_nop 0
	v_rcp_f32_e32 v39, v38
	s_nop 0
	v_mul_f32_e32 v3, v3, v39
	v_mul_f32_e32 v3, v37, v3
	v_cvt_pk_bf16_f32 v3, v3, s0
	ds_write_b16 v1, v3 offset:3120
	ds_read_u16 v3, v1 offset:4480
	s_waitcnt lgkmcnt(0)
	v_lshlrev_b32_e32 v3, 16, v3
	v_mul_f32_e32 v37, 0xbfb8aa3b, v3
	v_exp_f32_e32 v37, v37
	s_nop 0
	v_add_f32_e32 v37, 1.0, v37
	v_div_scale_f32 v38, s[0:1], v37, v37, v3
	s_nop 0
	v_rcp_f32_e32 v38, v37
	s_nop 0
	v_mul_f32_e32 v3, v3, v38
	v_mul_f32_e32 v3, v36, v3
	v_cvt_pk_bf16_f32 v3, v3, s0
	ds_write_b16 v1, v3 offset:4480
	ds_read_u16 v3, v1 offset:4752
	s_waitcnt lgkmcnt(0)
	v_lshlrev_b32_e32 v3, 16, v3
	v_mul_f32_e32 v36, 0xbfb8aa3b, v3
	v_exp_f32_e32 v36, v36
	s_nop 0
	v_add_f32_e32 v36, 1.0, v36
	v_div_scale_f32 v37, s[0:1], v36, v36, v3
	s_nop 0
	v_rcp_f32_e32 v37, v36
	s_nop 0
	v_mul_f32_e32 v3, v3, v37
	v_mul_f32_e32 v3, v34, v3
	v_cvt_pk_bf16_f32 v3, v3, s0
	ds_write_b16 v1, v3 offset:4752
	ds_read_u16 v3, v1 offset:5024
	s_waitcnt lgkmcnt(0)
	v_lshlrev_b32_e32 v3, 16, v3
	v_mul_f32_e32 v34, 0xbfb8aa3b, v3
	v_exp_f32_e32 v34, v34
	s_nop 0
	v_add_f32_e32 v34, 1.0, v34
	v_div_scale_f32 v36, s[0:1], v34, v34, v3
	s_nop 0
	v_rcp_f32_e32 v36, v34
	s_nop 0
	v_mul_f32_e32 v3, v3, v36
	v_mul_f32_e32 v3, v33, v3
	v_cvt_pk_bf16_f32 v3, v3, s0
	ds_write_b16 v1, v3 offset:5024
	ds_read_u16 v3, v1 offset:5296
	s_waitcnt lgkmcnt(0)
	v_lshlrev_b32_e32 v3, 16, v3
	v_mul_f32_e32 v33, 0xbfb8aa3b, v3
	v_exp_f32_e32 v33, v33
	s_nop 0
	v_add_f32_e32 v33, 1.0, v33
	v_div_scale_f32 v34, s[0:1], v33, v33, v3
	s_nop 0
	v_rcp_f32_e32 v34, v33
	s_nop 0
	v_mul_f32_e32 v3, v3, v34
	v_mul_f32_e32 v3, v32, v3
	v_cvt_pk_bf16_f32 v3, v3, s0
	ds_write_b16 v1, v3 offset:5296
	ds_read_u16 v3, v1 offset:6656
	s_waitcnt lgkmcnt(0)
	v_lshlrev_b32_e32 v3, 16, v3
	v_mul_f32_e32 v32, 0xbfb8aa3b, v3
	v_exp_f32_e32 v32, v32
	s_nop 0
	v_add_f32_e32 v32, 1.0, v32
	v_div_scale_f32 v33, s[0:1], v32, v32, v3
	s_nop 0
	v_rcp_f32_e32 v33, v32
	s_nop 0
	v_mul_f32_e32 v3, v3, v33
	v_mul_f32_e32 v3, v30, v3
	v_cvt_pk_bf16_f32 v3, v3, s0
	ds_write_b16 v1, v3 offset:6656
	ds_read_u16 v3, v1 offset:6928
	s_waitcnt lgkmcnt(0)
	v_lshlrev_b32_e32 v3, 16, v3
	v_mul_f32_e32 v30, 0xbfb8aa3b, v3
	v_exp_f32_e32 v30, v30
	s_nop 0
	v_add_f32_e32 v30, 1.0, v30
	v_div_scale_f32 v32, s[0:1], v30, v30, v3
	s_nop 0
	v_rcp_f32_e32 v32, v30
	s_nop 0
	v_mul_f32_e32 v3, v3, v32
	v_mul_f32_e32 v3, v29, v3
	v_cvt_pk_bf16_f32 v3, v3, s0
	ds_write_b16 v1, v3 offset:6928
	ds_read_u16 v3, v1 offset:7200
	s_waitcnt lgkmcnt(0)
	v_lshlrev_b32_e32 v3, 16, v3
	v_mul_f32_e32 v29, 0xbfb8aa3b, v3
	v_exp_f32_e32 v29, v29
	s_nop 0
	v_add_f32_e32 v29, 1.0, v29
	v_div_scale_f32 v30, s[0:1], v29, v29, v3
	s_nop 0
	v_rcp_f32_e32 v30, v29
	s_nop 0
	v_mul_f32_e32 v3, v3, v30
	v_mul_f32_e32 v3, v28, v3
	v_cvt_pk_bf16_f32 v3, v3, s0
	ds_write_b16 v1, v3 offset:7200
	ds_read_u16 v3, v1 offset:7472
	s_waitcnt lgkmcnt(0)
	v_lshlrev_b32_e32 v3, 16, v3
	v_mul_f32_e32 v26, 0xbfb8aa3b, v3
	v_exp_f32_e32 v26, v26
	s_nop 0
	v_add_f32_e32 v26, 1.0, v26
	v_div_scale_f32 v28, s[0:1], v26, v26, v3
	s_nop 0
	v_rcp_f32_e32 v28, v26
	s_nop 0
	v_mul_f32_e32 v3, v3, v28
	v_mul_f32_e32 v2, v2, v3
	v_cvt_pk_bf16_f32 v2, v2, s0
	ds_write_b16 v1, v2 offset:7472
	ds_read_u16 v3, v1 offset:192
	s_waitcnt lgkmcnt(0)
	v_lshlrev_b32_e32 v3, 16, v3
	v_mul_f32_e32 v26, 0xbfb8aa3b, v3
	v_exp_f32_e32 v26, v26
	s_waitcnt vmcnt(31)
	v_mul_f32_e32 v19, v19, v238
	v_add_f32_e32 v26, 1.0, v26
	v_div_scale_f32 v28, s[0:1], v26, v26, v3
	v_mul_f32_e32 v18, v18, v238
	v_mul_f32_e32 v17, v17, v238
	v_mul_f32_e32 v16, v16, v238
	v_rcp_f32_e32 v28, v26
	s_nop 0
	v_mul_f32_e32 v3, v3, v28
	v_mul_f32_e32 v3, v19, v3
	v_cvt_pk_bf16_f32 v3, v3, s0
	ds_write_b16 v1, v3 offset:192
	ds_read_u16 v3, v1 offset:464
	v_mul_f32_e32 v15, v15, v238
	v_mul_f32_e32 v14, v14, v238
	v_mul_f32_e32 v13, v13, v238
	v_mul_f32_e32 v12, v12, v238
	s_waitcnt lgkmcnt(0)
	v_lshlrev_b32_e32 v3, 16, v3
	v_mul_f32_e32 v19, 0xbfb8aa3b, v3
	v_exp_f32_e32 v19, v19
	v_mul_f32_e32 v11, v11, v238
	v_mul_f32_e32 v10, v10, v238
	v_mul_f32_e32 v9, v9, v238
	v_add_f32_e32 v19, 1.0, v19
	v_div_scale_f32 v26, s[0:1], v19, v19, v3
	v_mul_f32_e32 v8, v8, v238
	v_mul_f32_e32 v7, v7, v238
	v_mul_f32_e32 v6, v6, v238
	v_rcp_f32_e32 v26, v19
	s_nop 0
	v_mul_f32_e32 v3, v3, v26
	v_mul_f32_e32 v3, v18, v3
	v_cvt_pk_bf16_f32 v3, v3, s0
	ds_write_b16 v1, v3 offset:464
	ds_read_u16 v3, v1 offset:736
	v_mul_f32_e32 v5, v5, v238
	v_mul_f32_e32 v2, v4, v238
	s_waitcnt lgkmcnt(0)
	v_lshlrev_b32_e32 v3, 16, v3
	v_mul_f32_e32 v18, 0xbfb8aa3b, v3
	v_exp_f32_e32 v18, v18
	s_nop 0
	v_add_f32_e32 v18, 1.0, v18
	v_div_scale_f32 v19, s[0:1], v18, v18, v3
	s_nop 0
	v_rcp_f32_e32 v19, v18
	s_nop 0
	v_mul_f32_e32 v3, v3, v19
	v_mul_f32_e32 v3, v17, v3
	v_cvt_pk_bf16_f32 v3, v3, s0
	ds_write_b16 v1, v3 offset:736
	ds_read_u16 v3, v1 offset:1008
	s_waitcnt lgkmcnt(0)
	v_lshlrev_b32_e32 v3, 16, v3
	v_mul_f32_e32 v17, 0xbfb8aa3b, v3
	v_exp_f32_e32 v17, v17
	s_nop 0
	v_add_f32_e32 v17, 1.0, v17
	v_div_scale_f32 v18, s[0:1], v17, v17, v3
	s_nop 0
	v_rcp_f32_e32 v18, v17
	s_nop 0
	v_mul_f32_e32 v3, v3, v18
	v_mul_f32_e32 v3, v16, v3
	v_cvt_pk_bf16_f32 v3, v3, s0
	ds_write_b16 v1, v3 offset:1008
	ds_read_u16 v3, v1 offset:2368
	s_waitcnt lgkmcnt(0)
; #define LAS __attribute__((address_space(3)))
; #define LDS_WAIT() asm volatile("s_waitcnt lgkmcnt(0)" ::: "memory")
; DI unsigned cvtpk(float lo, float hi) { f32x2 v = {lo, hi}; bf16x2_t b = __builtin_convertvector(v, bf16x2_t); return __builtin_bit_cast(unsigned, b); }
; DI float bf2f(bf16 b) { return __uint_as_float(((unsigned)b) << 16); }
; DI float siluf_(float x) { return x / (1.f + __expf(-x)); }
; DI void g3_tile_out(bf16* g, const LAS unsigned char* R, int lane) {
;     LDS_WAIT();
; #pragma unroll
;     for (int it = 0; it < 8; ++it) { const int row = 4 * it + (lane >> 4), ch = lane & 15;
;         *(u32x4*)(g + (size_t)row * 512 + ch * 8) = *(const LAS u32x4*)(R + row * G3_PITCH + ch * 16); }
;     LDS_WAIT();
; }
; DI void gla_stage3(const Ctx& c0, int layer, int unit, int cb, LAS unsigned char* lds) {
;     ...
; #pragma unroll
;     for (int vb = 0; vb < 4; ++vb) { const float g = gn[32 * vb + r];
; #pragma unroll
;         for (int rg = 0; rg < 16; ++rg) { LAS bf16* e = (LAS bf16*)(R + (4 * hi) * G3_PITCH + r * 2 + ((rg & 3) + 8 * (rg >> 2)) * G3_PITCH + 64 * vb);
;             const float z = bf2f(*e);
;             *e = (bf16)(cvtpk(o[vb][rg] * rs[rg] * g * siluf_(z), 0.f) & 0xffffu); }
;         asm volatile("" ::: "memory"); }
;     g3_tile_out((bf16*)(c.ws + O_OGLA) + row0 * 512 + h * 128, R, lane);
	v_lshlrev_b32_e32 v3, 16, v3
	v_mul_f32_e32 v16, 0xbfb8aa3b, v3
	v_exp_f32_e32 v16, v16
	s_nop 0
	v_add_f32_e32 v16, 1.0, v16
	v_div_scale_f32 v17, s[0:1], v16, v16, v3
	s_nop 0
	v_rcp_f32_e32 v17, v16
	s_nop 0
	v_mul_f32_e32 v3, v3, v17
	v_mul_f32_e32 v3, v15, v3
	v_cvt_pk_bf16_f32 v3, v3, s0
	ds_write_b16 v1, v3 offset:2368
	ds_read_u16 v3, v1 offset:2640
	s_waitcnt lgkmcnt(0)
	v_lshlrev_b32_e32 v3, 16, v3
	v_mul_f32_e32 v15, 0xbfb8aa3b, v3
	v_exp_f32_e32 v15, v15
	s_nop 0
	v_add_f32_e32 v15, 1.0, v15
	v_div_scale_f32 v16, s[0:1], v15, v15, v3
	s_nop 0
	v_rcp_f32_e32 v16, v15
	s_nop 0
	v_mul_f32_e32 v3, v3, v16
	v_mul_f32_e32 v3, v14, v3
	v_cvt_pk_bf16_f32 v3, v3, s0
	ds_write_b16 v1, v3 offset:2640
	ds_read_u16 v3, v1 offset:2912
	s_waitcnt lgkmcnt(0)
	v_lshlrev_b32_e32 v3, 16, v3
	v_mul_f32_e32 v14, 0xbfb8aa3b, v3
	v_exp_f32_e32 v14, v14
	s_nop 0
	v_add_f32_e32 v14, 1.0, v14
	v_div_scale_f32 v15, s[0:1], v14, v14, v3
	s_nop 0
	v_rcp_f32_e32 v15, v14
	s_nop 0
	v_mul_f32_e32 v3, v3, v15
	v_mul_f32_e32 v3, v13, v3
	v_cvt_pk_bf16_f32 v3, v3, s0
	ds_write_b16 v1, v3 offset:2912
	ds_read_u16 v3, v1 offset:3184
	s_waitcnt lgkmcnt(0)
	v_lshlrev_b32_e32 v3, 16, v3
	v_mul_f32_e32 v13, 0xbfb8aa3b, v3
	v_exp_f32_e32 v13, v13
	s_nop 0
	v_add_f32_e32 v13, 1.0, v13
	v_div_scale_f32 v14, s[0:1], v13, v13, v3
	s_nop 0
	v_rcp_f32_e32 v14, v13
	s_nop 0
	v_mul_f32_e32 v3, v3, v14
	v_mul_f32_e32 v3, v12, v3
	v_cvt_pk_bf16_f32 v3, v3, s0
	ds_write_b16 v1, v3 offset:3184
	ds_read_u16 v3, v1 offset:4544
	s_waitcnt lgkmcnt(0)
	v_lshlrev_b32_e32 v3, 16, v3
	v_mul_f32_e32 v12, 0xbfb8aa3b, v3
	v_exp_f32_e32 v12, v12
	s_nop 0
	v_add_f32_e32 v12, 1.0, v12
	v_div_scale_f32 v13, s[0:1], v12, v12, v3
	s_nop 0
	v_rcp_f32_e32 v13, v12
	s_nop 0
	v_mul_f32_e32 v3, v3, v13
	v_mul_f32_e32 v3, v11, v3
	v_cvt_pk_bf16_f32 v3, v3, s0
	ds_write_b16 v1, v3 offset:4544
	ds_read_u16 v3, v1 offset:4816
	s_waitcnt lgkmcnt(0)
	v_lshlrev_b32_e32 v3, 16, v3
	v_mul_f32_e32 v11, 0xbfb8aa3b, v3
	v_exp_f32_e32 v11, v11
	s_nop 0
	v_add_f32_e32 v11, 1.0, v11
	v_div_scale_f32 v12, s[0:1], v11, v11, v3
	s_nop 0
	v_rcp_f32_e32 v12, v11
	s_nop 0
	v_mul_f32_e32 v3, v3, v12
	v_mul_f32_e32 v3, v10, v3
	v_cvt_pk_bf16_f32 v3, v3, s0
	ds_write_b16 v1, v3 offset:4816
	ds_read_u16 v3, v1 offset:5088
	s_waitcnt lgkmcnt(0)
	v_lshlrev_b32_e32 v3, 16, v3
	v_mul_f32_e32 v10, 0xbfb8aa3b, v3
	v_exp_f32_e32 v10, v10
	s_nop 0
	v_add_f32_e32 v10, 1.0, v10
	v_div_scale_f32 v11, s[0:1], v10, v10, v3
	s_nop 0
	v_rcp_f32_e32 v11, v10
	s_nop 0
	v_mul_f32_e32 v3, v3, v11
	v_mul_f32_e32 v3, v9, v3
	v_cvt_pk_bf16_f32 v3, v3, s0
	ds_write_b16 v1, v3 offset:5088
	ds_read_u16 v3, v1 offset:5360
	s_waitcnt lgkmcnt(0)
	v_lshlrev_b32_e32 v3, 16, v3
	v_mul_f32_e32 v9, 0xbfb8aa3b, v3
	v_exp_f32_e32 v9, v9
	s_nop 0
	v_add_f32_e32 v9, 1.0, v9
	v_div_scale_f32 v10, s[0:1], v9, v9, v3
	s_nop 0
	v_rcp_f32_e32 v10, v9
	s_nop 0
	v_mul_f32_e32 v3, v3, v10
	v_mul_f32_e32 v3, v8, v3
	v_cvt_pk_bf16_f32 v3, v3, s0
	ds_write_b16 v1, v3 offset:5360
	ds_read_u16 v3, v1 offset:6720
	s_waitcnt lgkmcnt(0)
	v_lshlrev_b32_e32 v3, 16, v3
	v_mul_f32_e32 v8, 0xbfb8aa3b, v3
	v_exp_f32_e32 v8, v8
	s_nop 0
	v_add_f32_e32 v8, 1.0, v8
	v_div_scale_f32 v9, s[0:1], v8, v8, v3
	s_nop 0
	v_rcp_f32_e32 v9, v8
	s_nop 0
	v_mul_f32_e32 v3, v3, v9
	v_mul_f32_e32 v3, v7, v3
	v_cvt_pk_bf16_f32 v3, v3, s0
	ds_write_b16 v1, v3 offset:6720
	ds_read_u16 v3, v1 offset:6992
	s_waitcnt lgkmcnt(0)
	v_lshlrev_b32_e32 v3, 16, v3
	v_mul_f32_e32 v7, 0xbfb8aa3b, v3
	v_exp_f32_e32 v7, v7
	s_nop 0
	v_add_f32_e32 v7, 1.0, v7
	v_div_scale_f32 v8, s[0:1], v7, v7, v3
	s_nop 0
	v_rcp_f32_e32 v8, v7
	s_nop 0
	v_mul_f32_e32 v3, v3, v8
	v_mul_f32_e32 v3, v6, v3
	v_cvt_pk_bf16_f32 v3, v3, s0
	ds_write_b16 v1, v3 offset:6992
	ds_read_u16 v3, v1 offset:7264
	s_waitcnt lgkmcnt(0)
	v_lshlrev_b32_e32 v3, 16, v3
	v_mul_f32_e32 v6, 0xbfb8aa3b, v3
	v_exp_f32_e32 v6, v6
	s_nop 0
	v_add_f32_e32 v6, 1.0, v6
	v_div_scale_f32 v7, s[0:1], v6, v6, v3
	s_nop 0
	v_rcp_f32_e32 v7, v6
	s_nop 0
	v_mul_f32_e32 v3, v3, v7
	v_mul_f32_e32 v3, v5, v3
	v_cvt_pk_bf16_f32 v3, v3, s0
	ds_write_b16 v1, v3 offset:7264
	ds_read_u16 v3, v1 offset:7536
	s_waitcnt lgkmcnt(0)
	v_lshlrev_b32_e32 v3, 16, v3
	v_mul_f32_e32 v4, 0xbfb8aa3b, v3
	v_exp_f32_e32 v4, v4
	s_nop 0
	v_add_f32_e32 v4, 1.0, v4
	v_div_scale_f32 v5, s[0:1], v4, v4, v3
	s_nop 0
	v_rcp_f32_e32 v5, v4
	s_nop 0
	v_mul_f32_e32 v3, v3, v5
	v_mul_f32_e32 v2, v2, v3
	v_cvt_pk_bf16_f32 v2, v2, s0
	ds_write_b16 v1, v2 offset:7536
	s_waitcnt lgkmcnt(0)
	ds_read_b128 v[2:5], v92
	v_lshl_add_u64 v[6:7], v[90:91], 0, s[24:25]
	v_lshl_add_u64 v[8:9], v[6:7], 0, v[66:67]
	s_waitcnt lgkmcnt(0)
	global_store_dwordx4 v[8:9], v[2:5], off
	ds_read_b128 v[2:5], v92 offset:1088
	v_lshl_add_u64 v[8:9], v[6:7], 0, v[68:69]
	s_waitcnt lgkmcnt(0)
	global_store_dwordx4 v[8:9], v[2:5], off
	ds_read_b128 v[2:5], v92 offset:2176
	v_lshl_add_u64 v[8:9], v[6:7], 0, v[70:71]
	s_waitcnt lgkmcnt(0)
	global_store_dwordx4 v[8:9], v[2:5], off
	ds_read_b128 v[2:5], v92 offset:3264
	v_lshl_add_u64 v[8:9], v[6:7], 0, v[72:73]
	s_waitcnt lgkmcnt(0)
	global_store_dwordx4 v[8:9], v[2:5], off
	ds_read_b128 v[2:5], v92 offset:4352
	v_lshl_add_u64 v[8:9], v[6:7], 0, v[74:75]
	s_waitcnt lgkmcnt(0)
	global_store_dwordx4 v[8:9], v[2:5], off
	ds_read_b128 v[2:5], v92 offset:5440
	v_lshl_add_u64 v[8:9], v[6:7], 0, v[76:77]
	s_waitcnt lgkmcnt(0)
	global_store_dwordx4 v[8:9], v[2:5], off
	ds_read_b128 v[2:5], v92 offset:6528
	v_lshl_add_u64 v[8:9], v[6:7], 0, v[78:79]
	v_lshl_add_u64 v[6:7], v[6:7], 0, v[80:81]
	s_waitcnt lgkmcnt(0)
	global_store_dwordx4 v[8:9], v[2:5], off
	ds_read_b128 v[2:5], v92 offset:7616
	s_waitcnt lgkmcnt(0)
	global_store_dwordx4 v[6:7], v[2:5], off
	s_waitcnt lgkmcnt(0)
	s_cbranch_scc1 .LBB0_1216
